# MFMA walk over all 32 MFMAs of a super-phase (m outer, 4 accumulators per m in a snake) instead of two 16-groups
# speedup vs baseline: 1.0005x; 1.0005x over previous
; #define PG8_STAGE(bufoff, gbase, voff) do { _Pragma("unroll") for (int _i = 0; _i < 2; ++_i) \
;         __builtin_amdgcn_global_load_lds((const unsigned*)((const char*)(gbase) + (voff)[_i]), (PG8_LAS unsigned*)(lds + (bufoff) + ldsw + _i * 8192), 16, 0, 0); } while (0)
; #define PG8_LDA(dst, b, h) do { _Pragma("unroll") for (int m = 0; m < 4; ++m) _Pragma("unroll") for (int k = 0; k < 2; ++k) dst[m][k] = *(const PG8_LAS bf16x8*)(lds + PG8_SA(b, h) + aoff + m * 2048 + k * 1024); } while (0)
; #define PG8_LDB(dst, b, h) do { _Pragma("unroll") for (int n = 0; n < 2; ++n) _Pragma("unroll") for (int k = 0; k < 2; ++k) dst[n][k] = *(const PG8_LAS bf16x8*)(lds + PG8_SB(b, h) + boff + n * 2048 + k * 1024); } while (0)
; #define PG8_MMA(ai, bj, At, Bt) do { __builtin_amdgcn_s_setprio(1); _Pragma("unroll") for (int m = 0; m < 4; ++m) _Pragma("unroll") for (int n = 0; n < 2; ++n) _Pragma("unroll") for (int k = 0; k < 2; ++k) \
;         acc[ai][bj][m][n] = __builtin_amdgcn_mfma_f32_16x16x32_bf16(Bt[n][k], At[m][k], acc[ai][bj][m][n], 0, 0, 0); __builtin_amdgcn_s_setprio(0); } while (0)
; #define PG8_WAIT_V(n) asm volatile("s_waitcnt vmcnt(" #n ")" ::: "memory")
; #define PG8_WAIT_L(n) asm volatile("s_waitcnt lgkmcnt(" #n ")" ::: "memory")
; template <class Epi, class Sched, bool ALIGN_EPI = false, bool SP2 = false>
; __device__ __forceinline__ void gemm_phase(PG8_LAS unsigned char* lds, const Gemm g, const Sched& S, const Epi& E) {
;     ...
;             const bool last = (t == nt - 2);
;             const char* a1 = cA + (size_t)(t + 1) * kstep;
;             const char* a2 = last ? nA : cA + (size_t)(t + 2) * kstep; const char* b2 = last ? nB : cB + (size_t)(t + 2) * kstep;
;             const char* a3 = a2 + kstep; const char* b3 = b2 + kstep;
;             if (last && has_next) S.a_ready(nxt);
;             if constexpr (SP2) {
;             PG8_LDB(B0, 0, 0); PG8_LDB(B1, 0, 1); PG8_SCHED; PG8_LDA(At, 0, 0); PG8_STAGE(PG8_SA(1, 1), a1 + hstep, voffA);
;             PG8_WAIT_V(8); PG8_WAIT_L(0); PG8_BAR; PG8_MMA(0, 0, At, B0); PG8_MMA(0, 1, At, B1); PG8_BAR; PG8_SCHED;
;             PG8_LDA(At, 0, 1); PG8_STAGE(PG8_SB(0, 0), b2, voffB); PG8_STAGE(PG8_SB(0, 1), b2 + hstep, voffB); PG8_STAGE(PG8_SA(0, 0), a2, voffA);
;             PG8_WAIT_V(8); PG8_WAIT_L(0); PG8_BAR; PG8_MMA(1, 0, At, B0); PG8_MMA(1, 1, At, B1); PG8_BAR; PG8_SCHED;
.LBB0_110:
	ds_read_b128 v[136:139], v161
	ds_read_b128 v[140:143], v161 offset:1024
	ds_read_b128 v[176:179], v161 offset:2048
	ds_read_b128 v[180:183], v161 offset:3072
	ds_read_b128 v[184:187], v162
	ds_read_b128 v[202:205], v162 offset:1024
	ds_read_b128 v[206:209], v162 offset:2048
	ds_read_b128 v[210:213], v162 offset:3072
	s_add_u32 s28, s52, 0xfff80080
	s_addc_u32 s29, s53, -1
	s_cmp_eq_u32 s74, 28
	s_cselect_b32 s49, s25, s29
	s_cselect_b32 s48, s34, s28
	s_cselect_b32 s29, s23, s73
	s_cselect_b32 s28, s35, s72
	v_lshl_add_u64 v[246:247], s[52:53], 0, v[128:129]
	s_add_i32 m0, s9, 0xc000
	ds_read_b128 v[214:217], v163
	ds_read_b128 v[218:221], v163 offset:1024
	ds_read_b128 v[222:225], v163 offset:2048
	ds_read_b128 v[226:229], v163 offset:3072
	ds_read_b128 v[230:233], v163 offset:4096
	ds_read_b128 v[234:237], v163 offset:5120
	ds_read_b128 v[238:241], v163 offset:6144
	ds_read_b128 v[242:245], v163 offset:7168
	global_load_lds_dwordx4 v[246:247], off
	v_lshl_add_u64 v[246:247], s[52:53], 0, v[130:131]
	s_add_i32 m0, s9, 0xe000
	s_nop 0
	global_load_lds_dwordx4 v[246:247], off
	s_waitcnt vmcnt(8)
	s_waitcnt lgkmcnt(0)
	s_barrier
	s_setprio 1
	s_waitcnt lgkmcnt(0)
	v_mfma_f32_16x16x32_bf16 v[124:127], v[136:139], v[214:217], v[124:127]
	v_mfma_f32_16x16x32_bf16 v[124:127], v[140:143], v[218:221], v[124:127]
	v_mfma_f32_16x16x32_bf16 v[120:123], v[180:183], v[218:221], v[120:123]
	v_mfma_f32_16x16x32_bf16 v[120:123], v[176:179], v[214:217], v[120:123]
	v_mfma_f32_16x16x32_bf16 v[116:119], v[184:187], v[214:217], v[116:119]
	v_mfma_f32_16x16x32_bf16 v[116:119], v[202:205], v[218:221], v[116:119]
	v_mfma_f32_16x16x32_bf16 v[112:115], v[210:213], v[218:221], v[112:115]
	v_mfma_f32_16x16x32_bf16 v[112:115], v[206:209], v[214:217], v[112:115]
	v_mfma_f32_16x16x32_bf16 v[92:95], v[206:209], v[222:225], v[92:95]
	v_mfma_f32_16x16x32_bf16 v[92:95], v[210:213], v[226:229], v[92:95]
	v_mfma_f32_16x16x32_bf16 v[100:103], v[202:205], v[226:229], v[100:103]
	v_mfma_f32_16x16x32_bf16 v[100:103], v[184:187], v[222:225], v[100:103]
	v_mfma_f32_16x16x32_bf16 v[104:107], v[176:179], v[222:225], v[104:107]
	v_mfma_f32_16x16x32_bf16 v[104:107], v[180:183], v[226:229], v[104:107]
	v_mfma_f32_16x16x32_bf16 v[108:111], v[140:143], v[226:229], v[108:111]
	v_mfma_f32_16x16x32_bf16 v[108:111], v[136:139], v[222:225], v[108:111]
	s_setprio 0
	s_setprio 1
	v_mfma_f32_16x16x32_bf16 v[96:99], v[136:139], v[230:233], v[96:99]
	v_mfma_f32_16x16x32_bf16 v[96:99], v[140:143], v[234:237], v[96:99]
	v_mfma_f32_16x16x32_bf16 v[88:91], v[180:183], v[234:237], v[88:91]
	v_mfma_f32_16x16x32_bf16 v[88:91], v[176:179], v[230:233], v[88:91]
	v_mfma_f32_16x16x32_bf16 v[84:87], v[184:187], v[230:233], v[84:87]
	v_mfma_f32_16x16x32_bf16 v[84:87], v[202:205], v[234:237], v[84:87]
	v_mfma_f32_16x16x32_bf16 v[76:79], v[210:213], v[234:237], v[76:79]
	v_mfma_f32_16x16x32_bf16 v[76:79], v[206:209], v[230:233], v[76:79]
	v_mfma_f32_16x16x32_bf16 v[64:67], v[206:209], v[238:241], v[64:67]
	v_mfma_f32_16x16x32_bf16 v[64:67], v[210:213], v[242:245], v[64:67]
	v_mfma_f32_16x16x32_bf16 v[68:71], v[202:205], v[242:245], v[68:71]
	v_mfma_f32_16x16x32_bf16 v[68:71], v[184:187], v[238:241], v[68:71]
	v_mfma_f32_16x16x32_bf16 v[72:75], v[176:179], v[238:241], v[72:75]
	v_mfma_f32_16x16x32_bf16 v[72:75], v[180:183], v[242:245], v[72:75]
	s_setprio 2
	s_barrier
	v_mfma_f32_16x16x32_bf16 v[80:83], v[140:143], v[242:245], v[80:83]
	v_mfma_f32_16x16x32_bf16 v[80:83], v[136:139], v[238:241], v[80:83]
	s_setprio 0
	s_add_i32 s75, s63, s45
	v_lshl_add_u64 v[246:247], s[28:29], 0, v[166:167]
	s_mov_b32 m0, s75
	ds_read_b128 v[214:217], v163 offset:16384
	ds_read_b128 v[218:221], v163 offset:17408
	ds_read_b128 v[222:225], v163 offset:18432
	ds_read_b128 v[226:229], v163 offset:19456
	ds_read_b128 v[230:233], v163 offset:20480
	ds_read_b128 v[234:237], v163 offset:21504
	ds_read_b128 v[238:241], v163 offset:22528
	ds_read_b128 v[242:245], v163 offset:23552
	global_load_lds_dwordx4 v[246:247], off
	s_add_i32 m0, s75, 0x2000
	s_add_u32 s76, s28, 0x80000
	v_lshl_add_u64 v[248:249], s[28:29], 0, v[170:171]
	s_addc_u32 s77, s29, 0
	s_add_i32 s75, s64, s45
	global_load_lds_dwordx4 v[248:249], off
	v_lshl_add_u64 v[250:251], s[76:77], 0, v[166:167]
	s_mov_b32 m0, s75
	v_lshl_add_u64 v[252:253], s[48:49], 0, v[168:169]
	global_load_lds_dwordx4 v[250:251], off
	v_lshl_add_u64 v[250:251], s[76:77], 0, v[170:171]
	s_add_i32 m0, s75, 0x2000
	s_nop 0
	global_load_lds_dwordx4 v[250:251], off
	v_lshl_add_u64 v[250:251], s[48:49], 0, v[164:165]
	s_mov_b32 m0, s9
	s_nop 0
	global_load_lds_dwordx4 v[250:251], off
	s_mov_b32 m0, s57
	s_nop 0
	global_load_lds_dwordx4 v[252:253], off
	s_waitcnt vmcnt(8)
	s_waitcnt lgkmcnt(0)
	s_barrier
; #define PG8_STAGE(bufoff, gbase, voff) do { _Pragma("unroll") for (int _i = 0; _i < 2; ++_i) \
;         __builtin_amdgcn_global_load_lds((const unsigned*)((const char*)(gbase) + (voff)[_i]), (PG8_LAS unsigned*)(lds + (bufoff) + ldsw + _i * 8192), 16, 0, 0); } while (0)
; #define PG8_LDA(dst, b, h) do { _Pragma("unroll") for (int m = 0; m < 4; ++m) _Pragma("unroll") for (int k = 0; k < 2; ++k) dst[m][k] = *(const PG8_LAS bf16x8*)(lds + PG8_SA(b, h) + aoff + m * 2048 + k * 1024); } while (0)
; #define PG8_LDB(dst, b, h) do { _Pragma("unroll") for (int n = 0; n < 2; ++n) _Pragma("unroll") for (int k = 0; k < 2; ++k) dst[n][k] = *(const PG8_LAS bf16x8*)(lds + PG8_SB(b, h) + boff + n * 2048 + k * 1024); } while (0)
; #define PG8_MMA(ai, bj, At, Bt) do { __builtin_amdgcn_s_setprio(1); _Pragma("unroll") for (int m = 0; m < 4; ++m) _Pragma("unroll") for (int n = 0; n < 2; ++n) _Pragma("unroll") for (int k = 0; k < 2; ++k) \
;         acc[ai][bj][m][n] = __builtin_amdgcn_mfma_f32_16x16x32_bf16(Bt[n][k], At[m][k], acc[ai][bj][m][n], 0, 0, 0); __builtin_amdgcn_s_setprio(0); } while (0)
; #define PG8_WAIT_V(n) asm volatile("s_waitcnt vmcnt(" #n ")" ::: "memory")
; #define PG8_WAIT_L(n) asm volatile("s_waitcnt lgkmcnt(" #n ")" ::: "memory")
; #define PG8_BAR __builtin_amdgcn_s_barrier()
; #define PG8_SCHED __builtin_amdgcn_sched_barrier(0)
; template <class Epi, class Sched, bool ALIGN_EPI = false, bool SP2 = false>
; __device__ __forceinline__ void gemm_phase(PG8_LAS unsigned char* lds, const Gemm g, const Sched& S, const Epi& E) {
;     ...
;             PG8_WAIT_V(8); PG8_WAIT_L(0); PG8_BAR; PG8_MMA(1, 0, At, B0); PG8_MMA(1, 1, At, B1); PG8_BAR; PG8_SCHED;
;             PG8_LDB(B0, 1, 0); PG8_LDB(B1, 1, 1); PG8_SCHED; PG8_LDA(At, 1, 0); PG8_STAGE(PG8_SA(0, 1), a2 + hstep, voffA);
;             PG8_WAIT_V(8); PG8_WAIT_L(0); PG8_BAR; PG8_MMA(0, 0, At, B0); PG8_MMA(0, 1, At, B1); PG8_BAR; PG8_SCHED;
	s_setprio 1
	s_waitcnt lgkmcnt(0)
	v_mfma_f32_16x16x32_bf16 v[60:63], v[136:139], v[214:217], v[60:63]
	v_mfma_f32_16x16x32_bf16 v[60:63], v[140:143], v[218:221], v[60:63]
	v_mfma_f32_16x16x32_bf16 v[56:59], v[180:183], v[218:221], v[56:59]
	v_mfma_f32_16x16x32_bf16 v[56:59], v[176:179], v[214:217], v[56:59]
	v_mfma_f32_16x16x32_bf16 v[52:55], v[184:187], v[214:217], v[52:55]
	v_mfma_f32_16x16x32_bf16 v[52:55], v[202:205], v[218:221], v[52:55]
	v_mfma_f32_16x16x32_bf16 v[44:47], v[210:213], v[218:221], v[44:47]
	v_mfma_f32_16x16x32_bf16 v[44:47], v[206:209], v[214:217], v[44:47]
	v_mfma_f32_16x16x32_bf16 v[28:31], v[206:209], v[222:225], v[28:31]
	v_mfma_f32_16x16x32_bf16 v[28:31], v[210:213], v[226:229], v[28:31]
	v_mfma_f32_16x16x32_bf16 v[36:39], v[202:205], v[226:229], v[36:39]
	v_mfma_f32_16x16x32_bf16 v[36:39], v[184:187], v[222:225], v[36:39]
	v_mfma_f32_16x16x32_bf16 v[40:43], v[176:179], v[222:225], v[40:43]
	v_mfma_f32_16x16x32_bf16 v[40:43], v[180:183], v[226:229], v[40:43]
	v_mfma_f32_16x16x32_bf16 v[48:51], v[140:143], v[226:229], v[48:51]
	v_mfma_f32_16x16x32_bf16 v[48:51], v[136:139], v[222:225], v[48:51]
	s_setprio 0
	s_setprio 1
	v_mfma_f32_16x16x32_bf16 v[32:35], v[136:139], v[230:233], v[32:35]
	v_mfma_f32_16x16x32_bf16 v[32:35], v[140:143], v[234:237], v[32:35]
	v_mfma_f32_16x16x32_bf16 v[24:27], v[180:183], v[234:237], v[24:27]
	v_mfma_f32_16x16x32_bf16 v[24:27], v[176:179], v[230:233], v[24:27]
	v_mfma_f32_16x16x32_bf16 v[20:23], v[184:187], v[230:233], v[20:23]
	v_mfma_f32_16x16x32_bf16 v[20:23], v[202:205], v[234:237], v[20:23]
	v_mfma_f32_16x16x32_bf16 v[16:19], v[210:213], v[234:237], v[16:19]
	v_mfma_f32_16x16x32_bf16 v[16:19], v[206:209], v[230:233], v[16:19]
	v_mfma_f32_16x16x32_bf16 v[0:3], v[206:209], v[238:241], v[0:3]
	v_mfma_f32_16x16x32_bf16 v[0:3], v[210:213], v[242:245], v[0:3]
	v_mfma_f32_16x16x32_bf16 v[4:7], v[202:205], v[242:245], v[4:7]
	v_mfma_f32_16x16x32_bf16 v[4:7], v[184:187], v[238:241], v[4:7]
	v_mfma_f32_16x16x32_bf16 v[8:11], v[176:179], v[238:241], v[8:11]
	v_mfma_f32_16x16x32_bf16 v[8:11], v[180:183], v[242:245], v[8:11]
	s_setprio 2
	s_barrier
	v_mfma_f32_16x16x32_bf16 v[12:15], v[140:143], v[242:245], v[12:15]
	v_mfma_f32_16x16x32_bf16 v[12:15], v[136:139], v[238:241], v[12:15]
	s_setprio 0
	s_add_i32 s75, 0, 0x18000
	v_add_u32_e32 v144, s75, v151
	s_add_i32 s76, 0, 0x1c000
	ds_read_b128 v[136:139], v144
	ds_read_b128 v[140:143], v144 offset:1024
	ds_read_b128 v[176:179], v144 offset:2048
	ds_read_b128 v[180:183], v144 offset:3072
	v_add_u32_e32 v144, s76, v151
	ds_read_b128 v[184:187], v144
	ds_read_b128 v[202:205], v144 offset:1024
	ds_read_b128 v[206:209], v144 offset:2048
	ds_read_b128 v[210:213], v144 offset:3072
	s_add_u32 s48, s48, 0x80000
	s_addc_u32 s49, s49, 0
	s_mov_b32 m0, s58
	v_lshl_add_u64 v[200:201], s[48:49], 0, v[164:165]
	ds_read_b128 v[214:217], v163 offset:32768
	ds_read_b128 v[218:221], v163 offset:33792
	ds_read_b128 v[222:225], v163 offset:34816
	ds_read_b128 v[226:229], v163 offset:35840
	ds_read_b128 v[230:233], v163 offset:36864
	ds_read_b128 v[234:237], v163 offset:37888
	ds_read_b128 v[238:241], v163 offset:38912
	ds_read_b128 v[242:245], v163 offset:39936
	global_load_lds_dwordx4 v[200:201], off
	v_lshl_add_u64 v[200:201], s[48:49], 0, v[168:169]
	s_mov_b32 m0, s59
	s_nop 0
	global_load_lds_dwordx4 v[200:201], off
	s_waitcnt vmcnt(8)
	s_waitcnt lgkmcnt(0)
	s_barrier
	s_setprio 1
	s_waitcnt lgkmcnt(0)
	v_mfma_f32_16x16x32_bf16 v[124:127], v[136:139], v[214:217], v[124:127]
	v_mfma_f32_16x16x32_bf16 v[124:127], v[140:143], v[218:221], v[124:127]
	v_mfma_f32_16x16x32_bf16 v[120:123], v[180:183], v[218:221], v[120:123]
	v_mfma_f32_16x16x32_bf16 v[120:123], v[176:179], v[214:217], v[120:123]
	v_mfma_f32_16x16x32_bf16 v[116:119], v[184:187], v[214:217], v[116:119]
	v_mfma_f32_16x16x32_bf16 v[116:119], v[202:205], v[218:221], v[116:119]
	v_mfma_f32_16x16x32_bf16 v[112:115], v[210:213], v[218:221], v[112:115]
	v_mfma_f32_16x16x32_bf16 v[112:115], v[206:209], v[214:217], v[112:115]
	v_mfma_f32_16x16x32_bf16 v[92:95], v[206:209], v[222:225], v[92:95]
	v_mfma_f32_16x16x32_bf16 v[92:95], v[210:213], v[226:229], v[92:95]
	v_mfma_f32_16x16x32_bf16 v[100:103], v[202:205], v[226:229], v[100:103]
	v_mfma_f32_16x16x32_bf16 v[100:103], v[184:187], v[222:225], v[100:103]
	v_mfma_f32_16x16x32_bf16 v[104:107], v[176:179], v[222:225], v[104:107]
	v_mfma_f32_16x16x32_bf16 v[104:107], v[180:183], v[226:229], v[104:107]
	v_mfma_f32_16x16x32_bf16 v[108:111], v[140:143], v[226:229], v[108:111]
	v_mfma_f32_16x16x32_bf16 v[108:111], v[136:139], v[222:225], v[108:111]
	s_setprio 0
	s_setprio 1
	v_mfma_f32_16x16x32_bf16 v[96:99], v[136:139], v[230:233], v[96:99]
	v_mfma_f32_16x16x32_bf16 v[96:99], v[140:143], v[234:237], v[96:99]
	v_mfma_f32_16x16x32_bf16 v[88:91], v[180:183], v[234:237], v[88:91]
	v_mfma_f32_16x16x32_bf16 v[88:91], v[176:179], v[230:233], v[88:91]
	v_mfma_f32_16x16x32_bf16 v[84:87], v[184:187], v[230:233], v[84:87]
	v_mfma_f32_16x16x32_bf16 v[84:87], v[202:205], v[234:237], v[84:87]
	v_mfma_f32_16x16x32_bf16 v[76:79], v[210:213], v[234:237], v[76:79]
	v_mfma_f32_16x16x32_bf16 v[76:79], v[206:209], v[230:233], v[76:79]
	v_mfma_f32_16x16x32_bf16 v[64:67], v[206:209], v[238:241], v[64:67]
	v_mfma_f32_16x16x32_bf16 v[64:67], v[210:213], v[242:245], v[64:67]
	v_mfma_f32_16x16x32_bf16 v[68:71], v[202:205], v[242:245], v[68:71]
	v_mfma_f32_16x16x32_bf16 v[68:71], v[184:187], v[238:241], v[68:71]
	v_mfma_f32_16x16x32_bf16 v[72:75], v[176:179], v[238:241], v[72:75]
	v_mfma_f32_16x16x32_bf16 v[72:75], v[180:183], v[242:245], v[72:75]
	s_setprio 2
	s_barrier
; #define PG8_STAGE(bufoff, gbase, voff) do { _Pragma("unroll") for (int _i = 0; _i < 2; ++_i) \
;         __builtin_amdgcn_global_load_lds((const unsigned*)((const char*)(gbase) + (voff)[_i]), (PG8_LAS unsigned*)(lds + (bufoff) + ldsw + _i * 8192), 16, 0, 0); } while (0)
; #define PG8_LDA(dst, b, h) do { _Pragma("unroll") for (int m = 0; m < 4; ++m) _Pragma("unroll") for (int k = 0; k < 2; ++k) dst[m][k] = *(const PG8_LAS bf16x8*)(lds + PG8_SA(b, h) + aoff + m * 2048 + k * 1024); } while (0)
; #define PG8_MMA(ai, bj, At, Bt) do { __builtin_amdgcn_s_setprio(1); _Pragma("unroll") for (int m = 0; m < 4; ++m) _Pragma("unroll") for (int n = 0; n < 2; ++n) _Pragma("unroll") for (int k = 0; k < 2; ++k) \
;         acc[ai][bj][m][n] = __builtin_amdgcn_mfma_f32_16x16x32_bf16(Bt[n][k], At[m][k], acc[ai][bj][m][n], 0, 0, 0); __builtin_amdgcn_s_setprio(0); } while (0)
; #define PG8_WAIT_V(n) asm volatile("s_waitcnt vmcnt(" #n ")" ::: "memory")
; #define PG8_WAIT_L(n) asm volatile("s_waitcnt lgkmcnt(" #n ")" ::: "memory")
; #define PG8_BAR __builtin_amdgcn_s_barrier()
; #define PG8_SCHED __builtin_amdgcn_sched_barrier(0)
; template <class Epi, class Sched, bool ALIGN_EPI = false, bool SP2 = false>
; __device__ __forceinline__ void gemm_phase(PG8_LAS unsigned char* lds, const Gemm g, const Sched& S, const Epi& E) {
;     ...
;             PG8_WAIT_V(8); PG8_WAIT_L(0); PG8_BAR; PG8_MMA(0, 0, At, B0); PG8_MMA(0, 1, At, B1); PG8_BAR; PG8_SCHED;
;             PG8_LDA(At, 1, 1); PG8_STAGE(PG8_SB(1, 0), b3, voffB); PG8_STAGE(PG8_SB(1, 1), b3 + hstep, voffB); PG8_STAGE(PG8_SA(1, 0), a3, voffA);
;             PG8_WAIT_V(8); PG8_WAIT_L(0); PG8_BAR; PG8_MMA(1, 0, At, B0); PG8_MMA(1, 1, At, B1); PG8_BAR; PG8_SCHED;
;     ...
;         if constexpr (ALIGN_EPI) { if (wr == 0) PG8_BAR; }
	v_mfma_f32_16x16x32_bf16 v[80:83], v[140:143], v[242:245], v[80:83]
	v_mfma_f32_16x16x32_bf16 v[80:83], v[136:139], v[238:241], v[80:83]
	s_setprio 0
	s_add_i32 s48, s75, s45
	v_lshl_add_u64 v[200:201], v[246:247], 0, s[18:19]
	s_mov_b32 m0, s48
	ds_read_b128 v[214:217], v163 offset:49152
	ds_read_b128 v[218:221], v163 offset:50176
	ds_read_b128 v[222:225], v163 offset:51200
	ds_read_b128 v[226:229], v163 offset:52224
	ds_read_b128 v[230:233], v163 offset:53248
	ds_read_b128 v[234:237], v163 offset:54272
	ds_read_b128 v[238:241], v163 offset:55296
	ds_read_b128 v[242:245], v163 offset:56320
	global_load_lds_dwordx4 v[200:201], off
	s_add_i32 m0, s48, 0x2000
	s_add_u32 s28, s28, 0x80080
	v_lshl_add_u64 v[200:201], v[248:249], 0, s[18:19]
	s_addc_u32 s29, s29, 0
	s_add_i32 s48, s76, s45
	global_load_lds_dwordx4 v[200:201], off
	v_lshl_add_u64 v[200:201], s[28:29], 0, v[166:167]
	s_mov_b32 m0, s48
	s_nop 0
	global_load_lds_dwordx4 v[200:201], off
	v_lshl_add_u64 v[200:201], s[28:29], 0, v[170:171]
	s_add_i32 m0, s48, 0x2000
	s_nop 0
	global_load_lds_dwordx4 v[200:201], off
	v_lshl_add_u64 v[200:201], v[250:251], 0, s[18:19]
	s_mov_b32 m0, s61
	s_nop 0
	global_load_lds_dwordx4 v[200:201], off
	v_lshl_add_u64 v[200:201], v[252:253], 0, s[18:19]
	s_mov_b32 m0, s62
	s_nop 0
	global_load_lds_dwordx4 v[200:201], off
	s_waitcnt vmcnt(8)
	s_waitcnt lgkmcnt(0)
	s_barrier
	s_setprio 1
	s_waitcnt lgkmcnt(0)
	v_mfma_f32_16x16x32_bf16 v[60:63], v[136:139], v[214:217], v[60:63]
	v_mfma_f32_16x16x32_bf16 v[60:63], v[140:143], v[218:221], v[60:63]
	v_mfma_f32_16x16x32_bf16 v[56:59], v[180:183], v[218:221], v[56:59]
	v_mfma_f32_16x16x32_bf16 v[56:59], v[176:179], v[214:217], v[56:59]
	v_mfma_f32_16x16x32_bf16 v[52:55], v[184:187], v[214:217], v[52:55]
	v_mfma_f32_16x16x32_bf16 v[52:55], v[202:205], v[218:221], v[52:55]
	v_mfma_f32_16x16x32_bf16 v[44:47], v[210:213], v[218:221], v[44:47]
	v_mfma_f32_16x16x32_bf16 v[44:47], v[206:209], v[214:217], v[44:47]
	v_mfma_f32_16x16x32_bf16 v[28:31], v[206:209], v[222:225], v[28:31]
	v_mfma_f32_16x16x32_bf16 v[28:31], v[210:213], v[226:229], v[28:31]
	v_mfma_f32_16x16x32_bf16 v[36:39], v[202:205], v[226:229], v[36:39]
	v_mfma_f32_16x16x32_bf16 v[36:39], v[184:187], v[222:225], v[36:39]
	v_mfma_f32_16x16x32_bf16 v[40:43], v[176:179], v[222:225], v[40:43]
	v_mfma_f32_16x16x32_bf16 v[40:43], v[180:183], v[226:229], v[40:43]
	v_mfma_f32_16x16x32_bf16 v[48:51], v[140:143], v[226:229], v[48:51]
	v_mfma_f32_16x16x32_bf16 v[48:51], v[136:139], v[222:225], v[48:51]
	s_setprio 0
	s_setprio 1
	v_mfma_f32_16x16x32_bf16 v[32:35], v[136:139], v[230:233], v[32:35]
	v_mfma_f32_16x16x32_bf16 v[32:35], v[140:143], v[234:237], v[32:35]
	v_mfma_f32_16x16x32_bf16 v[24:27], v[180:183], v[234:237], v[24:27]
	v_mfma_f32_16x16x32_bf16 v[24:27], v[176:179], v[230:233], v[24:27]
	v_mfma_f32_16x16x32_bf16 v[20:23], v[184:187], v[230:233], v[20:23]
	v_mfma_f32_16x16x32_bf16 v[20:23], v[202:205], v[234:237], v[20:23]
	v_mfma_f32_16x16x32_bf16 v[16:19], v[210:213], v[234:237], v[16:19]
	v_mfma_f32_16x16x32_bf16 v[16:19], v[206:209], v[230:233], v[16:19]
	v_mfma_f32_16x16x32_bf16 v[0:3], v[206:209], v[238:241], v[0:3]
	v_mfma_f32_16x16x32_bf16 v[0:3], v[210:213], v[242:245], v[0:3]
	v_mfma_f32_16x16x32_bf16 v[4:7], v[202:205], v[242:245], v[4:7]
	v_mfma_f32_16x16x32_bf16 v[4:7], v[184:187], v[238:241], v[4:7]
	v_mfma_f32_16x16x32_bf16 v[8:11], v[176:179], v[238:241], v[8:11]
	v_mfma_f32_16x16x32_bf16 v[8:11], v[180:183], v[242:245], v[8:11]
	s_setprio 2
	s_barrier
	v_mfma_f32_16x16x32_bf16 v[12:15], v[140:143], v[242:245], v[12:15]
	v_mfma_f32_16x16x32_bf16 v[12:15], v[136:139], v[238:241], v[12:15]
	s_setprio 0
	s_add_i32 s74, s74, 2
	s_add_u32 s52, s52, 0x100
	s_addc_u32 s53, s53, 0
	s_add_u32 s72, s72, 0x100
	s_addc_u32 s73, s73, 0
	s_cmp_gt_u32 s74, 29
	s_cbranch_scc0 .LBB0_110
	s_and_b64 vcc, exec, s[20:21]
	s_cbranch_vccz .LBB0_113
	s_barrier

; #define PG8_STAGE(bufoff, gbase, voff) do { _Pragma("unroll") for (int _i = 0; _i < 2; ++_i) \
;         __builtin_amdgcn_global_load_lds((const unsigned*)((const char*)(gbase) + (voff)[_i]), (PG8_LAS unsigned*)(lds + (bufoff) + ldsw + _i * 8192), 16, 0, 0); } while (0)
; #define PG8_LDA(dst, b, h) do { _Pragma("unroll") for (int m = 0; m < 4; ++m) _Pragma("unroll") for (int k = 0; k < 2; ++k) dst[m][k] = *(const PG8_LAS bf16x8*)(lds + PG8_SA(b, h) + aoff + m * 2048 + k * 1024); } while (0)
; #define PG8_LDB(dst, b, h) do { _Pragma("unroll") for (int n = 0; n < 2; ++n) _Pragma("unroll") for (int k = 0; k < 2; ++k) dst[n][k] = *(const PG8_LAS bf16x8*)(lds + PG8_SB(b, h) + boff + n * 2048 + k * 1024); } while (0)
; #define PG8_MMA(ai, bj, At, Bt) do { __builtin_amdgcn_s_setprio(1); _Pragma("unroll") for (int m = 0; m < 4; ++m) _Pragma("unroll") for (int n = 0; n < 2; ++n) _Pragma("unroll") for (int k = 0; k < 2; ++k) \
;         acc[ai][bj][m][n] = __builtin_amdgcn_mfma_f32_16x16x32_bf16(Bt[n][k], At[m][k], acc[ai][bj][m][n], 0, 0, 0); __builtin_amdgcn_s_setprio(0); } while (0)
; #define PG8_WAIT_V(n) asm volatile("s_waitcnt vmcnt(" #n ")" ::: "memory")
; #define PG8_WAIT_L(n) asm volatile("s_waitcnt lgkmcnt(" #n ")" ::: "memory")
; template <class Epi, class Sched, bool ALIGN_EPI = false, bool SP2 = false>
; __device__ __forceinline__ void gemm_phase(PG8_LAS unsigned char* lds, const Gemm g, const Sched& S, const Epi& E) {
;     ...
;             const bool last = (t == nt - 2);
;             const char* a1 = cA + (size_t)(t + 1) * kstep;
;             const char* a2 = last ? nA : cA + (size_t)(t + 2) * kstep; const char* b2 = last ? nB : cB + (size_t)(t + 2) * kstep;
;             const char* a3 = a2 + kstep; const char* b3 = b2 + kstep;
;             if (last && has_next) S.a_ready(nxt);
;             if constexpr (SP2) {
;             PG8_LDB(B0, 0, 0); PG8_LDB(B1, 0, 1); PG8_SCHED; PG8_LDA(At, 0, 0); PG8_STAGE(PG8_SA(1, 1), a1 + hstep, voffA);
;             PG8_WAIT_V(8); PG8_WAIT_L(0); PG8_BAR; PG8_MMA(0, 0, At, B0); PG8_MMA(0, 1, At, B1); PG8_BAR; PG8_SCHED;
;             PG8_LDA(At, 0, 1); PG8_STAGE(PG8_SB(0, 0), b2, voffB); PG8_STAGE(PG8_SB(0, 1), b2 + hstep, voffB); PG8_STAGE(PG8_SA(0, 0), a2, voffA);
;             PG8_WAIT_V(8); PG8_WAIT_L(0); PG8_BAR; PG8_MMA(1, 0, At, B0); PG8_MMA(1, 1, At, B1); PG8_BAR; PG8_SCHED;
.LBB0_177:
	ds_read_b128 v[80:83], v171
	ds_read_b128 v[84:87], v171 offset:1024
	ds_read_b128 v[92:95], v171 offset:2048
	ds_read_b128 v[100:103], v171 offset:3072
	ds_read_b128 v[144:147], v206
	ds_read_b128 v[148:151], v206 offset:1024
	ds_read_b128 v[152:155], v206 offset:2048
	ds_read_b128 v[156:159], v206 offset:3072
	s_add_u32 s28, s72, 0xffea0080
	s_addc_u32 s29, s73, -1
	s_cmpk_eq_i32 s76, 0x54
	s_cselect_b32 s49, s69, s29
	s_cselect_b32 s48, s68, s28
	s_cselect_b32 s29, s71, s35
	s_cselect_b32 s28, s70, s34
	v_lshl_add_u64 v[234:235], s[72:73], 0, v[174:175]
	s_add_i32 m0, s40, 0xc000
	ds_read_b128 v[180:183], v207
	ds_read_b128 v[184:187], v207 offset:1024
	ds_read_b128 v[210:213], v207 offset:2048
	ds_read_b128 v[214:217], v207 offset:3072
	ds_read_b128 v[218:221], v207 offset:4096
	ds_read_b128 v[222:225], v207 offset:5120
	ds_read_b128 v[226:229], v207 offset:6144
	ds_read_b128 v[230:233], v207 offset:7168
	global_load_lds_dwordx4 v[234:235], off
	v_lshl_add_u64 v[234:235], s[72:73], 0, v[176:177]
	s_add_i32 m0, s40, 0xe000
	s_nop 0
	global_load_lds_dwordx4 v[234:235], off
	s_waitcnt vmcnt(8)
	s_waitcnt lgkmcnt(0)
	s_barrier
	s_setprio 1
	s_waitcnt lgkmcnt(0)
	v_mfma_f32_16x16x32_bf16 v[140:143], v[80:83], v[180:183], v[140:143]
	v_mfma_f32_16x16x32_bf16 v[140:143], v[84:87], v[184:187], v[140:143]
	v_mfma_f32_16x16x32_bf16 v[136:139], v[100:103], v[184:187], v[136:139]
	v_mfma_f32_16x16x32_bf16 v[136:139], v[92:95], v[180:183], v[136:139]
	v_mfma_f32_16x16x32_bf16 v[132:135], v[144:147], v[180:183], v[132:135]
	v_mfma_f32_16x16x32_bf16 v[132:135], v[148:151], v[184:187], v[132:135]
	v_mfma_f32_16x16x32_bf16 v[128:131], v[156:159], v[184:187], v[128:131]
	v_mfma_f32_16x16x32_bf16 v[128:131], v[152:155], v[180:183], v[128:131]
	v_mfma_f32_16x16x32_bf16 v[112:115], v[152:155], v[210:213], v[112:115]
	v_mfma_f32_16x16x32_bf16 v[112:115], v[156:159], v[214:217], v[112:115]
	v_mfma_f32_16x16x32_bf16 v[116:119], v[148:151], v[214:217], v[116:119]
	v_mfma_f32_16x16x32_bf16 v[116:119], v[144:147], v[210:213], v[116:119]
	v_mfma_f32_16x16x32_bf16 v[120:123], v[92:95], v[210:213], v[120:123]
	v_mfma_f32_16x16x32_bf16 v[120:123], v[100:103], v[214:217], v[120:123]
	v_mfma_f32_16x16x32_bf16 v[124:127], v[84:87], v[214:217], v[124:127]
	v_mfma_f32_16x16x32_bf16 v[124:127], v[80:83], v[210:213], v[124:127]
	s_setprio 0
	s_setprio 1
	v_mfma_f32_16x16x32_bf16 v[108:111], v[80:83], v[218:221], v[108:111]
	v_mfma_f32_16x16x32_bf16 v[108:111], v[84:87], v[222:225], v[108:111]
	v_mfma_f32_16x16x32_bf16 v[104:107], v[100:103], v[222:225], v[104:107]
	v_mfma_f32_16x16x32_bf16 v[104:107], v[92:95], v[218:221], v[104:107]
	v_mfma_f32_16x16x32_bf16 v[96:99], v[144:147], v[218:221], v[96:99]
	v_mfma_f32_16x16x32_bf16 v[96:99], v[148:151], v[222:225], v[96:99]
	v_mfma_f32_16x16x32_bf16 v[88:91], v[156:159], v[222:225], v[88:91]
	v_mfma_f32_16x16x32_bf16 v[88:91], v[152:155], v[218:221], v[88:91]
	v_mfma_f32_16x16x32_bf16 v[64:67], v[152:155], v[226:229], v[64:67]
	v_mfma_f32_16x16x32_bf16 v[64:67], v[156:159], v[230:233], v[64:67]
	v_mfma_f32_16x16x32_bf16 v[68:71], v[148:151], v[230:233], v[68:71]
	v_mfma_f32_16x16x32_bf16 v[68:71], v[144:147], v[226:229], v[68:71]
	v_mfma_f32_16x16x32_bf16 v[72:75], v[92:95], v[226:229], v[72:75]
	v_mfma_f32_16x16x32_bf16 v[72:75], v[100:103], v[230:233], v[72:75]
	s_setprio 2
	s_barrier
	v_mfma_f32_16x16x32_bf16 v[76:79], v[84:87], v[230:233], v[76:79]
	v_mfma_f32_16x16x32_bf16 v[76:79], v[80:83], v[226:229], v[76:79]
	s_setprio 0
	s_add_i32 s77, s61, s13
	v_lshl_add_u64 v[234:235], s[28:29], 0, v[160:161]
	s_mov_b32 m0, s77
	ds_read_b128 v[180:183], v207 offset:16384
	ds_read_b128 v[184:187], v207 offset:17408
	ds_read_b128 v[210:213], v207 offset:18432
	ds_read_b128 v[214:217], v207 offset:19456
	ds_read_b128 v[218:221], v207 offset:20480
	ds_read_b128 v[222:225], v207 offset:21504
	ds_read_b128 v[226:229], v207 offset:22528
	ds_read_b128 v[230:233], v207 offset:23552
	global_load_lds_dwordx4 v[234:235], off
	s_add_i32 m0, s77, 0x2000
	s_add_u32 s78, s28, 0x160000
	v_lshl_add_u64 v[236:237], s[28:29], 0, v[162:163]
	s_addc_u32 s79, s29, 0
	s_add_i32 s77, s62, s13
	global_load_lds_dwordx4 v[236:237], off
	v_lshl_add_u64 v[238:239], s[78:79], 0, v[160:161]
	s_mov_b32 m0, s77
	v_lshl_add_u64 v[240:241], s[48:49], 0, v[162:163]
	global_load_lds_dwordx4 v[238:239], off
	v_lshl_add_u64 v[238:239], s[78:79], 0, v[162:163]
	s_add_i32 m0, s77, 0x2000
	s_nop 0
	global_load_lds_dwordx4 v[238:239], off
	v_lshl_add_u64 v[238:239], s[48:49], 0, v[160:161]
	s_mov_b32 m0, s40
	s_nop 0
	global_load_lds_dwordx4 v[238:239], off
	s_mov_b32 m0, s41
	s_nop 0
	global_load_lds_dwordx4 v[240:241], off
	s_waitcnt vmcnt(8)
	s_waitcnt lgkmcnt(0)
	s_barrier
; #define PG8_STAGE(bufoff, gbase, voff) do { _Pragma("unroll") for (int _i = 0; _i < 2; ++_i) \
;         __builtin_amdgcn_global_load_lds((const unsigned*)((const char*)(gbase) + (voff)[_i]), (PG8_LAS unsigned*)(lds + (bufoff) + ldsw + _i * 8192), 16, 0, 0); } while (0)
; #define PG8_LDA(dst, b, h) do { _Pragma("unroll") for (int m = 0; m < 4; ++m) _Pragma("unroll") for (int k = 0; k < 2; ++k) dst[m][k] = *(const PG8_LAS bf16x8*)(lds + PG8_SA(b, h) + aoff + m * 2048 + k * 1024); } while (0)
; #define PG8_LDB(dst, b, h) do { _Pragma("unroll") for (int n = 0; n < 2; ++n) _Pragma("unroll") for (int k = 0; k < 2; ++k) dst[n][k] = *(const PG8_LAS bf16x8*)(lds + PG8_SB(b, h) + boff + n * 2048 + k * 1024); } while (0)
; #define PG8_MMA(ai, bj, At, Bt) do { __builtin_amdgcn_s_setprio(1); _Pragma("unroll") for (int m = 0; m < 4; ++m) _Pragma("unroll") for (int n = 0; n < 2; ++n) _Pragma("unroll") for (int k = 0; k < 2; ++k) \
;         acc[ai][bj][m][n] = __builtin_amdgcn_mfma_f32_16x16x32_bf16(Bt[n][k], At[m][k], acc[ai][bj][m][n], 0, 0, 0); __builtin_amdgcn_s_setprio(0); } while (0)
; #define PG8_WAIT_V(n) asm volatile("s_waitcnt vmcnt(" #n ")" ::: "memory")
; #define PG8_WAIT_L(n) asm volatile("s_waitcnt lgkmcnt(" #n ")" ::: "memory")
; #define PG8_BAR __builtin_amdgcn_s_barrier()
; #define PG8_SCHED __builtin_amdgcn_sched_barrier(0)
; template <class Epi, class Sched, bool ALIGN_EPI = false, bool SP2 = false>
; __device__ __forceinline__ void gemm_phase(PG8_LAS unsigned char* lds, const Gemm g, const Sched& S, const Epi& E) {
;     ...
;             PG8_WAIT_V(8); PG8_WAIT_L(0); PG8_BAR; PG8_MMA(1, 0, At, B0); PG8_MMA(1, 1, At, B1); PG8_BAR; PG8_SCHED;
;             PG8_LDB(B0, 1, 0); PG8_LDB(B1, 1, 1); PG8_SCHED; PG8_LDA(At, 1, 0); PG8_STAGE(PG8_SA(0, 1), a2 + hstep, voffA);
;             PG8_WAIT_V(8); PG8_WAIT_L(0); PG8_BAR; PG8_MMA(0, 0, At, B0); PG8_MMA(0, 1, At, B1); PG8_BAR; PG8_SCHED;
	s_setprio 1
	s_waitcnt lgkmcnt(0)
	v_mfma_f32_16x16x32_bf16 v[60:63], v[80:83], v[180:183], v[60:63]
	v_mfma_f32_16x16x32_bf16 v[60:63], v[84:87], v[184:187], v[60:63]
	v_mfma_f32_16x16x32_bf16 v[56:59], v[100:103], v[184:187], v[56:59]
	v_mfma_f32_16x16x32_bf16 v[56:59], v[92:95], v[180:183], v[56:59]
	v_mfma_f32_16x16x32_bf16 v[52:55], v[144:147], v[180:183], v[52:55]
	v_mfma_f32_16x16x32_bf16 v[52:55], v[148:151], v[184:187], v[52:55]
	v_mfma_f32_16x16x32_bf16 v[48:51], v[156:159], v[184:187], v[48:51]
	v_mfma_f32_16x16x32_bf16 v[48:51], v[152:155], v[180:183], v[48:51]
	v_mfma_f32_16x16x32_bf16 v[32:35], v[152:155], v[210:213], v[32:35]
	v_mfma_f32_16x16x32_bf16 v[32:35], v[156:159], v[214:217], v[32:35]
	v_mfma_f32_16x16x32_bf16 v[36:39], v[148:151], v[214:217], v[36:39]
	v_mfma_f32_16x16x32_bf16 v[36:39], v[144:147], v[210:213], v[36:39]
	v_mfma_f32_16x16x32_bf16 v[40:43], v[92:95], v[210:213], v[40:43]
	v_mfma_f32_16x16x32_bf16 v[40:43], v[100:103], v[214:217], v[40:43]
	v_mfma_f32_16x16x32_bf16 v[44:47], v[84:87], v[214:217], v[44:47]
	v_mfma_f32_16x16x32_bf16 v[44:47], v[80:83], v[210:213], v[44:47]
	s_setprio 0
	s_setprio 1
	v_mfma_f32_16x16x32_bf16 v[28:31], v[80:83], v[218:221], v[28:31]
	v_mfma_f32_16x16x32_bf16 v[28:31], v[84:87], v[222:225], v[28:31]
	v_mfma_f32_16x16x32_bf16 v[24:27], v[100:103], v[222:225], v[24:27]
	v_mfma_f32_16x16x32_bf16 v[24:27], v[92:95], v[218:221], v[24:27]
	v_mfma_f32_16x16x32_bf16 v[20:23], v[144:147], v[218:221], v[20:23]
	v_mfma_f32_16x16x32_bf16 v[20:23], v[148:151], v[222:225], v[20:23]
	v_mfma_f32_16x16x32_bf16 v[16:19], v[156:159], v[222:225], v[16:19]
	v_mfma_f32_16x16x32_bf16 v[16:19], v[152:155], v[218:221], v[16:19]
	v_mfma_f32_16x16x32_bf16 v[0:3], v[152:155], v[226:229], v[0:3]
	v_mfma_f32_16x16x32_bf16 v[0:3], v[156:159], v[230:233], v[0:3]
	v_mfma_f32_16x16x32_bf16 v[4:7], v[148:151], v[230:233], v[4:7]
	v_mfma_f32_16x16x32_bf16 v[4:7], v[144:147], v[226:229], v[4:7]
	v_mfma_f32_16x16x32_bf16 v[8:11], v[92:95], v[226:229], v[8:11]
	v_mfma_f32_16x16x32_bf16 v[8:11], v[100:103], v[230:233], v[8:11]
	s_setprio 2
	s_barrier
	v_mfma_f32_16x16x32_bf16 v[12:15], v[84:87], v[230:233], v[12:15]
	v_mfma_f32_16x16x32_bf16 v[12:15], v[80:83], v[226:229], v[12:15]
	s_setprio 0
	s_add_i32 s77, 0, 0x18000
	s_add_i32 s78, 0, 0x1c000
	v_add_u32_e32 v100, s77, v167
	v_add_u32_e32 v156, s78, v167
	ds_read_b128 v[80:83], v100
	ds_read_b128 v[84:87], v100 offset:1024
	ds_read_b128 v[92:95], v100 offset:2048
	ds_read_b128 v[100:103], v100 offset:3072
	ds_read_b128 v[144:147], v156
	ds_read_b128 v[148:151], v156 offset:1024
	ds_read_b128 v[152:155], v156 offset:2048
	ds_read_b128 v[156:159], v156 offset:3072
	s_add_u32 s48, s48, 0x160000
	s_addc_u32 s49, s49, 0
	s_mov_b32 m0, s44
	v_lshl_add_u64 v[242:243], s[48:49], 0, v[160:161]
	ds_read_b128 v[180:183], v207 offset:32768
	ds_read_b128 v[184:187], v207 offset:33792
	ds_read_b128 v[210:213], v207 offset:34816
	ds_read_b128 v[214:217], v207 offset:35840
	ds_read_b128 v[218:221], v207 offset:36864
	ds_read_b128 v[222:225], v207 offset:37888
	ds_read_b128 v[226:229], v207 offset:38912
	ds_read_b128 v[230:233], v207 offset:39936
	global_load_lds_dwordx4 v[242:243], off
	v_lshl_add_u64 v[242:243], s[48:49], 0, v[162:163]
	s_mov_b32 m0, s45
	s_nop 0
	global_load_lds_dwordx4 v[242:243], off
	s_waitcnt vmcnt(8)
	s_waitcnt lgkmcnt(0)
	s_barrier
	s_setprio 1
	s_waitcnt lgkmcnt(0)
	v_mfma_f32_16x16x32_bf16 v[140:143], v[80:83], v[180:183], v[140:143]
	v_mfma_f32_16x16x32_bf16 v[140:143], v[84:87], v[184:187], v[140:143]
	v_mfma_f32_16x16x32_bf16 v[136:139], v[100:103], v[184:187], v[136:139]
	v_mfma_f32_16x16x32_bf16 v[136:139], v[92:95], v[180:183], v[136:139]
	v_mfma_f32_16x16x32_bf16 v[132:135], v[144:147], v[180:183], v[132:135]
	v_mfma_f32_16x16x32_bf16 v[132:135], v[148:151], v[184:187], v[132:135]
	v_mfma_f32_16x16x32_bf16 v[128:131], v[156:159], v[184:187], v[128:131]
	v_mfma_f32_16x16x32_bf16 v[128:131], v[152:155], v[180:183], v[128:131]
	v_mfma_f32_16x16x32_bf16 v[112:115], v[152:155], v[210:213], v[112:115]
	v_mfma_f32_16x16x32_bf16 v[112:115], v[156:159], v[214:217], v[112:115]
	v_mfma_f32_16x16x32_bf16 v[116:119], v[148:151], v[214:217], v[116:119]
	v_mfma_f32_16x16x32_bf16 v[116:119], v[144:147], v[210:213], v[116:119]
	v_mfma_f32_16x16x32_bf16 v[120:123], v[92:95], v[210:213], v[120:123]
	v_mfma_f32_16x16x32_bf16 v[120:123], v[100:103], v[214:217], v[120:123]
	v_mfma_f32_16x16x32_bf16 v[124:127], v[84:87], v[214:217], v[124:127]
	v_mfma_f32_16x16x32_bf16 v[124:127], v[80:83], v[210:213], v[124:127]
	s_setprio 0
	s_setprio 1
	v_mfma_f32_16x16x32_bf16 v[108:111], v[80:83], v[218:221], v[108:111]
	v_mfma_f32_16x16x32_bf16 v[108:111], v[84:87], v[222:225], v[108:111]
	v_mfma_f32_16x16x32_bf16 v[104:107], v[100:103], v[222:225], v[104:107]
	v_mfma_f32_16x16x32_bf16 v[104:107], v[92:95], v[218:221], v[104:107]
	v_mfma_f32_16x16x32_bf16 v[96:99], v[144:147], v[218:221], v[96:99]
	v_mfma_f32_16x16x32_bf16 v[96:99], v[148:151], v[222:225], v[96:99]
	v_mfma_f32_16x16x32_bf16 v[88:91], v[156:159], v[222:225], v[88:91]
	v_mfma_f32_16x16x32_bf16 v[88:91], v[152:155], v[218:221], v[88:91]
	v_mfma_f32_16x16x32_bf16 v[64:67], v[152:155], v[226:229], v[64:67]
	v_mfma_f32_16x16x32_bf16 v[64:67], v[156:159], v[230:233], v[64:67]
	v_mfma_f32_16x16x32_bf16 v[68:71], v[148:151], v[230:233], v[68:71]
	v_mfma_f32_16x16x32_bf16 v[68:71], v[144:147], v[226:229], v[68:71]
	v_mfma_f32_16x16x32_bf16 v[72:75], v[92:95], v[226:229], v[72:75]
	v_mfma_f32_16x16x32_bf16 v[72:75], v[100:103], v[230:233], v[72:75]
	s_setprio 2
	s_barrier
; #define PG8_STAGE(bufoff, gbase, voff) do { _Pragma("unroll") for (int _i = 0; _i < 2; ++_i) \
;         __builtin_amdgcn_global_load_lds((const unsigned*)((const char*)(gbase) + (voff)[_i]), (PG8_LAS unsigned*)(lds + (bufoff) + ldsw + _i * 8192), 16, 0, 0); } while (0)
; #define PG8_LDA(dst, b, h) do { _Pragma("unroll") for (int m = 0; m < 4; ++m) _Pragma("unroll") for (int k = 0; k < 2; ++k) dst[m][k] = *(const PG8_LAS bf16x8*)(lds + PG8_SA(b, h) + aoff + m * 2048 + k * 1024); } while (0)
; #define PG8_MMA(ai, bj, At, Bt) do { __builtin_amdgcn_s_setprio(1); _Pragma("unroll") for (int m = 0; m < 4; ++m) _Pragma("unroll") for (int n = 0; n < 2; ++n) _Pragma("unroll") for (int k = 0; k < 2; ++k) \
;         acc[ai][bj][m][n] = __builtin_amdgcn_mfma_f32_16x16x32_bf16(Bt[n][k], At[m][k], acc[ai][bj][m][n], 0, 0, 0); __builtin_amdgcn_s_setprio(0); } while (0)
; #define PG8_WAIT_V(n) asm volatile("s_waitcnt vmcnt(" #n ")" ::: "memory")
; #define PG8_WAIT_L(n) asm volatile("s_waitcnt lgkmcnt(" #n ")" ::: "memory")
; #define PG8_BAR __builtin_amdgcn_s_barrier()
; #define PG8_SCHED __builtin_amdgcn_sched_barrier(0)
; template <class Epi, class Sched, bool ALIGN_EPI = false, bool SP2 = false>
; __device__ __forceinline__ void gemm_phase(PG8_LAS unsigned char* lds, const Gemm g, const Sched& S, const Epi& E) {
;     ...
;             PG8_WAIT_V(8); PG8_WAIT_L(0); PG8_BAR; PG8_MMA(0, 0, At, B0); PG8_MMA(0, 1, At, B1); PG8_BAR; PG8_SCHED;
;             PG8_LDA(At, 1, 1); PG8_STAGE(PG8_SB(1, 0), b3, voffB); PG8_STAGE(PG8_SB(1, 1), b3 + hstep, voffB); PG8_STAGE(PG8_SA(1, 0), a3, voffA);
;             PG8_WAIT_V(8); PG8_WAIT_L(0); PG8_BAR; PG8_MMA(1, 0, At, B0); PG8_MMA(1, 1, At, B1); PG8_BAR; PG8_SCHED;
;     ...
;         if constexpr (ALIGN_EPI) { if (wr == 0) PG8_BAR; }
	v_mfma_f32_16x16x32_bf16 v[76:79], v[84:87], v[230:233], v[76:79]
	v_mfma_f32_16x16x32_bf16 v[76:79], v[80:83], v[226:229], v[76:79]
	s_setprio 0
	s_add_i32 s48, s77, s13
	v_lshl_add_u64 v[234:235], v[234:235], 0, s[50:51]
	s_mov_b32 m0, s48
	ds_read_b128 v[180:183], v207 offset:49152
	ds_read_b128 v[184:187], v207 offset:50176
	ds_read_b128 v[210:213], v207 offset:51200
	ds_read_b128 v[214:217], v207 offset:52224
	ds_read_b128 v[218:221], v207 offset:53248
	ds_read_b128 v[222:225], v207 offset:54272
	ds_read_b128 v[226:229], v207 offset:55296
	ds_read_b128 v[230:233], v207 offset:56320
	global_load_lds_dwordx4 v[234:235], off
	s_add_i32 m0, s48, 0x2000
	s_add_u32 s28, s28, 0x160080
	v_lshl_add_u64 v[234:235], v[236:237], 0, s[50:51]
	s_addc_u32 s29, s29, 0
	s_add_i32 s48, s78, s13
	global_load_lds_dwordx4 v[234:235], off
	v_lshl_add_u64 v[234:235], s[28:29], 0, v[160:161]
	s_mov_b32 m0, s48
	s_nop 0
	global_load_lds_dwordx4 v[234:235], off
	v_lshl_add_u64 v[234:235], s[28:29], 0, v[162:163]
	s_add_i32 m0, s48, 0x2000
	s_nop 0
	global_load_lds_dwordx4 v[234:235], off
	v_lshl_add_u64 v[234:235], v[238:239], 0, s[50:51]
	s_mov_b32 m0, s56
	s_nop 0
	global_load_lds_dwordx4 v[234:235], off
	v_lshl_add_u64 v[234:235], v[240:241], 0, s[50:51]
	s_mov_b32 m0, s57
	s_nop 0
	global_load_lds_dwordx4 v[234:235], off
	s_waitcnt vmcnt(8)
	s_waitcnt lgkmcnt(0)
	s_barrier
	s_setprio 1
	s_waitcnt lgkmcnt(0)
	v_mfma_f32_16x16x32_bf16 v[60:63], v[80:83], v[180:183], v[60:63]
	v_mfma_f32_16x16x32_bf16 v[60:63], v[84:87], v[184:187], v[60:63]
	v_mfma_f32_16x16x32_bf16 v[56:59], v[100:103], v[184:187], v[56:59]
	v_mfma_f32_16x16x32_bf16 v[56:59], v[92:95], v[180:183], v[56:59]
	v_mfma_f32_16x16x32_bf16 v[52:55], v[144:147], v[180:183], v[52:55]
	v_mfma_f32_16x16x32_bf16 v[52:55], v[148:151], v[184:187], v[52:55]
	v_mfma_f32_16x16x32_bf16 v[48:51], v[156:159], v[184:187], v[48:51]
	v_mfma_f32_16x16x32_bf16 v[48:51], v[152:155], v[180:183], v[48:51]
	v_mfma_f32_16x16x32_bf16 v[32:35], v[152:155], v[210:213], v[32:35]
	v_mfma_f32_16x16x32_bf16 v[32:35], v[156:159], v[214:217], v[32:35]
	v_mfma_f32_16x16x32_bf16 v[36:39], v[148:151], v[214:217], v[36:39]
	v_mfma_f32_16x16x32_bf16 v[36:39], v[144:147], v[210:213], v[36:39]
	v_mfma_f32_16x16x32_bf16 v[40:43], v[92:95], v[210:213], v[40:43]
	v_mfma_f32_16x16x32_bf16 v[40:43], v[100:103], v[214:217], v[40:43]
	v_mfma_f32_16x16x32_bf16 v[44:47], v[84:87], v[214:217], v[44:47]
	v_mfma_f32_16x16x32_bf16 v[44:47], v[80:83], v[210:213], v[44:47]
	s_setprio 0
	s_setprio 1
	v_mfma_f32_16x16x32_bf16 v[28:31], v[80:83], v[218:221], v[28:31]
	v_mfma_f32_16x16x32_bf16 v[28:31], v[84:87], v[222:225], v[28:31]
	v_mfma_f32_16x16x32_bf16 v[24:27], v[100:103], v[222:225], v[24:27]
	v_mfma_f32_16x16x32_bf16 v[24:27], v[92:95], v[218:221], v[24:27]
	v_mfma_f32_16x16x32_bf16 v[20:23], v[144:147], v[218:221], v[20:23]
	v_mfma_f32_16x16x32_bf16 v[20:23], v[148:151], v[222:225], v[20:23]
	v_mfma_f32_16x16x32_bf16 v[16:19], v[156:159], v[222:225], v[16:19]
	v_mfma_f32_16x16x32_bf16 v[16:19], v[152:155], v[218:221], v[16:19]
	v_mfma_f32_16x16x32_bf16 v[0:3], v[152:155], v[226:229], v[0:3]
	v_mfma_f32_16x16x32_bf16 v[0:3], v[156:159], v[230:233], v[0:3]
	v_mfma_f32_16x16x32_bf16 v[4:7], v[148:151], v[230:233], v[4:7]
	v_mfma_f32_16x16x32_bf16 v[4:7], v[144:147], v[226:229], v[4:7]
	v_mfma_f32_16x16x32_bf16 v[8:11], v[92:95], v[226:229], v[8:11]
	v_mfma_f32_16x16x32_bf16 v[8:11], v[100:103], v[230:233], v[8:11]
	s_setprio 2
	s_barrier
	v_mfma_f32_16x16x32_bf16 v[12:15], v[84:87], v[230:233], v[12:15]
	v_mfma_f32_16x16x32_bf16 v[12:15], v[80:83], v[226:229], v[12:15]
	s_setprio 0
	s_add_i32 s76, s76, 2
	s_add_u32 s72, s72, 0x100
	s_addc_u32 s73, s73, 0
	s_add_u32 s34, s34, 0x100
	s_addc_u32 s35, s35, 0
	s_cmpk_gt_u32 s76, 0x55
	s_cbranch_scc0 .LBB0_177
	s_and_b64 vcc, exec, s[52:53]
	s_cbranch_vccz .LBB0_180
	s_barrier

; #define PG8_STAGE(bufoff, gbase, voff) do { _Pragma("unroll") for (int _i = 0; _i < 2; ++_i) \
;         __builtin_amdgcn_global_load_lds((const unsigned*)((const char*)(gbase) + (voff)[_i]), (PG8_LAS unsigned*)(lds + (bufoff) + ldsw + _i * 8192), 16, 0, 0); } while (0)
; #define PG8_LDA(dst, b, h) do { _Pragma("unroll") for (int m = 0; m < 4; ++m) _Pragma("unroll") for (int k = 0; k < 2; ++k) dst[m][k] = *(const PG8_LAS bf16x8*)(lds + PG8_SA(b, h) + aoff + m * 2048 + k * 1024); } while (0)
; #define PG8_LDB(dst, b, h) do { _Pragma("unroll") for (int n = 0; n < 2; ++n) _Pragma("unroll") for (int k = 0; k < 2; ++k) dst[n][k] = *(const PG8_LAS bf16x8*)(lds + PG8_SB(b, h) + boff + n * 2048 + k * 1024); } while (0)
; #define PG8_MMA(ai, bj, At, Bt) do { __builtin_amdgcn_s_setprio(1); _Pragma("unroll") for (int m = 0; m < 4; ++m) _Pragma("unroll") for (int n = 0; n < 2; ++n) _Pragma("unroll") for (int k = 0; k < 2; ++k) \
;         acc[ai][bj][m][n] = __builtin_amdgcn_mfma_f32_16x16x32_bf16(Bt[n][k], At[m][k], acc[ai][bj][m][n], 0, 0, 0); __builtin_amdgcn_s_setprio(0); } while (0)
; #define PG8_WAIT_V(n) asm volatile("s_waitcnt vmcnt(" #n ")" ::: "memory")
; #define PG8_BAR __builtin_amdgcn_s_barrier()
; template <class Epi, class Sched, bool ALIGN_EPI = false, bool SP2 = false>
; __device__ __forceinline__ void gemm_phase(PG8_LAS unsigned char* lds, const Gemm g, const Sched& S, const Epi& E) {
;     ...
;         for (int t = 0; t < nt; t += 2) {
;             const bool last = (t == nt - 2);
;             const char* a1 = cA + (size_t)(t + 1) * kstep;
;             const char* a2 = last ? nA : cA + (size_t)(t + 2) * kstep; const char* b2 = last ? nB : cB + (size_t)(t + 2) * kstep;
;             const char* a3 = a2 + kstep; const char* b3 = b2 + kstep;
;             if (last && has_next) S.a_ready(nxt);
;             if constexpr (SP2) {
;             PG8_LDB(B0, 0, 0); PG8_LDB(B1, 0, 1); PG8_SCHED; PG8_LDA(At, 0, 0); PG8_STAGE(PG8_SA(1, 1), a1 + hstep, voffA);
;             PG8_WAIT_V(8); PG8_WAIT_L(0); PG8_BAR; PG8_MMA(0, 0, At, B0); PG8_MMA(0, 1, At, B1); PG8_BAR; PG8_SCHED;
;             PG8_LDA(At, 0, 1); PG8_STAGE(PG8_SB(0, 0), b2, voffB); PG8_STAGE(PG8_SB(0, 1), b2 + hstep, voffB); PG8_STAGE(PG8_SA(0, 0), a2, voffA);
;             PG8_WAIT_V(8); PG8_WAIT_L(0); PG8_BAR; PG8_MMA(1, 0, At, B0); PG8_MMA(1, 1, At, B1); PG8_BAR; PG8_SCHED;
.LBB0_231:
	ds_read_b128 v[142:145], v153
	ds_read_b128 v[146:149], v153 offset:1024
	ds_read_b128 v[174:177], v153 offset:2048
	ds_read_b128 v[178:181], v153 offset:3072
	ds_read_b128 v[182:185], v154
	ds_read_b128 v[206:209], v154 offset:1024
	ds_read_b128 v[210:213], v154 offset:2048
	ds_read_b128 v[214:217], v154 offset:3072
	s_add_u32 s28, s84, 0xfff80080
	s_addc_u32 s29, s85, -1
	s_cmp_eq_u32 s97, 28
	s_cselect_b32 s49, s34, s29
	s_cselect_b32 s48, s35, s28
	s_cselect_b32 s29, s75, s96
	s_cselect_b32 s28, s77, s95
	v_lshl_add_u64 v[158:159], s[84:85], 0, v[134:135]
	s_add_i32 m0, s56, 0xc000
	ds_read_b128 v[218:221], v155
	ds_read_b128 v[222:225], v155 offset:1024
	ds_read_b128 v[226:229], v155 offset:2048
	ds_read_b128 v[230:233], v155 offset:3072
	ds_read_b128 v[234:237], v155 offset:4096
	ds_read_b128 v[238:241], v155 offset:5120
	ds_read_b128 v[242:245], v155 offset:6144
	ds_read_b128 v[246:249], v155 offset:7168
	global_load_lds_dwordx4 v[158:159], off
	v_lshl_add_u64 v[158:159], s[84:85], 0, v[136:137]
	s_add_i32 m0, s56, 0xe000
	s_nop 0
	global_load_lds_dwordx4 v[158:159], off
	s_waitcnt vmcnt(8)
	s_waitcnt lgkmcnt(0)
	s_barrier
	s_setprio 1
	s_waitcnt lgkmcnt(0)
	v_mfma_f32_16x16x32_bf16 v[124:127], v[142:145], v[218:221], v[124:127]
	v_mfma_f32_16x16x32_bf16 v[124:127], v[146:149], v[222:225], v[124:127]
	v_mfma_f32_16x16x32_bf16 v[120:123], v[178:181], v[222:225], v[120:123]
	v_mfma_f32_16x16x32_bf16 v[120:123], v[174:177], v[218:221], v[120:123]
	v_mfma_f32_16x16x32_bf16 v[116:119], v[182:185], v[218:221], v[116:119]
	v_mfma_f32_16x16x32_bf16 v[116:119], v[206:209], v[222:225], v[116:119]
	v_mfma_f32_16x16x32_bf16 v[112:115], v[214:217], v[222:225], v[112:115]
	v_mfma_f32_16x16x32_bf16 v[112:115], v[210:213], v[218:221], v[112:115]
	v_mfma_f32_16x16x32_bf16 v[96:99], v[210:213], v[226:229], v[96:99]
	v_mfma_f32_16x16x32_bf16 v[96:99], v[214:217], v[230:233], v[96:99]
	v_mfma_f32_16x16x32_bf16 v[100:103], v[206:209], v[230:233], v[100:103]
	v_mfma_f32_16x16x32_bf16 v[100:103], v[182:185], v[226:229], v[100:103]
	v_mfma_f32_16x16x32_bf16 v[104:107], v[174:177], v[226:229], v[104:107]
	v_mfma_f32_16x16x32_bf16 v[104:107], v[178:181], v[230:233], v[104:107]
	v_mfma_f32_16x16x32_bf16 v[108:111], v[146:149], v[230:233], v[108:111]
	v_mfma_f32_16x16x32_bf16 v[108:111], v[142:145], v[226:229], v[108:111]
	s_setprio 0
	s_setprio 1
	v_mfma_f32_16x16x32_bf16 v[92:95], v[142:145], v[234:237], v[92:95]
	v_mfma_f32_16x16x32_bf16 v[92:95], v[146:149], v[238:241], v[92:95]
	v_mfma_f32_16x16x32_bf16 v[88:91], v[178:181], v[238:241], v[88:91]
	v_mfma_f32_16x16x32_bf16 v[88:91], v[174:177], v[234:237], v[88:91]
	v_mfma_f32_16x16x32_bf16 v[84:87], v[182:185], v[234:237], v[84:87]
	v_mfma_f32_16x16x32_bf16 v[84:87], v[206:209], v[238:241], v[84:87]
	v_mfma_f32_16x16x32_bf16 v[80:83], v[214:217], v[238:241], v[80:83]
	v_mfma_f32_16x16x32_bf16 v[80:83], v[210:213], v[234:237], v[80:83]
	v_mfma_f32_16x16x32_bf16 v[64:67], v[210:213], v[242:245], v[64:67]
	v_mfma_f32_16x16x32_bf16 v[64:67], v[214:217], v[246:249], v[64:67]
	v_mfma_f32_16x16x32_bf16 v[68:71], v[206:209], v[246:249], v[68:71]
	v_mfma_f32_16x16x32_bf16 v[68:71], v[182:185], v[242:245], v[68:71]
	v_mfma_f32_16x16x32_bf16 v[72:75], v[174:177], v[242:245], v[72:75]
	v_mfma_f32_16x16x32_bf16 v[72:75], v[178:181], v[246:249], v[72:75]
	s_setprio 2
	s_barrier
	v_mfma_f32_16x16x32_bf16 v[76:79], v[146:149], v[246:249], v[76:79]
	v_mfma_f32_16x16x32_bf16 v[76:79], v[142:145], v[242:245], v[76:79]
	s_setprio 0
	s_add_i32 vcc_lo, s83, s13
	v_lshl_add_u64 v[158:159], s[28:29], 0, v[166:167]
	s_mov_b32 m0, vcc_lo
	ds_read_b128 v[218:221], v155 offset:16384
	ds_read_b128 v[222:225], v155 offset:17408
	ds_read_b128 v[226:229], v155 offset:18432
	ds_read_b128 v[230:233], v155 offset:19456
	ds_read_b128 v[234:237], v155 offset:20480
	ds_read_b128 v[238:241], v155 offset:21504
	ds_read_b128 v[242:245], v155 offset:22528
	ds_read_b128 v[246:249], v155 offset:23552
	global_load_lds_dwordx4 v[158:159], off
	s_add_i32 m0, vcc_lo, 0x2000
	s_add_u32 vcc_lo, s28, 0x80000
	v_lshl_add_u64 v[186:187], s[28:29], 0, v[170:171]
	s_addc_u32 vcc_hi, s29, 0
	s_add_i32 s44, s90, s13
	global_load_lds_dwordx4 v[186:187], off
	v_lshl_add_u64 v[250:251], vcc, 0, v[166:167]
	s_mov_b32 m0, s44
	v_lshl_add_u64 v[252:253], s[48:49], 0, v[168:169]
	global_load_lds_dwordx4 v[250:251], off
	v_lshl_add_u64 v[250:251], vcc, 0, v[170:171]
	s_add_i32 m0, s44, 0x2000
	s_nop 0
	global_load_lds_dwordx4 v[250:251], off
	v_lshl_add_u64 v[250:251], s[48:49], 0, v[164:165]
	s_mov_b32 m0, s56
	s_nop 0
	global_load_lds_dwordx4 v[250:251], off
	s_mov_b32 m0, s57
	s_nop 0
	global_load_lds_dwordx4 v[252:253], off
	s_waitcnt vmcnt(8)
	s_waitcnt lgkmcnt(0)
	s_barrier
; #define PG8_STAGE(bufoff, gbase, voff) do { _Pragma("unroll") for (int _i = 0; _i < 2; ++_i) \
;         __builtin_amdgcn_global_load_lds((const unsigned*)((const char*)(gbase) + (voff)[_i]), (PG8_LAS unsigned*)(lds + (bufoff) + ldsw + _i * 8192), 16, 0, 0); } while (0)
; #define PG8_LDA(dst, b, h) do { _Pragma("unroll") for (int m = 0; m < 4; ++m) _Pragma("unroll") for (int k = 0; k < 2; ++k) dst[m][k] = *(const PG8_LAS bf16x8*)(lds + PG8_SA(b, h) + aoff + m * 2048 + k * 1024); } while (0)
; #define PG8_LDB(dst, b, h) do { _Pragma("unroll") for (int n = 0; n < 2; ++n) _Pragma("unroll") for (int k = 0; k < 2; ++k) dst[n][k] = *(const PG8_LAS bf16x8*)(lds + PG8_SB(b, h) + boff + n * 2048 + k * 1024); } while (0)
; #define PG8_MMA(ai, bj, At, Bt) do { __builtin_amdgcn_s_setprio(1); _Pragma("unroll") for (int m = 0; m < 4; ++m) _Pragma("unroll") for (int n = 0; n < 2; ++n) _Pragma("unroll") for (int k = 0; k < 2; ++k) \
;         acc[ai][bj][m][n] = __builtin_amdgcn_mfma_f32_16x16x32_bf16(Bt[n][k], At[m][k], acc[ai][bj][m][n], 0, 0, 0); __builtin_amdgcn_s_setprio(0); } while (0)
; #define PG8_WAIT_V(n) asm volatile("s_waitcnt vmcnt(" #n ")" ::: "memory")
; #define PG8_WAIT_L(n) asm volatile("s_waitcnt lgkmcnt(" #n ")" ::: "memory")
; #define PG8_BAR __builtin_amdgcn_s_barrier()
; #define PG8_SCHED __builtin_amdgcn_sched_barrier(0)
; template <class Epi, class Sched, bool ALIGN_EPI = false, bool SP2 = false>
; __device__ __forceinline__ void gemm_phase(PG8_LAS unsigned char* lds, const Gemm g, const Sched& S, const Epi& E) {
;     ...
;             PG8_WAIT_V(8); PG8_WAIT_L(0); PG8_BAR; PG8_MMA(1, 0, At, B0); PG8_MMA(1, 1, At, B1); PG8_BAR; PG8_SCHED;
;             PG8_LDB(B0, 1, 0); PG8_LDB(B1, 1, 1); PG8_SCHED; PG8_LDA(At, 1, 0); PG8_STAGE(PG8_SA(0, 1), a2 + hstep, voffA);
;             PG8_WAIT_V(8); PG8_WAIT_L(0); PG8_BAR; PG8_MMA(0, 0, At, B0); PG8_MMA(0, 1, At, B1); PG8_BAR; PG8_SCHED;
	s_setprio 1
	s_waitcnt lgkmcnt(0)
	v_mfma_f32_16x16x32_bf16 v[60:63], v[142:145], v[218:221], v[60:63]
	v_mfma_f32_16x16x32_bf16 v[60:63], v[146:149], v[222:225], v[60:63]
	v_mfma_f32_16x16x32_bf16 v[56:59], v[178:181], v[222:225], v[56:59]
	v_mfma_f32_16x16x32_bf16 v[56:59], v[174:177], v[218:221], v[56:59]
	v_mfma_f32_16x16x32_bf16 v[52:55], v[182:185], v[218:221], v[52:55]
	v_mfma_f32_16x16x32_bf16 v[52:55], v[206:209], v[222:225], v[52:55]
	v_mfma_f32_16x16x32_bf16 v[48:51], v[214:217], v[222:225], v[48:51]
	v_mfma_f32_16x16x32_bf16 v[48:51], v[210:213], v[218:221], v[48:51]
	v_mfma_f32_16x16x32_bf16 v[32:35], v[210:213], v[226:229], v[32:35]
	v_mfma_f32_16x16x32_bf16 v[32:35], v[214:217], v[230:233], v[32:35]
	v_mfma_f32_16x16x32_bf16 v[36:39], v[206:209], v[230:233], v[36:39]
	v_mfma_f32_16x16x32_bf16 v[36:39], v[182:185], v[226:229], v[36:39]
	v_mfma_f32_16x16x32_bf16 v[40:43], v[174:177], v[226:229], v[40:43]
	v_mfma_f32_16x16x32_bf16 v[40:43], v[178:181], v[230:233], v[40:43]
	v_mfma_f32_16x16x32_bf16 v[44:47], v[146:149], v[230:233], v[44:47]
	v_mfma_f32_16x16x32_bf16 v[44:47], v[142:145], v[226:229], v[44:47]
	s_setprio 0
	s_setprio 1
	v_mfma_f32_16x16x32_bf16 v[28:31], v[142:145], v[234:237], v[28:31]
	v_mfma_f32_16x16x32_bf16 v[28:31], v[146:149], v[238:241], v[28:31]
	v_mfma_f32_16x16x32_bf16 v[24:27], v[178:181], v[238:241], v[24:27]
	v_mfma_f32_16x16x32_bf16 v[24:27], v[174:177], v[234:237], v[24:27]
	v_mfma_f32_16x16x32_bf16 v[20:23], v[182:185], v[234:237], v[20:23]
	v_mfma_f32_16x16x32_bf16 v[20:23], v[206:209], v[238:241], v[20:23]
	v_mfma_f32_16x16x32_bf16 v[16:19], v[214:217], v[238:241], v[16:19]
	v_mfma_f32_16x16x32_bf16 v[16:19], v[210:213], v[234:237], v[16:19]
	v_mfma_f32_16x16x32_bf16 v[0:3], v[210:213], v[242:245], v[0:3]
	v_mfma_f32_16x16x32_bf16 v[0:3], v[214:217], v[246:249], v[0:3]
	v_mfma_f32_16x16x32_bf16 v[4:7], v[206:209], v[246:249], v[4:7]
	v_mfma_f32_16x16x32_bf16 v[4:7], v[182:185], v[242:245], v[4:7]
	v_mfma_f32_16x16x32_bf16 v[8:11], v[174:177], v[242:245], v[8:11]
	v_mfma_f32_16x16x32_bf16 v[8:11], v[178:181], v[246:249], v[8:11]
	s_setprio 2
	s_barrier
	v_mfma_f32_16x16x32_bf16 v[12:15], v[146:149], v[246:249], v[12:15]
	v_mfma_f32_16x16x32_bf16 v[12:15], v[142:145], v[242:245], v[12:15]
	s_setprio 0
	s_add_i32 s44, 0, 0x18000
	v_add_u32_e32 v161, s44, v151
	s_add_i32 s45, 0, 0x1c000
	ds_read_b128 v[142:145], v161
	ds_read_b128 v[146:149], v161 offset:1024
	ds_read_b128 v[174:177], v161 offset:2048
	ds_read_b128 v[178:181], v161 offset:3072
	v_add_u32_e32 v161, s45, v151
	ds_read_b128 v[182:185], v161
	ds_read_b128 v[206:209], v161 offset:1024
	ds_read_b128 v[210:213], v161 offset:2048
	ds_read_b128 v[214:217], v161 offset:3072
	s_add_u32 s48, s48, 0x80000
	s_addc_u32 s49, s49, 0
	s_mov_b32 m0, s60
	v_lshl_add_u64 v[200:201], s[48:49], 0, v[164:165]
	ds_read_b128 v[218:221], v155 offset:32768
	ds_read_b128 v[222:225], v155 offset:33792
	ds_read_b128 v[226:229], v155 offset:34816
	ds_read_b128 v[230:233], v155 offset:35840
	ds_read_b128 v[234:237], v155 offset:36864
	ds_read_b128 v[238:241], v155 offset:37888
	ds_read_b128 v[242:245], v155 offset:38912
	ds_read_b128 v[246:249], v155 offset:39936
	global_load_lds_dwordx4 v[200:201], off
	v_lshl_add_u64 v[200:201], s[48:49], 0, v[168:169]
	s_mov_b32 m0, s61
	s_nop 0
	global_load_lds_dwordx4 v[200:201], off
	s_waitcnt vmcnt(8)
	s_waitcnt lgkmcnt(0)
	s_barrier
	s_setprio 1
	s_waitcnt lgkmcnt(0)
	v_mfma_f32_16x16x32_bf16 v[124:127], v[142:145], v[218:221], v[124:127]
	v_mfma_f32_16x16x32_bf16 v[124:127], v[146:149], v[222:225], v[124:127]
	v_mfma_f32_16x16x32_bf16 v[120:123], v[178:181], v[222:225], v[120:123]
	v_mfma_f32_16x16x32_bf16 v[120:123], v[174:177], v[218:221], v[120:123]
	v_mfma_f32_16x16x32_bf16 v[116:119], v[182:185], v[218:221], v[116:119]
	v_mfma_f32_16x16x32_bf16 v[116:119], v[206:209], v[222:225], v[116:119]
	v_mfma_f32_16x16x32_bf16 v[112:115], v[214:217], v[222:225], v[112:115]
	v_mfma_f32_16x16x32_bf16 v[112:115], v[210:213], v[218:221], v[112:115]
	v_mfma_f32_16x16x32_bf16 v[96:99], v[210:213], v[226:229], v[96:99]
	v_mfma_f32_16x16x32_bf16 v[96:99], v[214:217], v[230:233], v[96:99]
	v_mfma_f32_16x16x32_bf16 v[100:103], v[206:209], v[230:233], v[100:103]
	v_mfma_f32_16x16x32_bf16 v[100:103], v[182:185], v[226:229], v[100:103]
	v_mfma_f32_16x16x32_bf16 v[104:107], v[174:177], v[226:229], v[104:107]
	v_mfma_f32_16x16x32_bf16 v[104:107], v[178:181], v[230:233], v[104:107]
	v_mfma_f32_16x16x32_bf16 v[108:111], v[146:149], v[230:233], v[108:111]
	v_mfma_f32_16x16x32_bf16 v[108:111], v[142:145], v[226:229], v[108:111]
	s_setprio 0
	s_setprio 1
	v_mfma_f32_16x16x32_bf16 v[92:95], v[142:145], v[234:237], v[92:95]
	v_mfma_f32_16x16x32_bf16 v[92:95], v[146:149], v[238:241], v[92:95]
	v_mfma_f32_16x16x32_bf16 v[88:91], v[178:181], v[238:241], v[88:91]
	v_mfma_f32_16x16x32_bf16 v[88:91], v[174:177], v[234:237], v[88:91]
	v_mfma_f32_16x16x32_bf16 v[84:87], v[182:185], v[234:237], v[84:87]
	v_mfma_f32_16x16x32_bf16 v[84:87], v[206:209], v[238:241], v[84:87]
	v_mfma_f32_16x16x32_bf16 v[80:83], v[214:217], v[238:241], v[80:83]
	v_mfma_f32_16x16x32_bf16 v[80:83], v[210:213], v[234:237], v[80:83]
	v_mfma_f32_16x16x32_bf16 v[64:67], v[210:213], v[242:245], v[64:67]
	v_mfma_f32_16x16x32_bf16 v[64:67], v[214:217], v[246:249], v[64:67]
	v_mfma_f32_16x16x32_bf16 v[68:71], v[206:209], v[246:249], v[68:71]
	v_mfma_f32_16x16x32_bf16 v[68:71], v[182:185], v[242:245], v[68:71]
	v_mfma_f32_16x16x32_bf16 v[72:75], v[174:177], v[242:245], v[72:75]
	v_mfma_f32_16x16x32_bf16 v[72:75], v[178:181], v[246:249], v[72:75]
	s_setprio 2
	s_barrier
; #define PG8_STAGE(bufoff, gbase, voff) do { _Pragma("unroll") for (int _i = 0; _i < 2; ++_i) \
;         __builtin_amdgcn_global_load_lds((const unsigned*)((const char*)(gbase) + (voff)[_i]), (PG8_LAS unsigned*)(lds + (bufoff) + ldsw + _i * 8192), 16, 0, 0); } while (0)
; #define PG8_LDA(dst, b, h) do { _Pragma("unroll") for (int m = 0; m < 4; ++m) _Pragma("unroll") for (int k = 0; k < 2; ++k) dst[m][k] = *(const PG8_LAS bf16x8*)(lds + PG8_SA(b, h) + aoff + m * 2048 + k * 1024); } while (0)
; #define PG8_MMA(ai, bj, At, Bt) do { __builtin_amdgcn_s_setprio(1); _Pragma("unroll") for (int m = 0; m < 4; ++m) _Pragma("unroll") for (int n = 0; n < 2; ++n) _Pragma("unroll") for (int k = 0; k < 2; ++k) \
;         acc[ai][bj][m][n] = __builtin_amdgcn_mfma_f32_16x16x32_bf16(Bt[n][k], At[m][k], acc[ai][bj][m][n], 0, 0, 0); __builtin_amdgcn_s_setprio(0); } while (0)
; #define PG8_WAIT_V(n) asm volatile("s_waitcnt vmcnt(" #n ")" ::: "memory")
; #define PG8_WAIT_L(n) asm volatile("s_waitcnt lgkmcnt(" #n ")" ::: "memory")
; #define PG8_BAR __builtin_amdgcn_s_barrier()
; #define PG8_SCHED __builtin_amdgcn_sched_barrier(0)
; template <class Epi, class Sched, bool ALIGN_EPI = false, bool SP2 = false>
; __device__ __forceinline__ void gemm_phase(PG8_LAS unsigned char* lds, const Gemm g, const Sched& S, const Epi& E) {
;     ...
;             PG8_WAIT_V(8); PG8_WAIT_L(0); PG8_BAR; PG8_MMA(0, 0, At, B0); PG8_MMA(0, 1, At, B1); PG8_BAR; PG8_SCHED;
;             PG8_LDA(At, 1, 1); PG8_STAGE(PG8_SB(1, 0), b3, voffB); PG8_STAGE(PG8_SB(1, 1), b3 + hstep, voffB); PG8_STAGE(PG8_SA(1, 0), a3, voffA);
;             PG8_WAIT_V(8); PG8_WAIT_L(0); PG8_BAR; PG8_MMA(1, 0, At, B0); PG8_MMA(1, 1, At, B1); PG8_BAR; PG8_SCHED;
;     ...
;         if constexpr (ALIGN_EPI) { if (wr == 0) PG8_BAR; }
;         if constexpr (!Epi::AFTER_DRAIN) { E(acc, cur, wr, wc, fr, fq); S.done(cur); }
;         if (!has_next) break;
	v_mfma_f32_16x16x32_bf16 v[76:79], v[146:149], v[246:249], v[76:79]
	v_mfma_f32_16x16x32_bf16 v[76:79], v[142:145], v[242:245], v[76:79]
	s_setprio 0
	s_add_i32 s44, s44, s13
	v_lshl_add_u64 v[158:159], v[158:159], 0, s[52:53]
	s_mov_b32 m0, s44
	ds_read_b128 v[218:221], v155 offset:49152
	ds_read_b128 v[222:225], v155 offset:50176
	ds_read_b128 v[226:229], v155 offset:51200
	ds_read_b128 v[230:233], v155 offset:52224
	ds_read_b128 v[234:237], v155 offset:53248
	ds_read_b128 v[238:241], v155 offset:54272
	ds_read_b128 v[242:245], v155 offset:55296
	ds_read_b128 v[246:249], v155 offset:56320
	global_load_lds_dwordx4 v[158:159], off
	s_add_i32 m0, s44, 0x2000
	s_add_u32 s28, s28, 0x80080
	v_lshl_add_u64 v[158:159], v[186:187], 0, s[52:53]
	s_addc_u32 s29, s29, 0
	s_add_i32 s44, s45, s13
	global_load_lds_dwordx4 v[158:159], off
	v_lshl_add_u64 v[158:159], s[28:29], 0, v[166:167]
	s_mov_b32 m0, s44
	s_nop 0
	global_load_lds_dwordx4 v[158:159], off
	v_lshl_add_u64 v[158:159], s[28:29], 0, v[170:171]
	s_add_i32 m0, s44, 0x2000
	s_nop 0
	global_load_lds_dwordx4 v[158:159], off
	v_lshl_add_u64 v[158:159], v[250:251], 0, s[52:53]
	s_mov_b32 m0, s62
	s_nop 0
	global_load_lds_dwordx4 v[158:159], off
	v_lshl_add_u64 v[158:159], v[252:253], 0, s[52:53]
	s_mov_b32 m0, s63
	s_nop 0
	global_load_lds_dwordx4 v[158:159], off
	s_waitcnt vmcnt(8)
	s_waitcnt lgkmcnt(0)
	s_barrier
	s_setprio 1
	s_waitcnt lgkmcnt(0)
	v_mfma_f32_16x16x32_bf16 v[60:63], v[142:145], v[218:221], v[60:63]
	v_mfma_f32_16x16x32_bf16 v[60:63], v[146:149], v[222:225], v[60:63]
	v_mfma_f32_16x16x32_bf16 v[56:59], v[178:181], v[222:225], v[56:59]
	v_mfma_f32_16x16x32_bf16 v[56:59], v[174:177], v[218:221], v[56:59]
	v_mfma_f32_16x16x32_bf16 v[52:55], v[182:185], v[218:221], v[52:55]
	v_mfma_f32_16x16x32_bf16 v[52:55], v[206:209], v[222:225], v[52:55]
	v_mfma_f32_16x16x32_bf16 v[48:51], v[214:217], v[222:225], v[48:51]
	v_mfma_f32_16x16x32_bf16 v[48:51], v[210:213], v[218:221], v[48:51]
	v_mfma_f32_16x16x32_bf16 v[32:35], v[210:213], v[226:229], v[32:35]
	v_mfma_f32_16x16x32_bf16 v[32:35], v[214:217], v[230:233], v[32:35]
	v_mfma_f32_16x16x32_bf16 v[36:39], v[206:209], v[230:233], v[36:39]
	v_mfma_f32_16x16x32_bf16 v[36:39], v[182:185], v[226:229], v[36:39]
	v_mfma_f32_16x16x32_bf16 v[40:43], v[174:177], v[226:229], v[40:43]
	v_mfma_f32_16x16x32_bf16 v[40:43], v[178:181], v[230:233], v[40:43]
	v_mfma_f32_16x16x32_bf16 v[44:47], v[146:149], v[230:233], v[44:47]
	v_mfma_f32_16x16x32_bf16 v[44:47], v[142:145], v[226:229], v[44:47]
	s_setprio 0
	s_setprio 1
	v_mfma_f32_16x16x32_bf16 v[28:31], v[142:145], v[234:237], v[28:31]
	v_mfma_f32_16x16x32_bf16 v[28:31], v[146:149], v[238:241], v[28:31]
	v_mfma_f32_16x16x32_bf16 v[24:27], v[178:181], v[238:241], v[24:27]
	v_mfma_f32_16x16x32_bf16 v[24:27], v[174:177], v[234:237], v[24:27]
	v_mfma_f32_16x16x32_bf16 v[20:23], v[182:185], v[234:237], v[20:23]
	v_mfma_f32_16x16x32_bf16 v[20:23], v[206:209], v[238:241], v[20:23]
	v_mfma_f32_16x16x32_bf16 v[16:19], v[214:217], v[238:241], v[16:19]
	v_mfma_f32_16x16x32_bf16 v[16:19], v[210:213], v[234:237], v[16:19]
	v_mfma_f32_16x16x32_bf16 v[0:3], v[210:213], v[242:245], v[0:3]
	v_mfma_f32_16x16x32_bf16 v[0:3], v[214:217], v[246:249], v[0:3]
	v_mfma_f32_16x16x32_bf16 v[4:7], v[206:209], v[246:249], v[4:7]
	v_mfma_f32_16x16x32_bf16 v[4:7], v[182:185], v[242:245], v[4:7]
	v_mfma_f32_16x16x32_bf16 v[8:11], v[174:177], v[242:245], v[8:11]
	v_mfma_f32_16x16x32_bf16 v[8:11], v[178:181], v[246:249], v[8:11]
	s_setprio 2
	s_barrier
	v_mfma_f32_16x16x32_bf16 v[12:15], v[146:149], v[246:249], v[12:15]
	v_mfma_f32_16x16x32_bf16 v[12:15], v[142:145], v[242:245], v[12:15]
	s_setprio 0
	s_add_i32 s97, s97, 2
	s_add_u32 s84, s84, 0x100
	s_addc_u32 s85, s85, 0
	s_add_u32 s95, s95, 0x100
	s_addc_u32 s96, s96, 0
	s_cmp_gt_u32 s97, 29
	s_cbranch_scc0 .LBB0_231
	s_and_b64 vcc, exec, s[72:73]
	s_cbranch_vccz .LBB0_236
	s_barrier
	v_lshl_add_u32 v142, s82, 8, v150
	s_cmp_gt_i32 s94, 7
	s_mov_b64 s[28:29], -1
	s_cbranch_scc1 .LBB0_237

; #define PG8_STAGE(bufoff, gbase, voff) do { _Pragma("unroll") for (int _i = 0; _i < 2; ++_i) \
;         __builtin_amdgcn_global_load_lds((const unsigned*)((const char*)(gbase) + (voff)[_i]), (PG8_LAS unsigned*)(lds + (bufoff) + ldsw + _i * 8192), 16, 0, 0); } while (0)
; #define PG8_LDA(dst, b, h) do { _Pragma("unroll") for (int m = 0; m < 4; ++m) _Pragma("unroll") for (int k = 0; k < 2; ++k) dst[m][k] = *(const PG8_LAS bf16x8*)(lds + PG8_SA(b, h) + aoff + m * 2048 + k * 1024); } while (0)
; #define PG8_LDB(dst, b, h) do { _Pragma("unroll") for (int n = 0; n < 2; ++n) _Pragma("unroll") for (int k = 0; k < 2; ++k) dst[n][k] = *(const PG8_LAS bf16x8*)(lds + PG8_SB(b, h) + boff + n * 2048 + k * 1024); } while (0)
; #define PG8_MMA(ai, bj, At, Bt) do { __builtin_amdgcn_s_setprio(1); _Pragma("unroll") for (int m = 0; m < 4; ++m) _Pragma("unroll") for (int n = 0; n < 2; ++n) _Pragma("unroll") for (int k = 0; k < 2; ++k) \
;         acc[ai][bj][m][n] = __builtin_amdgcn_mfma_f32_16x16x32_bf16(Bt[n][k], At[m][k], acc[ai][bj][m][n], 0, 0, 0); __builtin_amdgcn_s_setprio(0); } while (0)
; #define PG8_WAIT_V(n) asm volatile("s_waitcnt vmcnt(" #n ")" ::: "memory")
; #define PG8_BAR __builtin_amdgcn_s_barrier()
; template <class Epi, class Sched, bool ALIGN_EPI = false, bool SP2 = false>
; __device__ __forceinline__ void gemm_phase(PG8_LAS unsigned char* lds, const Gemm g, const Sched& S, const Epi& E) {
;     ...
;         for (int t = 0; t < nt; t += 2) {
;             const bool last = (t == nt - 2);
;             const char* a1 = cA + (size_t)(t + 1) * kstep;
;             const char* a2 = last ? nA : cA + (size_t)(t + 2) * kstep; const char* b2 = last ? nB : cB + (size_t)(t + 2) * kstep;
;             const char* a3 = a2 + kstep; const char* b3 = b2 + kstep;
;             if (last && has_next) S.a_ready(nxt);
;             if constexpr (SP2) {
;             PG8_LDB(B0, 0, 0); PG8_LDB(B1, 0, 1); PG8_SCHED; PG8_LDA(At, 0, 0); PG8_STAGE(PG8_SA(1, 1), a1 + hstep, voffA);
;             PG8_WAIT_V(8); PG8_WAIT_L(0); PG8_BAR; PG8_MMA(0, 0, At, B0); PG8_MMA(0, 1, At, B1); PG8_BAR; PG8_SCHED;
;             PG8_LDA(At, 0, 1); PG8_STAGE(PG8_SB(0, 0), b2, voffB); PG8_STAGE(PG8_SB(0, 1), b2 + hstep, voffB); PG8_STAGE(PG8_SA(0, 0), a2, voffA);
;             PG8_WAIT_V(8); PG8_WAIT_L(0); PG8_BAR; PG8_MMA(1, 0, At, B0); PG8_MMA(1, 1, At, B1); PG8_BAR; PG8_SCHED;
.LBB0_362:
	ds_read_b128 v[80:83], v171
	ds_read_b128 v[84:87], v171 offset:1024
	ds_read_b128 v[92:95], v171 offset:2048
	ds_read_b128 v[100:103], v171 offset:3072
	ds_read_b128 v[144:147], v186
	ds_read_b128 v[148:151], v186 offset:1024
	ds_read_b128 v[152:155], v186 offset:2048
	ds_read_b128 v[156:159], v186 offset:3072
	s_add_u32 s28, s74, 0xfff80080
	s_addc_u32 s29, s75, -1
	s_cmp_eq_u32 s77, 28
	s_cselect_b32 s49, s23, s29
	s_cselect_b32 s48, s34, s28
	s_cselect_b32 s29, s21, s76
	s_cselect_b32 s28, s35, s73
	v_lshl_add_u64 v[200:201], s[74:75], 0, v[172:173]
	s_add_i32 m0, s38, 0xc000
	ds_read_b128 v[178:181], v187
	ds_read_b128 v[182:185], v187 offset:1024
	ds_read_b128 v[206:209], v187 offset:2048
	ds_read_b128 v[210:213], v187 offset:3072
	ds_read_b128 v[214:217], v187 offset:4096
	ds_read_b128 v[218:221], v187 offset:5120
	ds_read_b128 v[222:225], v187 offset:6144
	ds_read_b128 v[226:229], v187 offset:7168
	global_load_lds_dwordx4 v[200:201], off
	v_lshl_add_u64 v[200:201], s[74:75], 0, v[174:175]
	s_add_i32 m0, s38, 0xe000
	s_nop 0
	global_load_lds_dwordx4 v[200:201], off
	s_waitcnt vmcnt(8)
	s_waitcnt lgkmcnt(0)
	s_barrier
	s_setprio 1
	s_waitcnt lgkmcnt(0)
	v_mfma_f32_16x16x32_bf16 v[140:143], v[80:83], v[178:181], v[140:143]
	v_mfma_f32_16x16x32_bf16 v[140:143], v[84:87], v[182:185], v[140:143]
	v_mfma_f32_16x16x32_bf16 v[136:139], v[100:103], v[182:185], v[136:139]
	v_mfma_f32_16x16x32_bf16 v[136:139], v[92:95], v[178:181], v[136:139]
	v_mfma_f32_16x16x32_bf16 v[132:135], v[144:147], v[178:181], v[132:135]
	v_mfma_f32_16x16x32_bf16 v[132:135], v[148:151], v[182:185], v[132:135]
	v_mfma_f32_16x16x32_bf16 v[128:131], v[156:159], v[182:185], v[128:131]
	v_mfma_f32_16x16x32_bf16 v[128:131], v[152:155], v[178:181], v[128:131]
	v_mfma_f32_16x16x32_bf16 v[112:115], v[152:155], v[206:209], v[112:115]
	v_mfma_f32_16x16x32_bf16 v[112:115], v[156:159], v[210:213], v[112:115]
	v_mfma_f32_16x16x32_bf16 v[116:119], v[148:151], v[210:213], v[116:119]
	v_mfma_f32_16x16x32_bf16 v[116:119], v[144:147], v[206:209], v[116:119]
	v_mfma_f32_16x16x32_bf16 v[120:123], v[92:95], v[206:209], v[120:123]
	v_mfma_f32_16x16x32_bf16 v[120:123], v[100:103], v[210:213], v[120:123]
	v_mfma_f32_16x16x32_bf16 v[124:127], v[84:87], v[210:213], v[124:127]
	v_mfma_f32_16x16x32_bf16 v[124:127], v[80:83], v[206:209], v[124:127]
	s_setprio 0
	s_setprio 1
	v_mfma_f32_16x16x32_bf16 v[108:111], v[80:83], v[214:217], v[108:111]
	v_mfma_f32_16x16x32_bf16 v[108:111], v[84:87], v[218:221], v[108:111]
	v_mfma_f32_16x16x32_bf16 v[104:107], v[100:103], v[218:221], v[104:107]
	v_mfma_f32_16x16x32_bf16 v[104:107], v[92:95], v[214:217], v[104:107]
	v_mfma_f32_16x16x32_bf16 v[96:99], v[144:147], v[214:217], v[96:99]
	v_mfma_f32_16x16x32_bf16 v[96:99], v[148:151], v[218:221], v[96:99]
	v_mfma_f32_16x16x32_bf16 v[88:91], v[156:159], v[218:221], v[88:91]
	v_mfma_f32_16x16x32_bf16 v[88:91], v[152:155], v[214:217], v[88:91]
	v_mfma_f32_16x16x32_bf16 v[64:67], v[152:155], v[222:225], v[64:67]
	v_mfma_f32_16x16x32_bf16 v[64:67], v[156:159], v[226:229], v[64:67]
	v_mfma_f32_16x16x32_bf16 v[68:71], v[148:151], v[226:229], v[68:71]
	v_mfma_f32_16x16x32_bf16 v[68:71], v[144:147], v[222:225], v[68:71]
	v_mfma_f32_16x16x32_bf16 v[72:75], v[92:95], v[222:225], v[72:75]
	v_mfma_f32_16x16x32_bf16 v[72:75], v[100:103], v[226:229], v[72:75]
	s_setprio 2
	s_barrier
	v_mfma_f32_16x16x32_bf16 v[76:79], v[84:87], v[226:229], v[76:79]
	v_mfma_f32_16x16x32_bf16 v[76:79], v[80:83], v[222:225], v[76:79]
	s_setprio 0
	s_add_i32 s44, s62, s13
	v_lshl_add_u64 v[200:201], s[28:29], 0, v[164:165]
	s_mov_b32 m0, s44
	ds_read_b128 v[178:181], v187 offset:16384
	ds_read_b128 v[182:185], v187 offset:17408
	ds_read_b128 v[206:209], v187 offset:18432
	ds_read_b128 v[210:213], v187 offset:19456
	ds_read_b128 v[214:217], v187 offset:20480
	ds_read_b128 v[218:221], v187 offset:21504
	ds_read_b128 v[222:225], v187 offset:22528
	ds_read_b128 v[226:229], v187 offset:23552
	global_load_lds_dwordx4 v[200:201], off
	s_add_i32 m0, s44, 0x2000
	s_add_u32 s78, s28, 0x80000
	v_lshl_add_u64 v[230:231], s[28:29], 0, v[168:169]
	s_addc_u32 s79, s29, 0
	s_add_i32 s44, s63, s13
	global_load_lds_dwordx4 v[230:231], off
	v_lshl_add_u64 v[232:233], s[78:79], 0, v[164:165]
	s_mov_b32 m0, s44
	v_lshl_add_u64 v[234:235], s[48:49], 0, v[168:169]
	global_load_lds_dwordx4 v[232:233], off
	v_lshl_add_u64 v[232:233], s[78:79], 0, v[168:169]
	s_add_i32 m0, s44, 0x2000
	s_nop 0
	global_load_lds_dwordx4 v[232:233], off
	v_lshl_add_u64 v[232:233], s[48:49], 0, v[164:165]
	s_mov_b32 m0, s38
	s_nop 0
	global_load_lds_dwordx4 v[232:233], off
	s_mov_b32 m0, s39
	s_nop 0
	global_load_lds_dwordx4 v[234:235], off
	s_waitcnt vmcnt(8)
	s_waitcnt lgkmcnt(0)
	s_barrier
; #define PG8_STAGE(bufoff, gbase, voff) do { _Pragma("unroll") for (int _i = 0; _i < 2; ++_i) \
;         __builtin_amdgcn_global_load_lds((const unsigned*)((const char*)(gbase) + (voff)[_i]), (PG8_LAS unsigned*)(lds + (bufoff) + ldsw + _i * 8192), 16, 0, 0); } while (0)
; #define PG8_LDA(dst, b, h) do { _Pragma("unroll") for (int m = 0; m < 4; ++m) _Pragma("unroll") for (int k = 0; k < 2; ++k) dst[m][k] = *(const PG8_LAS bf16x8*)(lds + PG8_SA(b, h) + aoff + m * 2048 + k * 1024); } while (0)
; #define PG8_LDB(dst, b, h) do { _Pragma("unroll") for (int n = 0; n < 2; ++n) _Pragma("unroll") for (int k = 0; k < 2; ++k) dst[n][k] = *(const PG8_LAS bf16x8*)(lds + PG8_SB(b, h) + boff + n * 2048 + k * 1024); } while (0)
; #define PG8_MMA(ai, bj, At, Bt) do { __builtin_amdgcn_s_setprio(1); _Pragma("unroll") for (int m = 0; m < 4; ++m) _Pragma("unroll") for (int n = 0; n < 2; ++n) _Pragma("unroll") for (int k = 0; k < 2; ++k) \
;         acc[ai][bj][m][n] = __builtin_amdgcn_mfma_f32_16x16x32_bf16(Bt[n][k], At[m][k], acc[ai][bj][m][n], 0, 0, 0); __builtin_amdgcn_s_setprio(0); } while (0)
; #define PG8_WAIT_V(n) asm volatile("s_waitcnt vmcnt(" #n ")" ::: "memory")
; #define PG8_WAIT_L(n) asm volatile("s_waitcnt lgkmcnt(" #n ")" ::: "memory")
; #define PG8_BAR __builtin_amdgcn_s_barrier()
; #define PG8_SCHED __builtin_amdgcn_sched_barrier(0)
; template <class Epi, class Sched, bool ALIGN_EPI = false, bool SP2 = false>
; __device__ __forceinline__ void gemm_phase(PG8_LAS unsigned char* lds, const Gemm g, const Sched& S, const Epi& E) {
;     ...
;             PG8_WAIT_V(8); PG8_WAIT_L(0); PG8_BAR; PG8_MMA(1, 0, At, B0); PG8_MMA(1, 1, At, B1); PG8_BAR; PG8_SCHED;
;             PG8_LDB(B0, 1, 0); PG8_LDB(B1, 1, 1); PG8_SCHED; PG8_LDA(At, 1, 0); PG8_STAGE(PG8_SA(0, 1), a2 + hstep, voffA);
;             PG8_WAIT_V(8); PG8_WAIT_L(0); PG8_BAR; PG8_MMA(0, 0, At, B0); PG8_MMA(0, 1, At, B1); PG8_BAR; PG8_SCHED;
	s_setprio 1
	s_waitcnt lgkmcnt(0)
	v_mfma_f32_16x16x32_bf16 v[60:63], v[80:83], v[178:181], v[60:63]
	v_mfma_f32_16x16x32_bf16 v[60:63], v[84:87], v[182:185], v[60:63]
	v_mfma_f32_16x16x32_bf16 v[56:59], v[100:103], v[182:185], v[56:59]
	v_mfma_f32_16x16x32_bf16 v[56:59], v[92:95], v[178:181], v[56:59]
	v_mfma_f32_16x16x32_bf16 v[52:55], v[144:147], v[178:181], v[52:55]
	v_mfma_f32_16x16x32_bf16 v[52:55], v[148:151], v[182:185], v[52:55]
	v_mfma_f32_16x16x32_bf16 v[48:51], v[156:159], v[182:185], v[48:51]
	v_mfma_f32_16x16x32_bf16 v[48:51], v[152:155], v[178:181], v[48:51]
	v_mfma_f32_16x16x32_bf16 v[32:35], v[152:155], v[206:209], v[32:35]
	v_mfma_f32_16x16x32_bf16 v[32:35], v[156:159], v[210:213], v[32:35]
	v_mfma_f32_16x16x32_bf16 v[36:39], v[148:151], v[210:213], v[36:39]
	v_mfma_f32_16x16x32_bf16 v[36:39], v[144:147], v[206:209], v[36:39]
	v_mfma_f32_16x16x32_bf16 v[40:43], v[92:95], v[206:209], v[40:43]
	v_mfma_f32_16x16x32_bf16 v[40:43], v[100:103], v[210:213], v[40:43]
	v_mfma_f32_16x16x32_bf16 v[44:47], v[84:87], v[210:213], v[44:47]
	v_mfma_f32_16x16x32_bf16 v[44:47], v[80:83], v[206:209], v[44:47]
	s_setprio 0
	s_setprio 1
	v_mfma_f32_16x16x32_bf16 v[28:31], v[80:83], v[214:217], v[28:31]
	v_mfma_f32_16x16x32_bf16 v[28:31], v[84:87], v[218:221], v[28:31]
	v_mfma_f32_16x16x32_bf16 v[24:27], v[100:103], v[218:221], v[24:27]
	v_mfma_f32_16x16x32_bf16 v[24:27], v[92:95], v[214:217], v[24:27]
	v_mfma_f32_16x16x32_bf16 v[20:23], v[144:147], v[214:217], v[20:23]
	v_mfma_f32_16x16x32_bf16 v[20:23], v[148:151], v[218:221], v[20:23]
	v_mfma_f32_16x16x32_bf16 v[16:19], v[156:159], v[218:221], v[16:19]
	v_mfma_f32_16x16x32_bf16 v[16:19], v[152:155], v[214:217], v[16:19]
	v_mfma_f32_16x16x32_bf16 v[0:3], v[152:155], v[222:225], v[0:3]
	v_mfma_f32_16x16x32_bf16 v[0:3], v[156:159], v[226:229], v[0:3]
	v_mfma_f32_16x16x32_bf16 v[4:7], v[148:151], v[226:229], v[4:7]
	v_mfma_f32_16x16x32_bf16 v[4:7], v[144:147], v[222:225], v[4:7]
	v_mfma_f32_16x16x32_bf16 v[8:11], v[92:95], v[222:225], v[8:11]
	v_mfma_f32_16x16x32_bf16 v[8:11], v[100:103], v[226:229], v[8:11]
	s_setprio 2
	s_barrier
	v_mfma_f32_16x16x32_bf16 v[12:15], v[84:87], v[226:229], v[12:15]
	v_mfma_f32_16x16x32_bf16 v[12:15], v[80:83], v[222:225], v[12:15]
	s_setprio 0
	s_add_i32 s44, 0, 0x18000
	s_add_i32 s45, 0, 0x1c000
	v_add_u32_e32 v100, s44, v163
	v_add_u32_e32 v156, s45, v163
	ds_read_b128 v[80:83], v100
	ds_read_b128 v[84:87], v100 offset:1024
	ds_read_b128 v[92:95], v100 offset:2048
	ds_read_b128 v[100:103], v100 offset:3072
	ds_read_b128 v[144:147], v156
	ds_read_b128 v[148:151], v156 offset:1024
	ds_read_b128 v[152:155], v156 offset:2048
	ds_read_b128 v[156:159], v156 offset:3072
	s_add_u32 s48, s48, 0x80000
	s_addc_u32 s49, s49, 0
	s_mov_b32 m0, s40
	v_lshl_add_u64 v[236:237], s[48:49], 0, v[164:165]
	ds_read_b128 v[178:181], v187 offset:32768
	ds_read_b128 v[182:185], v187 offset:33792
	ds_read_b128 v[206:209], v187 offset:34816
	ds_read_b128 v[210:213], v187 offset:35840
	ds_read_b128 v[214:217], v187 offset:36864
	ds_read_b128 v[218:221], v187 offset:37888
	ds_read_b128 v[222:225], v187 offset:38912
	ds_read_b128 v[226:229], v187 offset:39936
	global_load_lds_dwordx4 v[236:237], off
	v_lshl_add_u64 v[236:237], s[48:49], 0, v[168:169]
	s_mov_b32 m0, s41
	s_nop 0
	global_load_lds_dwordx4 v[236:237], off
	s_waitcnt vmcnt(8)
	s_waitcnt lgkmcnt(0)
	s_barrier
	s_setprio 1
	s_waitcnt lgkmcnt(0)
	v_mfma_f32_16x16x32_bf16 v[140:143], v[80:83], v[178:181], v[140:143]
	v_mfma_f32_16x16x32_bf16 v[140:143], v[84:87], v[182:185], v[140:143]
	v_mfma_f32_16x16x32_bf16 v[136:139], v[100:103], v[182:185], v[136:139]
	v_mfma_f32_16x16x32_bf16 v[136:139], v[92:95], v[178:181], v[136:139]
	v_mfma_f32_16x16x32_bf16 v[132:135], v[144:147], v[178:181], v[132:135]
	v_mfma_f32_16x16x32_bf16 v[132:135], v[148:151], v[182:185], v[132:135]
	v_mfma_f32_16x16x32_bf16 v[128:131], v[156:159], v[182:185], v[128:131]
	v_mfma_f32_16x16x32_bf16 v[128:131], v[152:155], v[178:181], v[128:131]
	v_mfma_f32_16x16x32_bf16 v[112:115], v[152:155], v[206:209], v[112:115]
	v_mfma_f32_16x16x32_bf16 v[112:115], v[156:159], v[210:213], v[112:115]
	v_mfma_f32_16x16x32_bf16 v[116:119], v[148:151], v[210:213], v[116:119]
	v_mfma_f32_16x16x32_bf16 v[116:119], v[144:147], v[206:209], v[116:119]
	v_mfma_f32_16x16x32_bf16 v[120:123], v[92:95], v[206:209], v[120:123]
	v_mfma_f32_16x16x32_bf16 v[120:123], v[100:103], v[210:213], v[120:123]
	v_mfma_f32_16x16x32_bf16 v[124:127], v[84:87], v[210:213], v[124:127]
	v_mfma_f32_16x16x32_bf16 v[124:127], v[80:83], v[206:209], v[124:127]
	s_setprio 0
	s_setprio 1
	v_mfma_f32_16x16x32_bf16 v[108:111], v[80:83], v[214:217], v[108:111]
	v_mfma_f32_16x16x32_bf16 v[108:111], v[84:87], v[218:221], v[108:111]
	v_mfma_f32_16x16x32_bf16 v[104:107], v[100:103], v[218:221], v[104:107]
	v_mfma_f32_16x16x32_bf16 v[104:107], v[92:95], v[214:217], v[104:107]
	v_mfma_f32_16x16x32_bf16 v[96:99], v[144:147], v[214:217], v[96:99]
	v_mfma_f32_16x16x32_bf16 v[96:99], v[148:151], v[218:221], v[96:99]
	v_mfma_f32_16x16x32_bf16 v[88:91], v[156:159], v[218:221], v[88:91]
	v_mfma_f32_16x16x32_bf16 v[88:91], v[152:155], v[214:217], v[88:91]
	v_mfma_f32_16x16x32_bf16 v[64:67], v[152:155], v[222:225], v[64:67]
	v_mfma_f32_16x16x32_bf16 v[64:67], v[156:159], v[226:229], v[64:67]
	v_mfma_f32_16x16x32_bf16 v[68:71], v[148:151], v[226:229], v[68:71]
	v_mfma_f32_16x16x32_bf16 v[68:71], v[144:147], v[222:225], v[68:71]
	v_mfma_f32_16x16x32_bf16 v[72:75], v[92:95], v[222:225], v[72:75]
	v_mfma_f32_16x16x32_bf16 v[72:75], v[100:103], v[226:229], v[72:75]
	s_setprio 2
	s_barrier
; #define PG8_STAGE(bufoff, gbase, voff) do { _Pragma("unroll") for (int _i = 0; _i < 2; ++_i) \
;         __builtin_amdgcn_global_load_lds((const unsigned*)((const char*)(gbase) + (voff)[_i]), (PG8_LAS unsigned*)(lds + (bufoff) + ldsw + _i * 8192), 16, 0, 0); } while (0)
; #define PG8_LDA(dst, b, h) do { _Pragma("unroll") for (int m = 0; m < 4; ++m) _Pragma("unroll") for (int k = 0; k < 2; ++k) dst[m][k] = *(const PG8_LAS bf16x8*)(lds + PG8_SA(b, h) + aoff + m * 2048 + k * 1024); } while (0)
; #define PG8_MMA(ai, bj, At, Bt) do { __builtin_amdgcn_s_setprio(1); _Pragma("unroll") for (int m = 0; m < 4; ++m) _Pragma("unroll") for (int n = 0; n < 2; ++n) _Pragma("unroll") for (int k = 0; k < 2; ++k) \
;         acc[ai][bj][m][n] = __builtin_amdgcn_mfma_f32_16x16x32_bf16(Bt[n][k], At[m][k], acc[ai][bj][m][n], 0, 0, 0); __builtin_amdgcn_s_setprio(0); } while (0)
; #define PG8_WAIT_V(n) asm volatile("s_waitcnt vmcnt(" #n ")" ::: "memory")
; #define PG8_WAIT_L(n) asm volatile("s_waitcnt lgkmcnt(" #n ")" ::: "memory")
; #define PG8_BAR __builtin_amdgcn_s_barrier()
; #define PG8_SCHED __builtin_amdgcn_sched_barrier(0)
; template <class Epi, class Sched, bool ALIGN_EPI = false, bool SP2 = false>
; __device__ __forceinline__ void gemm_phase(PG8_LAS unsigned char* lds, const Gemm g, const Sched& S, const Epi& E) {
;     ...
;             PG8_WAIT_V(8); PG8_WAIT_L(0); PG8_BAR; PG8_MMA(0, 0, At, B0); PG8_MMA(0, 1, At, B1); PG8_BAR; PG8_SCHED;
;             PG8_LDA(At, 1, 1); PG8_STAGE(PG8_SB(1, 0), b3, voffB); PG8_STAGE(PG8_SB(1, 1), b3 + hstep, voffB); PG8_STAGE(PG8_SA(1, 0), a3, voffA);
;             PG8_WAIT_V(8); PG8_WAIT_L(0); PG8_BAR; PG8_MMA(1, 0, At, B0); PG8_MMA(1, 1, At, B1); PG8_BAR; PG8_SCHED;
;     ...
;         if constexpr (ALIGN_EPI) { if (wr == 0) PG8_BAR; }
;         if constexpr (!Epi::AFTER_DRAIN) { E(acc, cur, wr, wc, fr, fq); S.done(cur); }
;         if (!has_next) break;
	v_mfma_f32_16x16x32_bf16 v[76:79], v[84:87], v[226:229], v[76:79]
	v_mfma_f32_16x16x32_bf16 v[76:79], v[80:83], v[222:225], v[76:79]
	s_setprio 0
	s_add_i32 s44, s44, s13
	v_lshl_add_u64 v[200:201], v[200:201], 0, s[16:17]
	s_mov_b32 m0, s44
	ds_read_b128 v[178:181], v187 offset:49152
	ds_read_b128 v[182:185], v187 offset:50176
	ds_read_b128 v[206:209], v187 offset:51200
	ds_read_b128 v[210:213], v187 offset:52224
	ds_read_b128 v[214:217], v187 offset:53248
	ds_read_b128 v[218:221], v187 offset:54272
	ds_read_b128 v[222:225], v187 offset:55296
	ds_read_b128 v[226:229], v187 offset:56320
	global_load_lds_dwordx4 v[200:201], off
	s_add_i32 m0, s44, 0x2000
	s_add_u32 s28, s28, 0x80080
	v_lshl_add_u64 v[200:201], v[230:231], 0, s[16:17]
	s_addc_u32 s29, s29, 0
	s_add_i32 s44, s45, s13
	global_load_lds_dwordx4 v[200:201], off
	v_lshl_add_u64 v[200:201], s[28:29], 0, v[164:165]
	s_mov_b32 m0, s44
	s_nop 0
	global_load_lds_dwordx4 v[200:201], off
	v_lshl_add_u64 v[200:201], s[28:29], 0, v[168:169]
	s_add_i32 m0, s44, 0x2000
	s_nop 0
	global_load_lds_dwordx4 v[200:201], off
	v_lshl_add_u64 v[200:201], v[232:233], 0, s[16:17]
	s_mov_b32 m0, s56
	s_nop 0
	global_load_lds_dwordx4 v[200:201], off
	v_lshl_add_u64 v[200:201], v[234:235], 0, s[16:17]
	s_mov_b32 m0, s57
	s_nop 0
	global_load_lds_dwordx4 v[200:201], off
	s_waitcnt vmcnt(8)
	s_waitcnt lgkmcnt(0)
	s_barrier
	s_setprio 1
	s_waitcnt lgkmcnt(0)
	v_mfma_f32_16x16x32_bf16 v[60:63], v[80:83], v[178:181], v[60:63]
	v_mfma_f32_16x16x32_bf16 v[60:63], v[84:87], v[182:185], v[60:63]
	v_mfma_f32_16x16x32_bf16 v[56:59], v[100:103], v[182:185], v[56:59]
	v_mfma_f32_16x16x32_bf16 v[56:59], v[92:95], v[178:181], v[56:59]
	v_mfma_f32_16x16x32_bf16 v[52:55], v[144:147], v[178:181], v[52:55]
	v_mfma_f32_16x16x32_bf16 v[52:55], v[148:151], v[182:185], v[52:55]
	v_mfma_f32_16x16x32_bf16 v[48:51], v[156:159], v[182:185], v[48:51]
	v_mfma_f32_16x16x32_bf16 v[48:51], v[152:155], v[178:181], v[48:51]
	v_mfma_f32_16x16x32_bf16 v[32:35], v[152:155], v[206:209], v[32:35]
	v_mfma_f32_16x16x32_bf16 v[32:35], v[156:159], v[210:213], v[32:35]
	v_mfma_f32_16x16x32_bf16 v[36:39], v[148:151], v[210:213], v[36:39]
	v_mfma_f32_16x16x32_bf16 v[36:39], v[144:147], v[206:209], v[36:39]
	v_mfma_f32_16x16x32_bf16 v[40:43], v[92:95], v[206:209], v[40:43]
	v_mfma_f32_16x16x32_bf16 v[40:43], v[100:103], v[210:213], v[40:43]
	v_mfma_f32_16x16x32_bf16 v[44:47], v[84:87], v[210:213], v[44:47]
	v_mfma_f32_16x16x32_bf16 v[44:47], v[80:83], v[206:209], v[44:47]
	s_setprio 0
	s_setprio 1
	v_mfma_f32_16x16x32_bf16 v[28:31], v[80:83], v[214:217], v[28:31]
	v_mfma_f32_16x16x32_bf16 v[28:31], v[84:87], v[218:221], v[28:31]
	v_mfma_f32_16x16x32_bf16 v[24:27], v[100:103], v[218:221], v[24:27]
	v_mfma_f32_16x16x32_bf16 v[24:27], v[92:95], v[214:217], v[24:27]
	v_mfma_f32_16x16x32_bf16 v[20:23], v[144:147], v[214:217], v[20:23]
	v_mfma_f32_16x16x32_bf16 v[20:23], v[148:151], v[218:221], v[20:23]
	v_mfma_f32_16x16x32_bf16 v[16:19], v[156:159], v[218:221], v[16:19]
	v_mfma_f32_16x16x32_bf16 v[16:19], v[152:155], v[214:217], v[16:19]
	v_mfma_f32_16x16x32_bf16 v[0:3], v[152:155], v[222:225], v[0:3]
	v_mfma_f32_16x16x32_bf16 v[0:3], v[156:159], v[226:229], v[0:3]
	v_mfma_f32_16x16x32_bf16 v[4:7], v[148:151], v[226:229], v[4:7]
	v_mfma_f32_16x16x32_bf16 v[4:7], v[144:147], v[222:225], v[4:7]
	v_mfma_f32_16x16x32_bf16 v[8:11], v[92:95], v[222:225], v[8:11]
	v_mfma_f32_16x16x32_bf16 v[8:11], v[100:103], v[226:229], v[8:11]
	s_setprio 2
	s_barrier
	v_mfma_f32_16x16x32_bf16 v[12:15], v[84:87], v[226:229], v[12:15]
	v_mfma_f32_16x16x32_bf16 v[12:15], v[80:83], v[222:225], v[12:15]
	s_setprio 0
	s_add_i32 s77, s77, 2
	s_add_u32 s74, s74, 0x100
	s_addc_u32 s75, s75, 0
	s_add_u32 s73, s73, 0x100
	s_addc_u32 s76, s76, 0
	s_cmp_gt_u32 s77, 29
	s_cbranch_scc0 .LBB0_362
	s_and_b64 vcc, exec, s[18:19]
	s_cbranch_vccz .LBB0_365
	s_barrier

; #define PG8_STAGE(bufoff, gbase, voff) do { _Pragma("unroll") for (int _i = 0; _i < 2; ++_i) \
;         __builtin_amdgcn_global_load_lds((const unsigned*)((const char*)(gbase) + (voff)[_i]), (PG8_LAS unsigned*)(lds + (bufoff) + ldsw + _i * 8192), 16, 0, 0); } while (0)
; #define PG8_LDA(dst, b, h) do { _Pragma("unroll") for (int m = 0; m < 4; ++m) _Pragma("unroll") for (int k = 0; k < 2; ++k) dst[m][k] = *(const PG8_LAS bf16x8*)(lds + PG8_SA(b, h) + aoff + m * 2048 + k * 1024); } while (0)
; #define PG8_LDB(dst, b, h) do { _Pragma("unroll") for (int n = 0; n < 2; ++n) _Pragma("unroll") for (int k = 0; k < 2; ++k) dst[n][k] = *(const PG8_LAS bf16x8*)(lds + PG8_SB(b, h) + boff + n * 2048 + k * 1024); } while (0)
; #define PG8_MMA(ai, bj, At, Bt) do { __builtin_amdgcn_s_setprio(1); _Pragma("unroll") for (int m = 0; m < 4; ++m) _Pragma("unroll") for (int n = 0; n < 2; ++n) _Pragma("unroll") for (int k = 0; k < 2; ++k) \
;         acc[ai][bj][m][n] = __builtin_amdgcn_mfma_f32_16x16x32_bf16(Bt[n][k], At[m][k], acc[ai][bj][m][n], 0, 0, 0); __builtin_amdgcn_s_setprio(0); } while (0)
; #define PG8_WAIT_V(n) asm volatile("s_waitcnt vmcnt(" #n ")" ::: "memory")
; #define PG8_BAR __builtin_amdgcn_s_barrier()
; template <class Epi, class Sched, bool ALIGN_EPI = false, bool SP2 = false>
; __device__ __forceinline__ void gemm_phase(PG8_LAS unsigned char* lds, const Gemm g, const Sched& S, const Epi& E) {
;     ...
;         for (int t = 0; t < nt; t += 2) {
;             const bool last = (t == nt - 2);
;             const char* a1 = cA + (size_t)(t + 1) * kstep;
;             const char* a2 = last ? nA : cA + (size_t)(t + 2) * kstep; const char* b2 = last ? nB : cB + (size_t)(t + 2) * kstep;
;             const char* a3 = a2 + kstep; const char* b3 = b2 + kstep;
;             if (last && has_next) S.a_ready(nxt);
;             if constexpr (SP2) {
;             PG8_LDB(B0, 0, 0); PG8_LDB(B1, 0, 1); PG8_SCHED; PG8_LDA(At, 0, 0); PG8_STAGE(PG8_SA(1, 1), a1 + hstep, voffA);
;             PG8_WAIT_V(8); PG8_WAIT_L(0); PG8_BAR; PG8_MMA(0, 0, At, B0); PG8_MMA(0, 1, At, B1); PG8_BAR; PG8_SCHED;
;             PG8_LDA(At, 0, 1); PG8_STAGE(PG8_SB(0, 0), b2, voffB); PG8_STAGE(PG8_SB(0, 1), b2 + hstep, voffB); PG8_STAGE(PG8_SA(0, 0), a2, voffA);
;             PG8_WAIT_V(8); PG8_WAIT_L(0); PG8_BAR; PG8_MMA(1, 0, At, B0); PG8_MMA(1, 1, At, B1); PG8_BAR; PG8_SCHED;
.LBB0_416:
	ds_read_b128 v[136:139], v156
	ds_read_b128 v[140:143], v156 offset:1024
	ds_read_b128 v[172:175], v156 offset:2048
	ds_read_b128 v[176:179], v156 offset:3072
	ds_read_b128 v[180:183], v157
	ds_read_b128 v[184:187], v157 offset:1024
	ds_read_b128 v[206:209], v157 offset:2048
	ds_read_b128 v[210:213], v157 offset:3072
	s_add_u32 s28, s68, 0xfff80080
	s_addc_u32 s29, s69, -1
	s_cmp_eq_u32 s79, 28
	s_cselect_b32 s49, s34, s29
	s_cselect_b32 s48, s35, s28
	s_cselect_b32 s29, s23, s78
	s_cselect_b32 s28, s63, s77
	v_lshl_add_u64 v[200:201], s[68:69], 0, v[128:129]
	s_add_i32 m0, s15, 0xc000
	ds_read_b128 v[214:217], v158
	ds_read_b128 v[218:221], v158 offset:1024
	ds_read_b128 v[222:225], v158 offset:2048
	ds_read_b128 v[226:229], v158 offset:3072
	ds_read_b128 v[230:233], v158 offset:4096
	ds_read_b128 v[234:237], v158 offset:5120
	ds_read_b128 v[238:241], v158 offset:6144
	ds_read_b128 v[242:245], v158 offset:7168
	global_load_lds_dwordx4 v[200:201], off
	v_lshl_add_u64 v[200:201], s[68:69], 0, v[130:131]
	s_add_i32 m0, s15, 0xe000
	s_nop 0
	global_load_lds_dwordx4 v[200:201], off
	s_waitcnt vmcnt(8)
	s_waitcnt lgkmcnt(0)
	s_barrier
	s_setprio 1
	s_waitcnt lgkmcnt(0)
	v_mfma_f32_16x16x32_bf16 v[124:127], v[136:139], v[214:217], v[124:127]
	v_mfma_f32_16x16x32_bf16 v[124:127], v[140:143], v[218:221], v[124:127]
	v_mfma_f32_16x16x32_bf16 v[120:123], v[176:179], v[218:221], v[120:123]
	v_mfma_f32_16x16x32_bf16 v[120:123], v[172:175], v[214:217], v[120:123]
	v_mfma_f32_16x16x32_bf16 v[116:119], v[180:183], v[214:217], v[116:119]
	v_mfma_f32_16x16x32_bf16 v[116:119], v[184:187], v[218:221], v[116:119]
	v_mfma_f32_16x16x32_bf16 v[112:115], v[210:213], v[218:221], v[112:115]
	v_mfma_f32_16x16x32_bf16 v[112:115], v[206:209], v[214:217], v[112:115]
	v_mfma_f32_16x16x32_bf16 v[92:95], v[206:209], v[222:225], v[92:95]
	v_mfma_f32_16x16x32_bf16 v[92:95], v[210:213], v[226:229], v[92:95]
	v_mfma_f32_16x16x32_bf16 v[100:103], v[184:187], v[226:229], v[100:103]
	v_mfma_f32_16x16x32_bf16 v[100:103], v[180:183], v[222:225], v[100:103]
	v_mfma_f32_16x16x32_bf16 v[104:107], v[172:175], v[222:225], v[104:107]
	v_mfma_f32_16x16x32_bf16 v[104:107], v[176:179], v[226:229], v[104:107]
	v_mfma_f32_16x16x32_bf16 v[108:111], v[140:143], v[226:229], v[108:111]
	v_mfma_f32_16x16x32_bf16 v[108:111], v[136:139], v[222:225], v[108:111]
	s_setprio 0
	s_setprio 1
	v_mfma_f32_16x16x32_bf16 v[96:99], v[136:139], v[230:233], v[96:99]
	v_mfma_f32_16x16x32_bf16 v[96:99], v[140:143], v[234:237], v[96:99]
	v_mfma_f32_16x16x32_bf16 v[88:91], v[176:179], v[234:237], v[88:91]
	v_mfma_f32_16x16x32_bf16 v[88:91], v[172:175], v[230:233], v[88:91]
	v_mfma_f32_16x16x32_bf16 v[84:87], v[180:183], v[230:233], v[84:87]
	v_mfma_f32_16x16x32_bf16 v[84:87], v[184:187], v[234:237], v[84:87]
	v_mfma_f32_16x16x32_bf16 v[76:79], v[210:213], v[234:237], v[76:79]
	v_mfma_f32_16x16x32_bf16 v[76:79], v[206:209], v[230:233], v[76:79]
	v_mfma_f32_16x16x32_bf16 v[64:67], v[206:209], v[238:241], v[64:67]
	v_mfma_f32_16x16x32_bf16 v[64:67], v[210:213], v[242:245], v[64:67]
	v_mfma_f32_16x16x32_bf16 v[68:71], v[184:187], v[242:245], v[68:71]
	v_mfma_f32_16x16x32_bf16 v[68:71], v[180:183], v[238:241], v[68:71]
	v_mfma_f32_16x16x32_bf16 v[72:75], v[172:175], v[238:241], v[72:75]
	v_mfma_f32_16x16x32_bf16 v[72:75], v[176:179], v[242:245], v[72:75]
	s_setprio 2
	s_barrier
	v_mfma_f32_16x16x32_bf16 v[80:83], v[140:143], v[242:245], v[80:83]
	v_mfma_f32_16x16x32_bf16 v[80:83], v[136:139], v[238:241], v[80:83]
	s_setprio 0
	s_add_i32 s44, s72, s39
	v_lshl_add_u64 v[200:201], s[28:29], 0, v[166:167]
	s_mov_b32 m0, s44
	ds_read_b128 v[214:217], v158 offset:16384
	ds_read_b128 v[218:221], v158 offset:17408
	ds_read_b128 v[222:225], v158 offset:18432
	ds_read_b128 v[226:229], v158 offset:19456
	ds_read_b128 v[230:233], v158 offset:20480
	ds_read_b128 v[234:237], v158 offset:21504
	ds_read_b128 v[238:241], v158 offset:22528
	ds_read_b128 v[242:245], v158 offset:23552
	global_load_lds_dwordx4 v[200:201], off
	s_add_i32 m0, s44, 0x2000
	s_add_u32 s80, s28, 0x80000
	v_lshl_add_u64 v[246:247], s[28:29], 0, v[170:171]
	s_addc_u32 s81, s29, 0
	s_add_i32 s44, s73, s39
	global_load_lds_dwordx4 v[246:247], off
	v_lshl_add_u64 v[248:249], s[80:81], 0, v[166:167]
	s_mov_b32 m0, s44
	v_lshl_add_u64 v[250:251], s[48:49], 0, v[168:169]
	global_load_lds_dwordx4 v[248:249], off
	v_lshl_add_u64 v[248:249], s[80:81], 0, v[170:171]
	s_add_i32 m0, s44, 0x2000
	s_nop 0
	global_load_lds_dwordx4 v[248:249], off
	v_lshl_add_u64 v[248:249], s[48:49], 0, v[164:165]
	s_mov_b32 m0, s15
	s_nop 0
	global_load_lds_dwordx4 v[248:249], off
	s_mov_b32 m0, s41
	s_nop 0
	global_load_lds_dwordx4 v[250:251], off
	s_waitcnt vmcnt(8)
	s_waitcnt lgkmcnt(0)
	s_barrier
; #define PG8_STAGE(bufoff, gbase, voff) do { _Pragma("unroll") for (int _i = 0; _i < 2; ++_i) \
;         __builtin_amdgcn_global_load_lds((const unsigned*)((const char*)(gbase) + (voff)[_i]), (PG8_LAS unsigned*)(lds + (bufoff) + ldsw + _i * 8192), 16, 0, 0); } while (0)
; #define PG8_LDA(dst, b, h) do { _Pragma("unroll") for (int m = 0; m < 4; ++m) _Pragma("unroll") for (int k = 0; k < 2; ++k) dst[m][k] = *(const PG8_LAS bf16x8*)(lds + PG8_SA(b, h) + aoff + m * 2048 + k * 1024); } while (0)
; #define PG8_LDB(dst, b, h) do { _Pragma("unroll") for (int n = 0; n < 2; ++n) _Pragma("unroll") for (int k = 0; k < 2; ++k) dst[n][k] = *(const PG8_LAS bf16x8*)(lds + PG8_SB(b, h) + boff + n * 2048 + k * 1024); } while (0)
; #define PG8_MMA(ai, bj, At, Bt) do { __builtin_amdgcn_s_setprio(1); _Pragma("unroll") for (int m = 0; m < 4; ++m) _Pragma("unroll") for (int n = 0; n < 2; ++n) _Pragma("unroll") for (int k = 0; k < 2; ++k) \
;         acc[ai][bj][m][n] = __builtin_amdgcn_mfma_f32_16x16x32_bf16(Bt[n][k], At[m][k], acc[ai][bj][m][n], 0, 0, 0); __builtin_amdgcn_s_setprio(0); } while (0)
; #define PG8_WAIT_V(n) asm volatile("s_waitcnt vmcnt(" #n ")" ::: "memory")
; #define PG8_WAIT_L(n) asm volatile("s_waitcnt lgkmcnt(" #n ")" ::: "memory")
; #define PG8_BAR __builtin_amdgcn_s_barrier()
; #define PG8_SCHED __builtin_amdgcn_sched_barrier(0)
; template <class Epi, class Sched, bool ALIGN_EPI = false, bool SP2 = false>
; __device__ __forceinline__ void gemm_phase(PG8_LAS unsigned char* lds, const Gemm g, const Sched& S, const Epi& E) {
;     ...
;             PG8_WAIT_V(8); PG8_WAIT_L(0); PG8_BAR; PG8_MMA(1, 0, At, B0); PG8_MMA(1, 1, At, B1); PG8_BAR; PG8_SCHED;
;             PG8_LDB(B0, 1, 0); PG8_LDB(B1, 1, 1); PG8_SCHED; PG8_LDA(At, 1, 0); PG8_STAGE(PG8_SA(0, 1), a2 + hstep, voffA);
;             PG8_WAIT_V(8); PG8_WAIT_L(0); PG8_BAR; PG8_MMA(0, 0, At, B0); PG8_MMA(0, 1, At, B1); PG8_BAR; PG8_SCHED;
	s_setprio 1
	s_waitcnt lgkmcnt(0)
	v_mfma_f32_16x16x32_bf16 v[60:63], v[136:139], v[214:217], v[60:63]
	v_mfma_f32_16x16x32_bf16 v[60:63], v[140:143], v[218:221], v[60:63]
	v_mfma_f32_16x16x32_bf16 v[56:59], v[176:179], v[218:221], v[56:59]
	v_mfma_f32_16x16x32_bf16 v[56:59], v[172:175], v[214:217], v[56:59]
	v_mfma_f32_16x16x32_bf16 v[52:55], v[180:183], v[214:217], v[52:55]
	v_mfma_f32_16x16x32_bf16 v[52:55], v[184:187], v[218:221], v[52:55]
	v_mfma_f32_16x16x32_bf16 v[44:47], v[210:213], v[218:221], v[44:47]
	v_mfma_f32_16x16x32_bf16 v[44:47], v[206:209], v[214:217], v[44:47]
	v_mfma_f32_16x16x32_bf16 v[28:31], v[206:209], v[222:225], v[28:31]
	v_mfma_f32_16x16x32_bf16 v[28:31], v[210:213], v[226:229], v[28:31]
	v_mfma_f32_16x16x32_bf16 v[36:39], v[184:187], v[226:229], v[36:39]
	v_mfma_f32_16x16x32_bf16 v[36:39], v[180:183], v[222:225], v[36:39]
	v_mfma_f32_16x16x32_bf16 v[40:43], v[172:175], v[222:225], v[40:43]
	v_mfma_f32_16x16x32_bf16 v[40:43], v[176:179], v[226:229], v[40:43]
	v_mfma_f32_16x16x32_bf16 v[48:51], v[140:143], v[226:229], v[48:51]
	v_mfma_f32_16x16x32_bf16 v[48:51], v[136:139], v[222:225], v[48:51]
	s_setprio 0
	s_setprio 1
	v_mfma_f32_16x16x32_bf16 v[32:35], v[136:139], v[230:233], v[32:35]
	v_mfma_f32_16x16x32_bf16 v[32:35], v[140:143], v[234:237], v[32:35]
	v_mfma_f32_16x16x32_bf16 v[24:27], v[176:179], v[234:237], v[24:27]
	v_mfma_f32_16x16x32_bf16 v[24:27], v[172:175], v[230:233], v[24:27]
	v_mfma_f32_16x16x32_bf16 v[20:23], v[180:183], v[230:233], v[20:23]
	v_mfma_f32_16x16x32_bf16 v[20:23], v[184:187], v[234:237], v[20:23]
	v_mfma_f32_16x16x32_bf16 v[16:19], v[210:213], v[234:237], v[16:19]
	v_mfma_f32_16x16x32_bf16 v[16:19], v[206:209], v[230:233], v[16:19]
	v_mfma_f32_16x16x32_bf16 v[0:3], v[206:209], v[238:241], v[0:3]
	v_mfma_f32_16x16x32_bf16 v[0:3], v[210:213], v[242:245], v[0:3]
	v_mfma_f32_16x16x32_bf16 v[4:7], v[184:187], v[242:245], v[4:7]
	v_mfma_f32_16x16x32_bf16 v[4:7], v[180:183], v[238:241], v[4:7]
	v_mfma_f32_16x16x32_bf16 v[8:11], v[172:175], v[238:241], v[8:11]
	v_mfma_f32_16x16x32_bf16 v[8:11], v[176:179], v[242:245], v[8:11]
	s_setprio 2
	s_barrier
	v_mfma_f32_16x16x32_bf16 v[12:15], v[140:143], v[242:245], v[12:15]
	v_mfma_f32_16x16x32_bf16 v[12:15], v[136:139], v[238:241], v[12:15]
	s_setprio 0
	s_add_i32 s44, 0, 0x18000
	v_add_u32_e32 v144, s44, v146
	s_add_i32 s45, 0, 0x1c000
	ds_read_b128 v[136:139], v144
	ds_read_b128 v[140:143], v144 offset:1024
	ds_read_b128 v[172:175], v144 offset:2048
	ds_read_b128 v[176:179], v144 offset:3072
	v_add_u32_e32 v144, s45, v146
	ds_read_b128 v[180:183], v144
	ds_read_b128 v[184:187], v144 offset:1024
	ds_read_b128 v[206:209], v144 offset:2048
	ds_read_b128 v[210:213], v144 offset:3072
	s_add_u32 s48, s48, 0x80000
	s_addc_u32 s49, s49, 0
	s_mov_b32 m0, s56
	v_lshl_add_u64 v[252:253], s[48:49], 0, v[164:165]
	ds_read_b128 v[214:217], v158 offset:32768
	ds_read_b128 v[218:221], v158 offset:33792
	ds_read_b128 v[222:225], v158 offset:34816
	ds_read_b128 v[226:229], v158 offset:35840
	ds_read_b128 v[230:233], v158 offset:36864
	ds_read_b128 v[234:237], v158 offset:37888
	ds_read_b128 v[238:241], v158 offset:38912
	ds_read_b128 v[242:245], v158 offset:39936
	global_load_lds_dwordx4 v[252:253], off
	v_lshl_add_u64 v[252:253], s[48:49], 0, v[168:169]
	s_mov_b32 m0, s57
	s_nop 0
	global_load_lds_dwordx4 v[252:253], off
	s_waitcnt vmcnt(8)
	s_waitcnt lgkmcnt(0)
	s_barrier
	s_setprio 1
	s_waitcnt lgkmcnt(0)
	v_mfma_f32_16x16x32_bf16 v[124:127], v[136:139], v[214:217], v[124:127]
	v_mfma_f32_16x16x32_bf16 v[124:127], v[140:143], v[218:221], v[124:127]
	v_mfma_f32_16x16x32_bf16 v[120:123], v[176:179], v[218:221], v[120:123]
	v_mfma_f32_16x16x32_bf16 v[120:123], v[172:175], v[214:217], v[120:123]
	v_mfma_f32_16x16x32_bf16 v[116:119], v[180:183], v[214:217], v[116:119]
	v_mfma_f32_16x16x32_bf16 v[116:119], v[184:187], v[218:221], v[116:119]
	v_mfma_f32_16x16x32_bf16 v[112:115], v[210:213], v[218:221], v[112:115]
	v_mfma_f32_16x16x32_bf16 v[112:115], v[206:209], v[214:217], v[112:115]
	v_mfma_f32_16x16x32_bf16 v[92:95], v[206:209], v[222:225], v[92:95]
	v_mfma_f32_16x16x32_bf16 v[92:95], v[210:213], v[226:229], v[92:95]
	v_mfma_f32_16x16x32_bf16 v[100:103], v[184:187], v[226:229], v[100:103]
	v_mfma_f32_16x16x32_bf16 v[100:103], v[180:183], v[222:225], v[100:103]
	v_mfma_f32_16x16x32_bf16 v[104:107], v[172:175], v[222:225], v[104:107]
	v_mfma_f32_16x16x32_bf16 v[104:107], v[176:179], v[226:229], v[104:107]
	v_mfma_f32_16x16x32_bf16 v[108:111], v[140:143], v[226:229], v[108:111]
	v_mfma_f32_16x16x32_bf16 v[108:111], v[136:139], v[222:225], v[108:111]
	s_setprio 0
	s_setprio 1
	v_mfma_f32_16x16x32_bf16 v[96:99], v[136:139], v[230:233], v[96:99]
	v_mfma_f32_16x16x32_bf16 v[96:99], v[140:143], v[234:237], v[96:99]
	v_mfma_f32_16x16x32_bf16 v[88:91], v[176:179], v[234:237], v[88:91]
	v_mfma_f32_16x16x32_bf16 v[88:91], v[172:175], v[230:233], v[88:91]
	v_mfma_f32_16x16x32_bf16 v[84:87], v[180:183], v[230:233], v[84:87]
	v_mfma_f32_16x16x32_bf16 v[84:87], v[184:187], v[234:237], v[84:87]
	v_mfma_f32_16x16x32_bf16 v[76:79], v[210:213], v[234:237], v[76:79]
	v_mfma_f32_16x16x32_bf16 v[76:79], v[206:209], v[230:233], v[76:79]
	v_mfma_f32_16x16x32_bf16 v[64:67], v[206:209], v[238:241], v[64:67]
	v_mfma_f32_16x16x32_bf16 v[64:67], v[210:213], v[242:245], v[64:67]
	v_mfma_f32_16x16x32_bf16 v[68:71], v[184:187], v[242:245], v[68:71]
	v_mfma_f32_16x16x32_bf16 v[68:71], v[180:183], v[238:241], v[68:71]
	v_mfma_f32_16x16x32_bf16 v[72:75], v[172:175], v[238:241], v[72:75]
	v_mfma_f32_16x16x32_bf16 v[72:75], v[176:179], v[242:245], v[72:75]
	s_setprio 2
	s_barrier
; #define PG8_STAGE(bufoff, gbase, voff) do { _Pragma("unroll") for (int _i = 0; _i < 2; ++_i) \
;         __builtin_amdgcn_global_load_lds((const unsigned*)((const char*)(gbase) + (voff)[_i]), (PG8_LAS unsigned*)(lds + (bufoff) + ldsw + _i * 8192), 16, 0, 0); } while (0)
; #define PG8_LDA(dst, b, h) do { _Pragma("unroll") for (int m = 0; m < 4; ++m) _Pragma("unroll") for (int k = 0; k < 2; ++k) dst[m][k] = *(const PG8_LAS bf16x8*)(lds + PG8_SA(b, h) + aoff + m * 2048 + k * 1024); } while (0)
; #define PG8_MMA(ai, bj, At, Bt) do { __builtin_amdgcn_s_setprio(1); _Pragma("unroll") for (int m = 0; m < 4; ++m) _Pragma("unroll") for (int n = 0; n < 2; ++n) _Pragma("unroll") for (int k = 0; k < 2; ++k) \
;         acc[ai][bj][m][n] = __builtin_amdgcn_mfma_f32_16x16x32_bf16(Bt[n][k], At[m][k], acc[ai][bj][m][n], 0, 0, 0); __builtin_amdgcn_s_setprio(0); } while (0)
; #define PG8_WAIT_V(n) asm volatile("s_waitcnt vmcnt(" #n ")" ::: "memory")
; #define PG8_WAIT_L(n) asm volatile("s_waitcnt lgkmcnt(" #n ")" ::: "memory")
; #define PG8_BAR __builtin_amdgcn_s_barrier()
; #define PG8_SCHED __builtin_amdgcn_sched_barrier(0)
; template <class Epi, class Sched, bool ALIGN_EPI = false, bool SP2 = false>
; __device__ __forceinline__ void gemm_phase(PG8_LAS unsigned char* lds, const Gemm g, const Sched& S, const Epi& E) {
;     ...
;             PG8_WAIT_V(8); PG8_WAIT_L(0); PG8_BAR; PG8_MMA(0, 0, At, B0); PG8_MMA(0, 1, At, B1); PG8_BAR; PG8_SCHED;
;             PG8_LDA(At, 1, 1); PG8_STAGE(PG8_SB(1, 0), b3, voffB); PG8_STAGE(PG8_SB(1, 1), b3 + hstep, voffB); PG8_STAGE(PG8_SA(1, 0), a3, voffA);
;             PG8_WAIT_V(8); PG8_WAIT_L(0); PG8_BAR; PG8_MMA(1, 0, At, B0); PG8_MMA(1, 1, At, B1); PG8_BAR; PG8_SCHED;
;     ...
;         if constexpr (ALIGN_EPI) { if (wr == 0) PG8_BAR; }
;         if constexpr (!Epi::AFTER_DRAIN) { E(acc, cur, wr, wc, fr, fq); S.done(cur); }
;         if (!has_next) break;
	v_mfma_f32_16x16x32_bf16 v[80:83], v[140:143], v[242:245], v[80:83]
	v_mfma_f32_16x16x32_bf16 v[80:83], v[136:139], v[238:241], v[80:83]
	s_setprio 0
	s_add_i32 s44, s44, s39
	v_lshl_add_u64 v[200:201], v[200:201], 0, s[18:19]
	s_mov_b32 m0, s44
	ds_read_b128 v[214:217], v158 offset:49152
	ds_read_b128 v[218:221], v158 offset:50176
	ds_read_b128 v[222:225], v158 offset:51200
	ds_read_b128 v[226:229], v158 offset:52224
	ds_read_b128 v[230:233], v158 offset:53248
	ds_read_b128 v[234:237], v158 offset:54272
	ds_read_b128 v[238:241], v158 offset:55296
	ds_read_b128 v[242:245], v158 offset:56320
	global_load_lds_dwordx4 v[200:201], off
	s_add_i32 m0, s44, 0x2000
	s_add_u32 s28, s28, 0x80080
	v_lshl_add_u64 v[200:201], v[246:247], 0, s[18:19]
	s_addc_u32 s29, s29, 0
	s_add_i32 s44, s45, s39
	global_load_lds_dwordx4 v[200:201], off
	v_lshl_add_u64 v[200:201], s[28:29], 0, v[166:167]
	s_mov_b32 m0, s44
	s_nop 0
	global_load_lds_dwordx4 v[200:201], off
	v_lshl_add_u64 v[200:201], s[28:29], 0, v[170:171]
	s_add_i32 m0, s44, 0x2000
	s_nop 0
	global_load_lds_dwordx4 v[200:201], off
	v_lshl_add_u64 v[200:201], v[248:249], 0, s[18:19]
	s_mov_b32 m0, s70
	s_nop 0
	global_load_lds_dwordx4 v[200:201], off
	v_lshl_add_u64 v[200:201], v[250:251], 0, s[18:19]
	s_mov_b32 m0, s71
	s_nop 0
	global_load_lds_dwordx4 v[200:201], off
	s_waitcnt vmcnt(8)
	s_waitcnt lgkmcnt(0)
	s_barrier
	s_setprio 1
	s_waitcnt lgkmcnt(0)
	v_mfma_f32_16x16x32_bf16 v[60:63], v[136:139], v[214:217], v[60:63]
	v_mfma_f32_16x16x32_bf16 v[60:63], v[140:143], v[218:221], v[60:63]
	v_mfma_f32_16x16x32_bf16 v[56:59], v[176:179], v[218:221], v[56:59]
	v_mfma_f32_16x16x32_bf16 v[56:59], v[172:175], v[214:217], v[56:59]
	v_mfma_f32_16x16x32_bf16 v[52:55], v[180:183], v[214:217], v[52:55]
	v_mfma_f32_16x16x32_bf16 v[52:55], v[184:187], v[218:221], v[52:55]
	v_mfma_f32_16x16x32_bf16 v[44:47], v[210:213], v[218:221], v[44:47]
	v_mfma_f32_16x16x32_bf16 v[44:47], v[206:209], v[214:217], v[44:47]
	v_mfma_f32_16x16x32_bf16 v[28:31], v[206:209], v[222:225], v[28:31]
	v_mfma_f32_16x16x32_bf16 v[28:31], v[210:213], v[226:229], v[28:31]
	v_mfma_f32_16x16x32_bf16 v[36:39], v[184:187], v[226:229], v[36:39]
	v_mfma_f32_16x16x32_bf16 v[36:39], v[180:183], v[222:225], v[36:39]
	v_mfma_f32_16x16x32_bf16 v[40:43], v[172:175], v[222:225], v[40:43]
	v_mfma_f32_16x16x32_bf16 v[40:43], v[176:179], v[226:229], v[40:43]
	v_mfma_f32_16x16x32_bf16 v[48:51], v[140:143], v[226:229], v[48:51]
	v_mfma_f32_16x16x32_bf16 v[48:51], v[136:139], v[222:225], v[48:51]
	s_setprio 0
	s_setprio 1
	v_mfma_f32_16x16x32_bf16 v[32:35], v[136:139], v[230:233], v[32:35]
	v_mfma_f32_16x16x32_bf16 v[32:35], v[140:143], v[234:237], v[32:35]
	v_mfma_f32_16x16x32_bf16 v[24:27], v[176:179], v[234:237], v[24:27]
	v_mfma_f32_16x16x32_bf16 v[24:27], v[172:175], v[230:233], v[24:27]
	v_mfma_f32_16x16x32_bf16 v[20:23], v[180:183], v[230:233], v[20:23]
	v_mfma_f32_16x16x32_bf16 v[20:23], v[184:187], v[234:237], v[20:23]
	v_mfma_f32_16x16x32_bf16 v[16:19], v[210:213], v[234:237], v[16:19]
	v_mfma_f32_16x16x32_bf16 v[16:19], v[206:209], v[230:233], v[16:19]
	v_mfma_f32_16x16x32_bf16 v[0:3], v[206:209], v[238:241], v[0:3]
	v_mfma_f32_16x16x32_bf16 v[0:3], v[210:213], v[242:245], v[0:3]
	v_mfma_f32_16x16x32_bf16 v[4:7], v[184:187], v[242:245], v[4:7]
	v_mfma_f32_16x16x32_bf16 v[4:7], v[180:183], v[238:241], v[4:7]
	v_mfma_f32_16x16x32_bf16 v[8:11], v[172:175], v[238:241], v[8:11]
	v_mfma_f32_16x16x32_bf16 v[8:11], v[176:179], v[242:245], v[8:11]
	s_setprio 2
	s_barrier
	v_mfma_f32_16x16x32_bf16 v[12:15], v[140:143], v[242:245], v[12:15]
	v_mfma_f32_16x16x32_bf16 v[12:15], v[136:139], v[238:241], v[12:15]
	s_setprio 0
	s_add_i32 s79, s79, 2
	s_add_u32 s68, s68, 0x100
	s_addc_u32 s69, s69, 0
	s_add_u32 s77, s77, 0x100
	s_addc_u32 s78, s78, 0
	s_cmp_gt_u32 s79, 29
	s_cbranch_scc0 .LBB0_416
	s_and_b64 vcc, exec, s[20:21]
	s_cbranch_vccz .LBB0_419
	s_barrier

; #define PG8_STAGE(bufoff, gbase, voff) do { _Pragma("unroll") for (int _i = 0; _i < 2; ++_i) \
;         __builtin_amdgcn_global_load_lds((const unsigned*)((const char*)(gbase) + (voff)[_i]), (PG8_LAS unsigned*)(lds + (bufoff) + ldsw + _i * 8192), 16, 0, 0); } while (0)
; #define PG8_LDA(dst, b, h) do { _Pragma("unroll") for (int m = 0; m < 4; ++m) _Pragma("unroll") for (int k = 0; k < 2; ++k) dst[m][k] = *(const PG8_LAS bf16x8*)(lds + PG8_SA(b, h) + aoff + m * 2048 + k * 1024); } while (0)
; #define PG8_LDB(dst, b, h) do { _Pragma("unroll") for (int n = 0; n < 2; ++n) _Pragma("unroll") for (int k = 0; k < 2; ++k) dst[n][k] = *(const PG8_LAS bf16x8*)(lds + PG8_SB(b, h) + boff + n * 2048 + k * 1024); } while (0)
; #define PG8_MMA(ai, bj, At, Bt) do { __builtin_amdgcn_s_setprio(1); _Pragma("unroll") for (int m = 0; m < 4; ++m) _Pragma("unroll") for (int n = 0; n < 2; ++n) _Pragma("unroll") for (int k = 0; k < 2; ++k) \
;         acc[ai][bj][m][n] = __builtin_amdgcn_mfma_f32_16x16x32_bf16(Bt[n][k], At[m][k], acc[ai][bj][m][n], 0, 0, 0); __builtin_amdgcn_s_setprio(0); } while (0)
; #define PG8_WAIT_V(n) asm volatile("s_waitcnt vmcnt(" #n ")" ::: "memory")
; #define PG8_BAR __builtin_amdgcn_s_barrier()
; template <class Epi, class Sched, bool ALIGN_EPI = false, bool SP2 = false>
; __device__ __forceinline__ void gemm_phase(PG8_LAS unsigned char* lds, const Gemm g, const Sched& S, const Epi& E) {
;     ...
;         for (int t = 0; t < nt; t += 2) {
;             const bool last = (t == nt - 2);
;             const char* a1 = cA + (size_t)(t + 1) * kstep;
;             const char* a2 = last ? nA : cA + (size_t)(t + 2) * kstep; const char* b2 = last ? nB : cB + (size_t)(t + 2) * kstep;
;             const char* a3 = a2 + kstep; const char* b3 = b2 + kstep;
;             if (last && has_next) S.a_ready(nxt);
;             if constexpr (SP2) {
;             PG8_LDB(B0, 0, 0); PG8_LDB(B1, 0, 1); PG8_SCHED; PG8_LDA(At, 0, 0); PG8_STAGE(PG8_SA(1, 1), a1 + hstep, voffA);
;             PG8_WAIT_V(8); PG8_WAIT_L(0); PG8_BAR; PG8_MMA(0, 0, At, B0); PG8_MMA(0, 1, At, B1); PG8_BAR; PG8_SCHED;
;             PG8_LDA(At, 0, 1); PG8_STAGE(PG8_SB(0, 0), b2, voffB); PG8_STAGE(PG8_SB(0, 1), b2 + hstep, voffB); PG8_STAGE(PG8_SA(0, 0), a2, voffA);
;             PG8_WAIT_V(8); PG8_WAIT_L(0); PG8_BAR; PG8_MMA(1, 0, At, B0); PG8_MMA(1, 1, At, B1); PG8_BAR; PG8_SCHED;
.LBB0_482:
	ds_read_b128 v[76:79], v171
	ds_read_b128 v[84:87], v171 offset:1024
	ds_read_b128 v[92:95], v171 offset:2048
	ds_read_b128 v[96:99], v171 offset:3072
	ds_read_b128 v[144:147], v186
	ds_read_b128 v[148:151], v186 offset:1024
	ds_read_b128 v[152:155], v186 offset:2048
	ds_read_b128 v[156:159], v186 offset:3072
	s_add_u32 s28, s64, 0xffea0080
	s_addc_u32 s29, s65, -1
	s_cmpk_eq_i32 s77, 0x54
	s_cselect_b32 s49, s39, s29
	s_cselect_b32 s48, s38, s28
	s_cselect_b32 s29, s63, s35
	s_cselect_b32 s28, s62, s34
	v_lshl_add_u64 v[200:201], s[64:65], 0, v[172:173]
	s_add_i32 m0, s56, 0xc000
	ds_read_b128 v[178:181], v187
	ds_read_b128 v[182:185], v187 offset:1024
	ds_read_b128 v[206:209], v187 offset:2048
	ds_read_b128 v[210:213], v187 offset:3072
	ds_read_b128 v[214:217], v187 offset:4096
	ds_read_b128 v[218:221], v187 offset:5120
	ds_read_b128 v[222:225], v187 offset:6144
	ds_read_b128 v[226:229], v187 offset:7168
	global_load_lds_dwordx4 v[200:201], off
	v_lshl_add_u64 v[200:201], s[64:65], 0, v[174:175]
	s_add_i32 m0, s56, 0xe000
	s_nop 0
	global_load_lds_dwordx4 v[200:201], off
	s_waitcnt vmcnt(8)
	s_waitcnt lgkmcnt(0)
	s_barrier
	s_setprio 1
	s_waitcnt lgkmcnt(0)
	v_mfma_f32_16x16x32_bf16 v[140:143], v[76:79], v[178:181], v[140:143]
	v_mfma_f32_16x16x32_bf16 v[140:143], v[84:87], v[182:185], v[140:143]
	v_mfma_f32_16x16x32_bf16 v[136:139], v[96:99], v[182:185], v[136:139]
	v_mfma_f32_16x16x32_bf16 v[136:139], v[92:95], v[178:181], v[136:139]
	v_mfma_f32_16x16x32_bf16 v[132:135], v[144:147], v[178:181], v[132:135]
	v_mfma_f32_16x16x32_bf16 v[132:135], v[148:151], v[182:185], v[132:135]
	v_mfma_f32_16x16x32_bf16 v[128:131], v[156:159], v[182:185], v[128:131]
	v_mfma_f32_16x16x32_bf16 v[128:131], v[152:155], v[178:181], v[128:131]
	v_mfma_f32_16x16x32_bf16 v[112:115], v[152:155], v[206:209], v[112:115]
	v_mfma_f32_16x16x32_bf16 v[112:115], v[156:159], v[210:213], v[112:115]
	v_mfma_f32_16x16x32_bf16 v[116:119], v[148:151], v[210:213], v[116:119]
	v_mfma_f32_16x16x32_bf16 v[116:119], v[144:147], v[206:209], v[116:119]
	v_mfma_f32_16x16x32_bf16 v[120:123], v[92:95], v[206:209], v[120:123]
	v_mfma_f32_16x16x32_bf16 v[120:123], v[96:99], v[210:213], v[120:123]
	v_mfma_f32_16x16x32_bf16 v[124:127], v[84:87], v[210:213], v[124:127]
	v_mfma_f32_16x16x32_bf16 v[124:127], v[76:79], v[206:209], v[124:127]
	s_setprio 0
	s_setprio 1
	v_mfma_f32_16x16x32_bf16 v[108:111], v[76:79], v[214:217], v[108:111]
	v_mfma_f32_16x16x32_bf16 v[108:111], v[84:87], v[218:221], v[108:111]
	v_mfma_f32_16x16x32_bf16 v[104:107], v[96:99], v[218:221], v[104:107]
	v_mfma_f32_16x16x32_bf16 v[104:107], v[92:95], v[214:217], v[104:107]
	v_mfma_f32_16x16x32_bf16 v[100:103], v[144:147], v[214:217], v[100:103]
	v_mfma_f32_16x16x32_bf16 v[100:103], v[148:151], v[218:221], v[100:103]
	v_mfma_f32_16x16x32_bf16 v[88:91], v[156:159], v[218:221], v[88:91]
	v_mfma_f32_16x16x32_bf16 v[88:91], v[152:155], v[214:217], v[88:91]
	v_mfma_f32_16x16x32_bf16 v[64:67], v[152:155], v[222:225], v[64:67]
	v_mfma_f32_16x16x32_bf16 v[64:67], v[156:159], v[226:229], v[64:67]
	v_mfma_f32_16x16x32_bf16 v[68:71], v[148:151], v[226:229], v[68:71]
	v_mfma_f32_16x16x32_bf16 v[68:71], v[144:147], v[222:225], v[68:71]
	v_mfma_f32_16x16x32_bf16 v[72:75], v[92:95], v[222:225], v[72:75]
	v_mfma_f32_16x16x32_bf16 v[72:75], v[96:99], v[226:229], v[72:75]
	s_setprio 2
	s_barrier
	v_mfma_f32_16x16x32_bf16 v[80:83], v[84:87], v[226:229], v[80:83]
	v_mfma_f32_16x16x32_bf16 v[80:83], v[76:79], v[222:225], v[80:83]
	s_setprio 0
	s_add_i32 s44, s70, s41
	v_lshl_add_u64 v[200:201], s[28:29], 0, v[160:161]
	s_mov_b32 m0, s44
	ds_read_b128 v[178:181], v187 offset:16384
	ds_read_b128 v[182:185], v187 offset:17408
	ds_read_b128 v[206:209], v187 offset:18432
	ds_read_b128 v[210:213], v187 offset:19456
	ds_read_b128 v[214:217], v187 offset:20480
	ds_read_b128 v[218:221], v187 offset:21504
	ds_read_b128 v[222:225], v187 offset:22528
	ds_read_b128 v[226:229], v187 offset:23552
	global_load_lds_dwordx4 v[200:201], off
	s_add_i32 m0, s44, 0x2000
	s_add_u32 s78, s28, 0x160000
	v_lshl_add_u64 v[230:231], s[28:29], 0, v[162:163]
	s_addc_u32 s79, s29, 0
	s_add_i32 s44, s71, s41
	global_load_lds_dwordx4 v[230:231], off
	v_lshl_add_u64 v[232:233], s[78:79], 0, v[160:161]
	s_mov_b32 m0, s44
	v_lshl_add_u64 v[234:235], s[48:49], 0, v[162:163]
	global_load_lds_dwordx4 v[232:233], off
	v_lshl_add_u64 v[232:233], s[78:79], 0, v[162:163]
	s_add_i32 m0, s44, 0x2000
	s_nop 0
	global_load_lds_dwordx4 v[232:233], off
	v_lshl_add_u64 v[232:233], s[48:49], 0, v[160:161]
	s_mov_b32 m0, s56
	s_nop 0
	global_load_lds_dwordx4 v[232:233], off
	s_mov_b32 m0, s57
	s_nop 0
	global_load_lds_dwordx4 v[234:235], off
	s_waitcnt vmcnt(8)
	s_waitcnt lgkmcnt(0)
	s_barrier
; #define PG8_STAGE(bufoff, gbase, voff) do { _Pragma("unroll") for (int _i = 0; _i < 2; ++_i) \
;         __builtin_amdgcn_global_load_lds((const unsigned*)((const char*)(gbase) + (voff)[_i]), (PG8_LAS unsigned*)(lds + (bufoff) + ldsw + _i * 8192), 16, 0, 0); } while (0)
; #define PG8_LDA(dst, b, h) do { _Pragma("unroll") for (int m = 0; m < 4; ++m) _Pragma("unroll") for (int k = 0; k < 2; ++k) dst[m][k] = *(const PG8_LAS bf16x8*)(lds + PG8_SA(b, h) + aoff + m * 2048 + k * 1024); } while (0)
; #define PG8_LDB(dst, b, h) do { _Pragma("unroll") for (int n = 0; n < 2; ++n) _Pragma("unroll") for (int k = 0; k < 2; ++k) dst[n][k] = *(const PG8_LAS bf16x8*)(lds + PG8_SB(b, h) + boff + n * 2048 + k * 1024); } while (0)
; #define PG8_MMA(ai, bj, At, Bt) do { __builtin_amdgcn_s_setprio(1); _Pragma("unroll") for (int m = 0; m < 4; ++m) _Pragma("unroll") for (int n = 0; n < 2; ++n) _Pragma("unroll") for (int k = 0; k < 2; ++k) \
;         acc[ai][bj][m][n] = __builtin_amdgcn_mfma_f32_16x16x32_bf16(Bt[n][k], At[m][k], acc[ai][bj][m][n], 0, 0, 0); __builtin_amdgcn_s_setprio(0); } while (0)
; #define PG8_WAIT_V(n) asm volatile("s_waitcnt vmcnt(" #n ")" ::: "memory")
; #define PG8_WAIT_L(n) asm volatile("s_waitcnt lgkmcnt(" #n ")" ::: "memory")
; #define PG8_BAR __builtin_amdgcn_s_barrier()
; #define PG8_SCHED __builtin_amdgcn_sched_barrier(0)
; template <class Epi, class Sched, bool ALIGN_EPI = false, bool SP2 = false>
; __device__ __forceinline__ void gemm_phase(PG8_LAS unsigned char* lds, const Gemm g, const Sched& S, const Epi& E) {
;     ...
;             PG8_WAIT_V(8); PG8_WAIT_L(0); PG8_BAR; PG8_MMA(1, 0, At, B0); PG8_MMA(1, 1, At, B1); PG8_BAR; PG8_SCHED;
;             PG8_LDB(B0, 1, 0); PG8_LDB(B1, 1, 1); PG8_SCHED; PG8_LDA(At, 1, 0); PG8_STAGE(PG8_SA(0, 1), a2 + hstep, voffA);
;             PG8_WAIT_V(8); PG8_WAIT_L(0); PG8_BAR; PG8_MMA(0, 0, At, B0); PG8_MMA(0, 1, At, B1); PG8_BAR; PG8_SCHED;
	s_setprio 1
	s_waitcnt lgkmcnt(0)
	v_mfma_f32_16x16x32_bf16 v[60:63], v[76:79], v[178:181], v[60:63]
	v_mfma_f32_16x16x32_bf16 v[60:63], v[84:87], v[182:185], v[60:63]
	v_mfma_f32_16x16x32_bf16 v[56:59], v[96:99], v[182:185], v[56:59]
	v_mfma_f32_16x16x32_bf16 v[56:59], v[92:95], v[178:181], v[56:59]
	v_mfma_f32_16x16x32_bf16 v[52:55], v[144:147], v[178:181], v[52:55]
	v_mfma_f32_16x16x32_bf16 v[52:55], v[148:151], v[182:185], v[52:55]
	v_mfma_f32_16x16x32_bf16 v[48:51], v[156:159], v[182:185], v[48:51]
	v_mfma_f32_16x16x32_bf16 v[48:51], v[152:155], v[178:181], v[48:51]
	v_mfma_f32_16x16x32_bf16 v[32:35], v[152:155], v[206:209], v[32:35]
	v_mfma_f32_16x16x32_bf16 v[32:35], v[156:159], v[210:213], v[32:35]
	v_mfma_f32_16x16x32_bf16 v[36:39], v[148:151], v[210:213], v[36:39]
	v_mfma_f32_16x16x32_bf16 v[36:39], v[144:147], v[206:209], v[36:39]
	v_mfma_f32_16x16x32_bf16 v[40:43], v[92:95], v[206:209], v[40:43]
	v_mfma_f32_16x16x32_bf16 v[40:43], v[96:99], v[210:213], v[40:43]
	v_mfma_f32_16x16x32_bf16 v[44:47], v[84:87], v[210:213], v[44:47]
	v_mfma_f32_16x16x32_bf16 v[44:47], v[76:79], v[206:209], v[44:47]
	s_setprio 0
	s_setprio 1
	v_mfma_f32_16x16x32_bf16 v[28:31], v[76:79], v[214:217], v[28:31]
	v_mfma_f32_16x16x32_bf16 v[28:31], v[84:87], v[218:221], v[28:31]
	v_mfma_f32_16x16x32_bf16 v[24:27], v[96:99], v[218:221], v[24:27]
	v_mfma_f32_16x16x32_bf16 v[24:27], v[92:95], v[214:217], v[24:27]
	v_mfma_f32_16x16x32_bf16 v[20:23], v[144:147], v[214:217], v[20:23]
	v_mfma_f32_16x16x32_bf16 v[20:23], v[148:151], v[218:221], v[20:23]
	v_mfma_f32_16x16x32_bf16 v[16:19], v[156:159], v[218:221], v[16:19]
	v_mfma_f32_16x16x32_bf16 v[16:19], v[152:155], v[214:217], v[16:19]
	v_mfma_f32_16x16x32_bf16 v[0:3], v[152:155], v[222:225], v[0:3]
	v_mfma_f32_16x16x32_bf16 v[0:3], v[156:159], v[226:229], v[0:3]
	v_mfma_f32_16x16x32_bf16 v[4:7], v[148:151], v[226:229], v[4:7]
	v_mfma_f32_16x16x32_bf16 v[4:7], v[144:147], v[222:225], v[4:7]
	v_mfma_f32_16x16x32_bf16 v[8:11], v[92:95], v[222:225], v[8:11]
	v_mfma_f32_16x16x32_bf16 v[8:11], v[96:99], v[226:229], v[8:11]
	s_setprio 2
	s_barrier
	v_mfma_f32_16x16x32_bf16 v[12:15], v[84:87], v[226:229], v[12:15]
	v_mfma_f32_16x16x32_bf16 v[12:15], v[76:79], v[222:225], v[12:15]
	s_setprio 0
	s_add_i32 s44, 0, 0x18000
	s_add_i32 s45, 0, 0x1c000
	v_add_u32_e32 v96, s44, v167
	v_add_u32_e32 v156, s45, v167
	ds_read_b128 v[76:79], v96
	ds_read_b128 v[84:87], v96 offset:1024
	ds_read_b128 v[92:95], v96 offset:2048
	ds_read_b128 v[96:99], v96 offset:3072
	ds_read_b128 v[144:147], v156
	ds_read_b128 v[148:151], v156 offset:1024
	ds_read_b128 v[152:155], v156 offset:2048
	ds_read_b128 v[156:159], v156 offset:3072
	s_add_u32 s48, s48, 0x160000
	s_addc_u32 s49, s49, 0
	s_mov_b32 m0, s61
	v_lshl_add_u64 v[236:237], s[48:49], 0, v[160:161]
	ds_read_b128 v[178:181], v187 offset:32768
	ds_read_b128 v[182:185], v187 offset:33792
	ds_read_b128 v[206:209], v187 offset:34816
	ds_read_b128 v[210:213], v187 offset:35840
	ds_read_b128 v[214:217], v187 offset:36864
	ds_read_b128 v[218:221], v187 offset:37888
	ds_read_b128 v[222:225], v187 offset:38912
	ds_read_b128 v[226:229], v187 offset:39936
	global_load_lds_dwordx4 v[236:237], off
	v_lshl_add_u64 v[236:237], s[48:49], 0, v[162:163]
	s_mov_b32 m0, s66
	s_nop 0
	global_load_lds_dwordx4 v[236:237], off
	s_waitcnt vmcnt(8)
	s_waitcnt lgkmcnt(0)
	s_barrier
	s_setprio 1
	s_waitcnt lgkmcnt(0)
	v_mfma_f32_16x16x32_bf16 v[140:143], v[76:79], v[178:181], v[140:143]
	v_mfma_f32_16x16x32_bf16 v[140:143], v[84:87], v[182:185], v[140:143]
	v_mfma_f32_16x16x32_bf16 v[136:139], v[96:99], v[182:185], v[136:139]
	v_mfma_f32_16x16x32_bf16 v[136:139], v[92:95], v[178:181], v[136:139]
	v_mfma_f32_16x16x32_bf16 v[132:135], v[144:147], v[178:181], v[132:135]
	v_mfma_f32_16x16x32_bf16 v[132:135], v[148:151], v[182:185], v[132:135]
	v_mfma_f32_16x16x32_bf16 v[128:131], v[156:159], v[182:185], v[128:131]
	v_mfma_f32_16x16x32_bf16 v[128:131], v[152:155], v[178:181], v[128:131]
	v_mfma_f32_16x16x32_bf16 v[112:115], v[152:155], v[206:209], v[112:115]
	v_mfma_f32_16x16x32_bf16 v[112:115], v[156:159], v[210:213], v[112:115]
	v_mfma_f32_16x16x32_bf16 v[116:119], v[148:151], v[210:213], v[116:119]
	v_mfma_f32_16x16x32_bf16 v[116:119], v[144:147], v[206:209], v[116:119]
	v_mfma_f32_16x16x32_bf16 v[120:123], v[92:95], v[206:209], v[120:123]
	v_mfma_f32_16x16x32_bf16 v[120:123], v[96:99], v[210:213], v[120:123]
	v_mfma_f32_16x16x32_bf16 v[124:127], v[84:87], v[210:213], v[124:127]
	v_mfma_f32_16x16x32_bf16 v[124:127], v[76:79], v[206:209], v[124:127]
	s_setprio 0
	s_setprio 1
	v_mfma_f32_16x16x32_bf16 v[108:111], v[76:79], v[214:217], v[108:111]
	v_mfma_f32_16x16x32_bf16 v[108:111], v[84:87], v[218:221], v[108:111]
	v_mfma_f32_16x16x32_bf16 v[104:107], v[96:99], v[218:221], v[104:107]
	v_mfma_f32_16x16x32_bf16 v[104:107], v[92:95], v[214:217], v[104:107]
	v_mfma_f32_16x16x32_bf16 v[100:103], v[144:147], v[214:217], v[100:103]
	v_mfma_f32_16x16x32_bf16 v[100:103], v[148:151], v[218:221], v[100:103]
	v_mfma_f32_16x16x32_bf16 v[88:91], v[156:159], v[218:221], v[88:91]
	v_mfma_f32_16x16x32_bf16 v[88:91], v[152:155], v[214:217], v[88:91]
	v_mfma_f32_16x16x32_bf16 v[64:67], v[152:155], v[222:225], v[64:67]
	v_mfma_f32_16x16x32_bf16 v[64:67], v[156:159], v[226:229], v[64:67]
	v_mfma_f32_16x16x32_bf16 v[68:71], v[148:151], v[226:229], v[68:71]
	v_mfma_f32_16x16x32_bf16 v[68:71], v[144:147], v[222:225], v[68:71]
	v_mfma_f32_16x16x32_bf16 v[72:75], v[92:95], v[222:225], v[72:75]
	v_mfma_f32_16x16x32_bf16 v[72:75], v[96:99], v[226:229], v[72:75]
	s_setprio 2
	s_barrier
; #define PG8_STAGE(bufoff, gbase, voff) do { _Pragma("unroll") for (int _i = 0; _i < 2; ++_i) \
;         __builtin_amdgcn_global_load_lds((const unsigned*)((const char*)(gbase) + (voff)[_i]), (PG8_LAS unsigned*)(lds + (bufoff) + ldsw + _i * 8192), 16, 0, 0); } while (0)
; #define PG8_LDA(dst, b, h) do { _Pragma("unroll") for (int m = 0; m < 4; ++m) _Pragma("unroll") for (int k = 0; k < 2; ++k) dst[m][k] = *(const PG8_LAS bf16x8*)(lds + PG8_SA(b, h) + aoff + m * 2048 + k * 1024); } while (0)
; #define PG8_MMA(ai, bj, At, Bt) do { __builtin_amdgcn_s_setprio(1); _Pragma("unroll") for (int m = 0; m < 4; ++m) _Pragma("unroll") for (int n = 0; n < 2; ++n) _Pragma("unroll") for (int k = 0; k < 2; ++k) \
;         acc[ai][bj][m][n] = __builtin_amdgcn_mfma_f32_16x16x32_bf16(Bt[n][k], At[m][k], acc[ai][bj][m][n], 0, 0, 0); __builtin_amdgcn_s_setprio(0); } while (0)
; #define PG8_WAIT_V(n) asm volatile("s_waitcnt vmcnt(" #n ")" ::: "memory")
; #define PG8_WAIT_L(n) asm volatile("s_waitcnt lgkmcnt(" #n ")" ::: "memory")
; #define PG8_BAR __builtin_amdgcn_s_barrier()
; #define PG8_SCHED __builtin_amdgcn_sched_barrier(0)
; template <class Epi, class Sched, bool ALIGN_EPI = false, bool SP2 = false>
; __device__ __forceinline__ void gemm_phase(PG8_LAS unsigned char* lds, const Gemm g, const Sched& S, const Epi& E) {
;     ...
;             PG8_WAIT_V(8); PG8_WAIT_L(0); PG8_BAR; PG8_MMA(0, 0, At, B0); PG8_MMA(0, 1, At, B1); PG8_BAR; PG8_SCHED;
;             PG8_LDA(At, 1, 1); PG8_STAGE(PG8_SB(1, 0), b3, voffB); PG8_STAGE(PG8_SB(1, 1), b3 + hstep, voffB); PG8_STAGE(PG8_SA(1, 0), a3, voffA);
;             PG8_WAIT_V(8); PG8_WAIT_L(0); PG8_BAR; PG8_MMA(1, 0, At, B0); PG8_MMA(1, 1, At, B1); PG8_BAR; PG8_SCHED;
;     ...
;         if constexpr (ALIGN_EPI) { if (wr == 0) PG8_BAR; }
;         if constexpr (!Epi::AFTER_DRAIN) { E(acc, cur, wr, wc, fr, fq); S.done(cur); }
;         if (!has_next) break;
	v_mfma_f32_16x16x32_bf16 v[80:83], v[84:87], v[226:229], v[80:83]
	v_mfma_f32_16x16x32_bf16 v[80:83], v[76:79], v[222:225], v[80:83]
	s_setprio 0
	s_add_i32 s44, s44, s41
	v_lshl_add_u64 v[200:201], v[200:201], 0, s[20:21]
	s_mov_b32 m0, s44
	ds_read_b128 v[178:181], v187 offset:49152
	ds_read_b128 v[182:185], v187 offset:50176
	ds_read_b128 v[206:209], v187 offset:51200
	ds_read_b128 v[210:213], v187 offset:52224
	ds_read_b128 v[214:217], v187 offset:53248
	ds_read_b128 v[218:221], v187 offset:54272
	ds_read_b128 v[222:225], v187 offset:55296
	ds_read_b128 v[226:229], v187 offset:56320
	global_load_lds_dwordx4 v[200:201], off
	s_add_i32 m0, s44, 0x2000
	s_add_u32 s28, s28, 0x160080
	v_lshl_add_u64 v[200:201], v[230:231], 0, s[20:21]
	s_addc_u32 s29, s29, 0
	s_add_i32 s44, s45, s41
	global_load_lds_dwordx4 v[200:201], off
	v_lshl_add_u64 v[200:201], s[28:29], 0, v[160:161]
	s_mov_b32 m0, s44
	s_nop 0
	global_load_lds_dwordx4 v[200:201], off
	v_lshl_add_u64 v[200:201], s[28:29], 0, v[162:163]
	s_add_i32 m0, s44, 0x2000
	s_nop 0
	global_load_lds_dwordx4 v[200:201], off
	v_lshl_add_u64 v[200:201], v[232:233], 0, s[20:21]
	s_mov_b32 m0, s67
	s_nop 0
	global_load_lds_dwordx4 v[200:201], off
	v_lshl_add_u64 v[200:201], v[234:235], 0, s[20:21]
	s_mov_b32 m0, s68
	s_nop 0
	global_load_lds_dwordx4 v[200:201], off
	s_waitcnt vmcnt(8)
	s_waitcnt lgkmcnt(0)
	s_barrier
	s_setprio 1
	s_waitcnt lgkmcnt(0)
	v_mfma_f32_16x16x32_bf16 v[60:63], v[76:79], v[178:181], v[60:63]
	v_mfma_f32_16x16x32_bf16 v[60:63], v[84:87], v[182:185], v[60:63]
	v_mfma_f32_16x16x32_bf16 v[56:59], v[96:99], v[182:185], v[56:59]
	v_mfma_f32_16x16x32_bf16 v[56:59], v[92:95], v[178:181], v[56:59]
	v_mfma_f32_16x16x32_bf16 v[52:55], v[144:147], v[178:181], v[52:55]
	v_mfma_f32_16x16x32_bf16 v[52:55], v[148:151], v[182:185], v[52:55]
	v_mfma_f32_16x16x32_bf16 v[48:51], v[156:159], v[182:185], v[48:51]
	v_mfma_f32_16x16x32_bf16 v[48:51], v[152:155], v[178:181], v[48:51]
	v_mfma_f32_16x16x32_bf16 v[32:35], v[152:155], v[206:209], v[32:35]
	v_mfma_f32_16x16x32_bf16 v[32:35], v[156:159], v[210:213], v[32:35]
	v_mfma_f32_16x16x32_bf16 v[36:39], v[148:151], v[210:213], v[36:39]
	v_mfma_f32_16x16x32_bf16 v[36:39], v[144:147], v[206:209], v[36:39]
	v_mfma_f32_16x16x32_bf16 v[40:43], v[92:95], v[206:209], v[40:43]
	v_mfma_f32_16x16x32_bf16 v[40:43], v[96:99], v[210:213], v[40:43]
	v_mfma_f32_16x16x32_bf16 v[44:47], v[84:87], v[210:213], v[44:47]
	v_mfma_f32_16x16x32_bf16 v[44:47], v[76:79], v[206:209], v[44:47]
	s_setprio 0
	s_setprio 1
	v_mfma_f32_16x16x32_bf16 v[28:31], v[76:79], v[214:217], v[28:31]
	v_mfma_f32_16x16x32_bf16 v[28:31], v[84:87], v[218:221], v[28:31]
	v_mfma_f32_16x16x32_bf16 v[24:27], v[96:99], v[218:221], v[24:27]
	v_mfma_f32_16x16x32_bf16 v[24:27], v[92:95], v[214:217], v[24:27]
	v_mfma_f32_16x16x32_bf16 v[20:23], v[144:147], v[214:217], v[20:23]
	v_mfma_f32_16x16x32_bf16 v[20:23], v[148:151], v[218:221], v[20:23]
	v_mfma_f32_16x16x32_bf16 v[16:19], v[156:159], v[218:221], v[16:19]
	v_mfma_f32_16x16x32_bf16 v[16:19], v[152:155], v[214:217], v[16:19]
	v_mfma_f32_16x16x32_bf16 v[0:3], v[152:155], v[222:225], v[0:3]
	v_mfma_f32_16x16x32_bf16 v[0:3], v[156:159], v[226:229], v[0:3]
	v_mfma_f32_16x16x32_bf16 v[4:7], v[148:151], v[226:229], v[4:7]
	v_mfma_f32_16x16x32_bf16 v[4:7], v[144:147], v[222:225], v[4:7]
	v_mfma_f32_16x16x32_bf16 v[8:11], v[92:95], v[222:225], v[8:11]
	v_mfma_f32_16x16x32_bf16 v[8:11], v[96:99], v[226:229], v[8:11]
	s_setprio 2
	s_barrier
	v_mfma_f32_16x16x32_bf16 v[12:15], v[84:87], v[226:229], v[12:15]
	v_mfma_f32_16x16x32_bf16 v[12:15], v[76:79], v[222:225], v[12:15]
	s_setprio 0
	s_add_i32 s77, s77, 2
	s_add_u32 s64, s64, 0x100
	s_addc_u32 s65, s65, 0
	s_add_u32 s34, s34, 0x100
	s_addc_u32 s35, s35, 0
	s_cmpk_gt_u32 s77, 0x55
	s_cbranch_scc0 .LBB0_482
	s_and_b64 vcc, exec, s[22:23]
	s_cbranch_vccz .LBB0_485
	s_barrier

; #define PG8_STAGE(bufoff, gbase, voff) do { _Pragma("unroll") for (int _i = 0; _i < 2; ++_i) \
;         __builtin_amdgcn_global_load_lds((const unsigned*)((const char*)(gbase) + (voff)[_i]), (PG8_LAS unsigned*)(lds + (bufoff) + ldsw + _i * 8192), 16, 0, 0); } while (0)
; #define PG8_LDA(dst, b, h) do { _Pragma("unroll") for (int m = 0; m < 4; ++m) _Pragma("unroll") for (int k = 0; k < 2; ++k) dst[m][k] = *(const PG8_LAS bf16x8*)(lds + PG8_SA(b, h) + aoff + m * 2048 + k * 1024); } while (0)
; #define PG8_LDB(dst, b, h) do { _Pragma("unroll") for (int n = 0; n < 2; ++n) _Pragma("unroll") for (int k = 0; k < 2; ++k) dst[n][k] = *(const PG8_LAS bf16x8*)(lds + PG8_SB(b, h) + boff + n * 2048 + k * 1024); } while (0)
; #define PG8_MMA(ai, bj, At, Bt) do { __builtin_amdgcn_s_setprio(1); _Pragma("unroll") for (int m = 0; m < 4; ++m) _Pragma("unroll") for (int n = 0; n < 2; ++n) _Pragma("unroll") for (int k = 0; k < 2; ++k) \
;         acc[ai][bj][m][n] = __builtin_amdgcn_mfma_f32_16x16x32_bf16(Bt[n][k], At[m][k], acc[ai][bj][m][n], 0, 0, 0); __builtin_amdgcn_s_setprio(0); } while (0)
; #define PG8_WAIT_V(n) asm volatile("s_waitcnt vmcnt(" #n ")" ::: "memory")
; #define PG8_BAR __builtin_amdgcn_s_barrier()
; template <class Epi, class Sched, bool ALIGN_EPI = false, bool SP2 = false>
; __device__ __forceinline__ void gemm_phase(PG8_LAS unsigned char* lds, const Gemm g, const Sched& S, const Epi& E) {
;     ...
;         for (int t = 0; t < nt; t += 2) {
;             const bool last = (t == nt - 2);
;             const char* a1 = cA + (size_t)(t + 1) * kstep;
;             const char* a2 = last ? nA : cA + (size_t)(t + 2) * kstep; const char* b2 = last ? nB : cB + (size_t)(t + 2) * kstep;
;             const char* a3 = a2 + kstep; const char* b3 = b2 + kstep;
;             if (last && has_next) S.a_ready(nxt);
;             if constexpr (SP2) {
;             PG8_LDB(B0, 0, 0); PG8_LDB(B1, 0, 1); PG8_SCHED; PG8_LDA(At, 0, 0); PG8_STAGE(PG8_SA(1, 1), a1 + hstep, voffA);
;             PG8_WAIT_V(8); PG8_WAIT_L(0); PG8_BAR; PG8_MMA(0, 0, At, B0); PG8_MMA(0, 1, At, B1); PG8_BAR; PG8_SCHED;
;             PG8_LDA(At, 0, 1); PG8_STAGE(PG8_SB(0, 0), b2, voffB); PG8_STAGE(PG8_SB(0, 1), b2 + hstep, voffB); PG8_STAGE(PG8_SA(0, 0), a2, voffA);
;             PG8_WAIT_V(8); PG8_WAIT_L(0); PG8_BAR; PG8_MMA(1, 0, At, B0); PG8_MMA(1, 1, At, B1); PG8_BAR; PG8_SCHED;
.LBB0_536:
	ds_read_b128 v[136:139], v156
	ds_read_b128 v[140:143], v156 offset:1024
	ds_read_b128 v[172:175], v156 offset:2048
	ds_read_b128 v[176:179], v156 offset:3072
	ds_read_b128 v[180:183], v157
	ds_read_b128 v[184:187], v157 offset:1024
	ds_read_b128 v[206:209], v157 offset:2048
	ds_read_b128 v[210:213], v157 offset:3072
	s_add_u32 s28, s66, 0xfff80080
	s_addc_u32 s29, s67, -1
	s_cmp_eq_u32 s79, 28
	s_cselect_b32 s49, s34, s29
	s_cselect_b32 s48, s35, s28
	s_cselect_b32 s29, s23, s78
	s_cselect_b32 s28, s39, s77
	v_lshl_add_u64 v[200:201], s[66:67], 0, v[128:129]
	s_add_i32 m0, s11, 0xc000
	ds_read_b128 v[214:217], v158
	ds_read_b128 v[218:221], v158 offset:1024
	ds_read_b128 v[222:225], v158 offset:2048
	ds_read_b128 v[226:229], v158 offset:3072
	ds_read_b128 v[230:233], v158 offset:4096
	ds_read_b128 v[234:237], v158 offset:5120
	ds_read_b128 v[238:241], v158 offset:6144
	ds_read_b128 v[242:245], v158 offset:7168
	global_load_lds_dwordx4 v[200:201], off
	v_lshl_add_u64 v[200:201], s[66:67], 0, v[130:131]
	s_add_i32 m0, s11, 0xe000
	s_nop 0
	global_load_lds_dwordx4 v[200:201], off
	s_waitcnt vmcnt(8)
	s_waitcnt lgkmcnt(0)
	s_barrier
	s_setprio 1
	s_waitcnt lgkmcnt(0)
	v_mfma_f32_16x16x32_bf16 v[124:127], v[136:139], v[214:217], v[124:127]
	v_mfma_f32_16x16x32_bf16 v[124:127], v[140:143], v[218:221], v[124:127]
	v_mfma_f32_16x16x32_bf16 v[120:123], v[176:179], v[218:221], v[120:123]
	v_mfma_f32_16x16x32_bf16 v[120:123], v[172:175], v[214:217], v[120:123]
	v_mfma_f32_16x16x32_bf16 v[116:119], v[180:183], v[214:217], v[116:119]
	v_mfma_f32_16x16x32_bf16 v[116:119], v[184:187], v[218:221], v[116:119]
	v_mfma_f32_16x16x32_bf16 v[112:115], v[210:213], v[218:221], v[112:115]
	v_mfma_f32_16x16x32_bf16 v[112:115], v[206:209], v[214:217], v[112:115]
	v_mfma_f32_16x16x32_bf16 v[92:95], v[206:209], v[222:225], v[92:95]
	v_mfma_f32_16x16x32_bf16 v[92:95], v[210:213], v[226:229], v[92:95]
	v_mfma_f32_16x16x32_bf16 v[100:103], v[184:187], v[226:229], v[100:103]
	v_mfma_f32_16x16x32_bf16 v[100:103], v[180:183], v[222:225], v[100:103]
	v_mfma_f32_16x16x32_bf16 v[104:107], v[172:175], v[222:225], v[104:107]
	v_mfma_f32_16x16x32_bf16 v[104:107], v[176:179], v[226:229], v[104:107]
	v_mfma_f32_16x16x32_bf16 v[108:111], v[140:143], v[226:229], v[108:111]
	v_mfma_f32_16x16x32_bf16 v[108:111], v[136:139], v[222:225], v[108:111]
	s_setprio 0
	s_setprio 1
	v_mfma_f32_16x16x32_bf16 v[96:99], v[136:139], v[230:233], v[96:99]
	v_mfma_f32_16x16x32_bf16 v[96:99], v[140:143], v[234:237], v[96:99]
	v_mfma_f32_16x16x32_bf16 v[88:91], v[176:179], v[234:237], v[88:91]
	v_mfma_f32_16x16x32_bf16 v[88:91], v[172:175], v[230:233], v[88:91]
	v_mfma_f32_16x16x32_bf16 v[84:87], v[180:183], v[230:233], v[84:87]
	v_mfma_f32_16x16x32_bf16 v[84:87], v[184:187], v[234:237], v[84:87]
	v_mfma_f32_16x16x32_bf16 v[76:79], v[210:213], v[234:237], v[76:79]
	v_mfma_f32_16x16x32_bf16 v[76:79], v[206:209], v[230:233], v[76:79]
	v_mfma_f32_16x16x32_bf16 v[64:67], v[206:209], v[238:241], v[64:67]
	v_mfma_f32_16x16x32_bf16 v[64:67], v[210:213], v[242:245], v[64:67]
	v_mfma_f32_16x16x32_bf16 v[68:71], v[184:187], v[242:245], v[68:71]
	v_mfma_f32_16x16x32_bf16 v[68:71], v[180:183], v[238:241], v[68:71]
	v_mfma_f32_16x16x32_bf16 v[72:75], v[172:175], v[238:241], v[72:75]
	v_mfma_f32_16x16x32_bf16 v[72:75], v[176:179], v[242:245], v[72:75]
	s_setprio 2
	s_barrier
	v_mfma_f32_16x16x32_bf16 v[80:83], v[140:143], v[242:245], v[80:83]
	v_mfma_f32_16x16x32_bf16 v[80:83], v[136:139], v[238:241], v[80:83]
	s_setprio 0
	s_add_i32 s44, s72, s41
	v_lshl_add_u64 v[200:201], s[28:29], 0, v[166:167]
	s_mov_b32 m0, s44
	ds_read_b128 v[214:217], v158 offset:16384
	ds_read_b128 v[218:221], v158 offset:17408
	ds_read_b128 v[222:225], v158 offset:18432
	ds_read_b128 v[226:229], v158 offset:19456
	ds_read_b128 v[230:233], v158 offset:20480
	ds_read_b128 v[234:237], v158 offset:21504
	ds_read_b128 v[238:241], v158 offset:22528
	ds_read_b128 v[242:245], v158 offset:23552
	global_load_lds_dwordx4 v[200:201], off
	s_add_i32 m0, s44, 0x2000
	s_add_u32 s80, s28, 0x80000
	v_lshl_add_u64 v[246:247], s[28:29], 0, v[170:171]
	s_addc_u32 s81, s29, 0
	s_add_i32 s44, s73, s41
	global_load_lds_dwordx4 v[246:247], off
	v_lshl_add_u64 v[248:249], s[80:81], 0, v[166:167]
	s_mov_b32 m0, s44
	v_lshl_add_u64 v[250:251], s[48:49], 0, v[168:169]
	global_load_lds_dwordx4 v[248:249], off
	v_lshl_add_u64 v[248:249], s[80:81], 0, v[170:171]
	s_add_i32 m0, s44, 0x2000
	s_nop 0
	global_load_lds_dwordx4 v[248:249], off
	v_lshl_add_u64 v[248:249], s[48:49], 0, v[164:165]
	s_mov_b32 m0, s11
	s_nop 0
	global_load_lds_dwordx4 v[248:249], off
	s_mov_b32 m0, s57
	s_nop 0
	global_load_lds_dwordx4 v[250:251], off
	s_waitcnt vmcnt(8)
	s_waitcnt lgkmcnt(0)
	s_barrier
; #define PG8_STAGE(bufoff, gbase, voff) do { _Pragma("unroll") for (int _i = 0; _i < 2; ++_i) \
;         __builtin_amdgcn_global_load_lds((const unsigned*)((const char*)(gbase) + (voff)[_i]), (PG8_LAS unsigned*)(lds + (bufoff) + ldsw + _i * 8192), 16, 0, 0); } while (0)
; #define PG8_LDA(dst, b, h) do { _Pragma("unroll") for (int m = 0; m < 4; ++m) _Pragma("unroll") for (int k = 0; k < 2; ++k) dst[m][k] = *(const PG8_LAS bf16x8*)(lds + PG8_SA(b, h) + aoff + m * 2048 + k * 1024); } while (0)
; #define PG8_LDB(dst, b, h) do { _Pragma("unroll") for (int n = 0; n < 2; ++n) _Pragma("unroll") for (int k = 0; k < 2; ++k) dst[n][k] = *(const PG8_LAS bf16x8*)(lds + PG8_SB(b, h) + boff + n * 2048 + k * 1024); } while (0)
; #define PG8_MMA(ai, bj, At, Bt) do { __builtin_amdgcn_s_setprio(1); _Pragma("unroll") for (int m = 0; m < 4; ++m) _Pragma("unroll") for (int n = 0; n < 2; ++n) _Pragma("unroll") for (int k = 0; k < 2; ++k) \
;         acc[ai][bj][m][n] = __builtin_amdgcn_mfma_f32_16x16x32_bf16(Bt[n][k], At[m][k], acc[ai][bj][m][n], 0, 0, 0); __builtin_amdgcn_s_setprio(0); } while (0)
; #define PG8_WAIT_V(n) asm volatile("s_waitcnt vmcnt(" #n ")" ::: "memory")
; #define PG8_WAIT_L(n) asm volatile("s_waitcnt lgkmcnt(" #n ")" ::: "memory")
; #define PG8_BAR __builtin_amdgcn_s_barrier()
; #define PG8_SCHED __builtin_amdgcn_sched_barrier(0)
; template <class Epi, class Sched, bool ALIGN_EPI = false, bool SP2 = false>
; __device__ __forceinline__ void gemm_phase(PG8_LAS unsigned char* lds, const Gemm g, const Sched& S, const Epi& E) {
;     ...
;             PG8_WAIT_V(8); PG8_WAIT_L(0); PG8_BAR; PG8_MMA(1, 0, At, B0); PG8_MMA(1, 1, At, B1); PG8_BAR; PG8_SCHED;
;             PG8_LDB(B0, 1, 0); PG8_LDB(B1, 1, 1); PG8_SCHED; PG8_LDA(At, 1, 0); PG8_STAGE(PG8_SA(0, 1), a2 + hstep, voffA);
;             PG8_WAIT_V(8); PG8_WAIT_L(0); PG8_BAR; PG8_MMA(0, 0, At, B0); PG8_MMA(0, 1, At, B1); PG8_BAR; PG8_SCHED;
	s_setprio 1
	s_waitcnt lgkmcnt(0)
	v_mfma_f32_16x16x32_bf16 v[60:63], v[136:139], v[214:217], v[60:63]
	v_mfma_f32_16x16x32_bf16 v[60:63], v[140:143], v[218:221], v[60:63]
	v_mfma_f32_16x16x32_bf16 v[56:59], v[176:179], v[218:221], v[56:59]
	v_mfma_f32_16x16x32_bf16 v[56:59], v[172:175], v[214:217], v[56:59]
	v_mfma_f32_16x16x32_bf16 v[52:55], v[180:183], v[214:217], v[52:55]
	v_mfma_f32_16x16x32_bf16 v[52:55], v[184:187], v[218:221], v[52:55]
	v_mfma_f32_16x16x32_bf16 v[44:47], v[210:213], v[218:221], v[44:47]
	v_mfma_f32_16x16x32_bf16 v[44:47], v[206:209], v[214:217], v[44:47]
	v_mfma_f32_16x16x32_bf16 v[28:31], v[206:209], v[222:225], v[28:31]
	v_mfma_f32_16x16x32_bf16 v[28:31], v[210:213], v[226:229], v[28:31]
	v_mfma_f32_16x16x32_bf16 v[36:39], v[184:187], v[226:229], v[36:39]
	v_mfma_f32_16x16x32_bf16 v[36:39], v[180:183], v[222:225], v[36:39]
	v_mfma_f32_16x16x32_bf16 v[40:43], v[172:175], v[222:225], v[40:43]
	v_mfma_f32_16x16x32_bf16 v[40:43], v[176:179], v[226:229], v[40:43]
	v_mfma_f32_16x16x32_bf16 v[48:51], v[140:143], v[226:229], v[48:51]
	v_mfma_f32_16x16x32_bf16 v[48:51], v[136:139], v[222:225], v[48:51]
	s_setprio 0
	s_setprio 1
	v_mfma_f32_16x16x32_bf16 v[32:35], v[136:139], v[230:233], v[32:35]
	v_mfma_f32_16x16x32_bf16 v[32:35], v[140:143], v[234:237], v[32:35]
	v_mfma_f32_16x16x32_bf16 v[24:27], v[176:179], v[234:237], v[24:27]
	v_mfma_f32_16x16x32_bf16 v[24:27], v[172:175], v[230:233], v[24:27]
	v_mfma_f32_16x16x32_bf16 v[20:23], v[180:183], v[230:233], v[20:23]
	v_mfma_f32_16x16x32_bf16 v[20:23], v[184:187], v[234:237], v[20:23]
	v_mfma_f32_16x16x32_bf16 v[16:19], v[210:213], v[234:237], v[16:19]
	v_mfma_f32_16x16x32_bf16 v[16:19], v[206:209], v[230:233], v[16:19]
	v_mfma_f32_16x16x32_bf16 v[0:3], v[206:209], v[238:241], v[0:3]
	v_mfma_f32_16x16x32_bf16 v[0:3], v[210:213], v[242:245], v[0:3]
	v_mfma_f32_16x16x32_bf16 v[4:7], v[184:187], v[242:245], v[4:7]
	v_mfma_f32_16x16x32_bf16 v[4:7], v[180:183], v[238:241], v[4:7]
	v_mfma_f32_16x16x32_bf16 v[8:11], v[172:175], v[238:241], v[8:11]
	v_mfma_f32_16x16x32_bf16 v[8:11], v[176:179], v[242:245], v[8:11]
	s_setprio 2
	s_barrier
	v_mfma_f32_16x16x32_bf16 v[12:15], v[140:143], v[242:245], v[12:15]
	v_mfma_f32_16x16x32_bf16 v[12:15], v[136:139], v[238:241], v[12:15]
	s_setprio 0
	s_add_i32 s44, 0, 0x18000
	v_add_u32_e32 v144, s44, v146
	s_add_i32 s45, 0, 0x1c000
	ds_read_b128 v[136:139], v144
	ds_read_b128 v[140:143], v144 offset:1024
	ds_read_b128 v[172:175], v144 offset:2048
	ds_read_b128 v[176:179], v144 offset:3072
	v_add_u32_e32 v144, s45, v146
	ds_read_b128 v[180:183], v144
	ds_read_b128 v[184:187], v144 offset:1024
	ds_read_b128 v[206:209], v144 offset:2048
	ds_read_b128 v[210:213], v144 offset:3072
	s_add_u32 s48, s48, 0x80000
	s_addc_u32 s49, s49, 0
	s_mov_b32 m0, s61
	v_lshl_add_u64 v[252:253], s[48:49], 0, v[164:165]
	ds_read_b128 v[214:217], v158 offset:32768
	ds_read_b128 v[218:221], v158 offset:33792
	ds_read_b128 v[222:225], v158 offset:34816
	ds_read_b128 v[226:229], v158 offset:35840
	ds_read_b128 v[230:233], v158 offset:36864
	ds_read_b128 v[234:237], v158 offset:37888
	ds_read_b128 v[238:241], v158 offset:38912
	ds_read_b128 v[242:245], v158 offset:39936
	global_load_lds_dwordx4 v[252:253], off
	v_lshl_add_u64 v[252:253], s[48:49], 0, v[168:169]
	s_mov_b32 m0, s68
	s_nop 0
	global_load_lds_dwordx4 v[252:253], off
	s_waitcnt vmcnt(8)
	s_waitcnt lgkmcnt(0)
	s_barrier
	s_setprio 1
	s_waitcnt lgkmcnt(0)
	v_mfma_f32_16x16x32_bf16 v[124:127], v[136:139], v[214:217], v[124:127]
	v_mfma_f32_16x16x32_bf16 v[124:127], v[140:143], v[218:221], v[124:127]
	v_mfma_f32_16x16x32_bf16 v[120:123], v[176:179], v[218:221], v[120:123]
	v_mfma_f32_16x16x32_bf16 v[120:123], v[172:175], v[214:217], v[120:123]
	v_mfma_f32_16x16x32_bf16 v[116:119], v[180:183], v[214:217], v[116:119]
	v_mfma_f32_16x16x32_bf16 v[116:119], v[184:187], v[218:221], v[116:119]
	v_mfma_f32_16x16x32_bf16 v[112:115], v[210:213], v[218:221], v[112:115]
	v_mfma_f32_16x16x32_bf16 v[112:115], v[206:209], v[214:217], v[112:115]
	v_mfma_f32_16x16x32_bf16 v[92:95], v[206:209], v[222:225], v[92:95]
	v_mfma_f32_16x16x32_bf16 v[92:95], v[210:213], v[226:229], v[92:95]
	v_mfma_f32_16x16x32_bf16 v[100:103], v[184:187], v[226:229], v[100:103]
	v_mfma_f32_16x16x32_bf16 v[100:103], v[180:183], v[222:225], v[100:103]
	v_mfma_f32_16x16x32_bf16 v[104:107], v[172:175], v[222:225], v[104:107]
	v_mfma_f32_16x16x32_bf16 v[104:107], v[176:179], v[226:229], v[104:107]
	v_mfma_f32_16x16x32_bf16 v[108:111], v[140:143], v[226:229], v[108:111]
	v_mfma_f32_16x16x32_bf16 v[108:111], v[136:139], v[222:225], v[108:111]
	s_setprio 0
	s_setprio 1
	v_mfma_f32_16x16x32_bf16 v[96:99], v[136:139], v[230:233], v[96:99]
	v_mfma_f32_16x16x32_bf16 v[96:99], v[140:143], v[234:237], v[96:99]
	v_mfma_f32_16x16x32_bf16 v[88:91], v[176:179], v[234:237], v[88:91]
	v_mfma_f32_16x16x32_bf16 v[88:91], v[172:175], v[230:233], v[88:91]
	v_mfma_f32_16x16x32_bf16 v[84:87], v[180:183], v[230:233], v[84:87]
	v_mfma_f32_16x16x32_bf16 v[84:87], v[184:187], v[234:237], v[84:87]
	v_mfma_f32_16x16x32_bf16 v[76:79], v[210:213], v[234:237], v[76:79]
	v_mfma_f32_16x16x32_bf16 v[76:79], v[206:209], v[230:233], v[76:79]
	v_mfma_f32_16x16x32_bf16 v[64:67], v[206:209], v[238:241], v[64:67]
	v_mfma_f32_16x16x32_bf16 v[64:67], v[210:213], v[242:245], v[64:67]
	v_mfma_f32_16x16x32_bf16 v[68:71], v[184:187], v[242:245], v[68:71]
	v_mfma_f32_16x16x32_bf16 v[68:71], v[180:183], v[238:241], v[68:71]
	v_mfma_f32_16x16x32_bf16 v[72:75], v[172:175], v[238:241], v[72:75]
	v_mfma_f32_16x16x32_bf16 v[72:75], v[176:179], v[242:245], v[72:75]
	s_setprio 2
	s_barrier
; #define PG8_STAGE(bufoff, gbase, voff) do { _Pragma("unroll") for (int _i = 0; _i < 2; ++_i) \
;         __builtin_amdgcn_global_load_lds((const unsigned*)((const char*)(gbase) + (voff)[_i]), (PG8_LAS unsigned*)(lds + (bufoff) + ldsw + _i * 8192), 16, 0, 0); } while (0)
; #define PG8_LDA(dst, b, h) do { _Pragma("unroll") for (int m = 0; m < 4; ++m) _Pragma("unroll") for (int k = 0; k < 2; ++k) dst[m][k] = *(const PG8_LAS bf16x8*)(lds + PG8_SA(b, h) + aoff + m * 2048 + k * 1024); } while (0)
; #define PG8_MMA(ai, bj, At, Bt) do { __builtin_amdgcn_s_setprio(1); _Pragma("unroll") for (int m = 0; m < 4; ++m) _Pragma("unroll") for (int n = 0; n < 2; ++n) _Pragma("unroll") for (int k = 0; k < 2; ++k) \
;         acc[ai][bj][m][n] = __builtin_amdgcn_mfma_f32_16x16x32_bf16(Bt[n][k], At[m][k], acc[ai][bj][m][n], 0, 0, 0); __builtin_amdgcn_s_setprio(0); } while (0)
; #define PG8_WAIT_V(n) asm volatile("s_waitcnt vmcnt(" #n ")" ::: "memory")
; #define PG8_WAIT_L(n) asm volatile("s_waitcnt lgkmcnt(" #n ")" ::: "memory")
; #define PG8_BAR __builtin_amdgcn_s_barrier()
; #define PG8_SCHED __builtin_amdgcn_sched_barrier(0)
; template <class Epi, class Sched, bool ALIGN_EPI = false, bool SP2 = false>
; __device__ __forceinline__ void gemm_phase(PG8_LAS unsigned char* lds, const Gemm g, const Sched& S, const Epi& E) {
;     ...
;             PG8_WAIT_V(8); PG8_WAIT_L(0); PG8_BAR; PG8_MMA(0, 0, At, B0); PG8_MMA(0, 1, At, B1); PG8_BAR; PG8_SCHED;
;             PG8_LDA(At, 1, 1); PG8_STAGE(PG8_SB(1, 0), b3, voffB); PG8_STAGE(PG8_SB(1, 1), b3 + hstep, voffB); PG8_STAGE(PG8_SA(1, 0), a3, voffA);
;             PG8_WAIT_V(8); PG8_WAIT_L(0); PG8_BAR; PG8_MMA(1, 0, At, B0); PG8_MMA(1, 1, At, B1); PG8_BAR; PG8_SCHED;
;     ...
;         if constexpr (ALIGN_EPI) { if (wr == 0) PG8_BAR; }
;         if constexpr (!Epi::AFTER_DRAIN) { E(acc, cur, wr, wc, fr, fq); S.done(cur); }
;         if (!has_next) break;
	v_mfma_f32_16x16x32_bf16 v[80:83], v[140:143], v[242:245], v[80:83]
	v_mfma_f32_16x16x32_bf16 v[80:83], v[136:139], v[238:241], v[80:83]
	s_setprio 0
	s_add_i32 s44, s44, s41
	v_lshl_add_u64 v[200:201], v[200:201], 0, s[18:19]
	s_mov_b32 m0, s44
	ds_read_b128 v[214:217], v158 offset:49152
	ds_read_b128 v[218:221], v158 offset:50176
	ds_read_b128 v[222:225], v158 offset:51200
	ds_read_b128 v[226:229], v158 offset:52224
	ds_read_b128 v[230:233], v158 offset:53248
	ds_read_b128 v[234:237], v158 offset:54272
	ds_read_b128 v[238:241], v158 offset:55296
	ds_read_b128 v[242:245], v158 offset:56320
	global_load_lds_dwordx4 v[200:201], off
	s_add_i32 m0, s44, 0x2000
	s_add_u32 s28, s28, 0x80080
	v_lshl_add_u64 v[200:201], v[246:247], 0, s[18:19]
	s_addc_u32 s29, s29, 0
	s_add_i32 s44, s45, s41
	global_load_lds_dwordx4 v[200:201], off
	v_lshl_add_u64 v[200:201], s[28:29], 0, v[166:167]
	s_mov_b32 m0, s44
	s_nop 0
	global_load_lds_dwordx4 v[200:201], off
	v_lshl_add_u64 v[200:201], s[28:29], 0, v[170:171]
	s_add_i32 m0, s44, 0x2000
	s_nop 0
	global_load_lds_dwordx4 v[200:201], off
	v_lshl_add_u64 v[200:201], v[248:249], 0, s[18:19]
	s_mov_b32 m0, s70
	s_nop 0
	global_load_lds_dwordx4 v[200:201], off
	v_lshl_add_u64 v[200:201], v[250:251], 0, s[18:19]
	s_mov_b32 m0, s71
	s_nop 0
	global_load_lds_dwordx4 v[200:201], off
	s_waitcnt vmcnt(8)
	s_waitcnt lgkmcnt(0)
	s_barrier
	s_setprio 1
	s_waitcnt lgkmcnt(0)
	v_mfma_f32_16x16x32_bf16 v[60:63], v[136:139], v[214:217], v[60:63]
	v_mfma_f32_16x16x32_bf16 v[60:63], v[140:143], v[218:221], v[60:63]
	v_mfma_f32_16x16x32_bf16 v[56:59], v[176:179], v[218:221], v[56:59]
	v_mfma_f32_16x16x32_bf16 v[56:59], v[172:175], v[214:217], v[56:59]
	v_mfma_f32_16x16x32_bf16 v[52:55], v[180:183], v[214:217], v[52:55]
	v_mfma_f32_16x16x32_bf16 v[52:55], v[184:187], v[218:221], v[52:55]
	v_mfma_f32_16x16x32_bf16 v[44:47], v[210:213], v[218:221], v[44:47]
	v_mfma_f32_16x16x32_bf16 v[44:47], v[206:209], v[214:217], v[44:47]
	v_mfma_f32_16x16x32_bf16 v[28:31], v[206:209], v[222:225], v[28:31]
	v_mfma_f32_16x16x32_bf16 v[28:31], v[210:213], v[226:229], v[28:31]
	v_mfma_f32_16x16x32_bf16 v[36:39], v[184:187], v[226:229], v[36:39]
	v_mfma_f32_16x16x32_bf16 v[36:39], v[180:183], v[222:225], v[36:39]
	v_mfma_f32_16x16x32_bf16 v[40:43], v[172:175], v[222:225], v[40:43]
	v_mfma_f32_16x16x32_bf16 v[40:43], v[176:179], v[226:229], v[40:43]
	v_mfma_f32_16x16x32_bf16 v[48:51], v[140:143], v[226:229], v[48:51]
	v_mfma_f32_16x16x32_bf16 v[48:51], v[136:139], v[222:225], v[48:51]
	s_setprio 0
	s_setprio 1
	v_mfma_f32_16x16x32_bf16 v[32:35], v[136:139], v[230:233], v[32:35]
	v_mfma_f32_16x16x32_bf16 v[32:35], v[140:143], v[234:237], v[32:35]
	v_mfma_f32_16x16x32_bf16 v[24:27], v[176:179], v[234:237], v[24:27]
	v_mfma_f32_16x16x32_bf16 v[24:27], v[172:175], v[230:233], v[24:27]
	v_mfma_f32_16x16x32_bf16 v[20:23], v[180:183], v[230:233], v[20:23]
	v_mfma_f32_16x16x32_bf16 v[20:23], v[184:187], v[234:237], v[20:23]
	v_mfma_f32_16x16x32_bf16 v[16:19], v[210:213], v[234:237], v[16:19]
	v_mfma_f32_16x16x32_bf16 v[16:19], v[206:209], v[230:233], v[16:19]
	v_mfma_f32_16x16x32_bf16 v[0:3], v[206:209], v[238:241], v[0:3]
	v_mfma_f32_16x16x32_bf16 v[0:3], v[210:213], v[242:245], v[0:3]
	v_mfma_f32_16x16x32_bf16 v[4:7], v[184:187], v[242:245], v[4:7]
	v_mfma_f32_16x16x32_bf16 v[4:7], v[180:183], v[238:241], v[4:7]
	v_mfma_f32_16x16x32_bf16 v[8:11], v[172:175], v[238:241], v[8:11]
	v_mfma_f32_16x16x32_bf16 v[8:11], v[176:179], v[242:245], v[8:11]
	s_setprio 2
	s_barrier
	v_mfma_f32_16x16x32_bf16 v[12:15], v[140:143], v[242:245], v[12:15]
	v_mfma_f32_16x16x32_bf16 v[12:15], v[136:139], v[238:241], v[12:15]
	s_setprio 0
	s_add_i32 s79, s79, 2
	s_add_u32 s66, s66, 0x100
	s_addc_u32 s67, s67, 0
	s_add_u32 s77, s77, 0x100
	s_addc_u32 s78, s78, 0
	s_cmp_gt_u32 s79, 29
	s_cbranch_scc0 .LBB0_536
	s_and_b64 vcc, exec, s[20:21]
	s_cbranch_vccz .LBB0_539
	s_barrier

; #define PG8_STAGE(bufoff, gbase, voff) do { _Pragma("unroll") for (int _i = 0; _i < 2; ++_i) \
;         __builtin_amdgcn_global_load_lds((const unsigned*)((const char*)(gbase) + (voff)[_i]), (PG8_LAS unsigned*)(lds + (bufoff) + ldsw + _i * 8192), 16, 0, 0); } while (0)
; #define PG8_LDA(dst, b, h) do { _Pragma("unroll") for (int m = 0; m < 4; ++m) _Pragma("unroll") for (int k = 0; k < 2; ++k) dst[m][k] = *(const PG8_LAS bf16x8*)(lds + PG8_SA(b, h) + aoff + m * 2048 + k * 1024); } while (0)
; #define PG8_LDB(dst, b, h) do { _Pragma("unroll") for (int n = 0; n < 2; ++n) _Pragma("unroll") for (int k = 0; k < 2; ++k) dst[n][k] = *(const PG8_LAS bf16x8*)(lds + PG8_SB(b, h) + boff + n * 2048 + k * 1024); } while (0)
; #define PG8_MMA(ai, bj, At, Bt) do { __builtin_amdgcn_s_setprio(1); _Pragma("unroll") for (int m = 0; m < 4; ++m) _Pragma("unroll") for (int n = 0; n < 2; ++n) _Pragma("unroll") for (int k = 0; k < 2; ++k) \
;         acc[ai][bj][m][n] = __builtin_amdgcn_mfma_f32_16x16x32_bf16(Bt[n][k], At[m][k], acc[ai][bj][m][n], 0, 0, 0); __builtin_amdgcn_s_setprio(0); } while (0)
; #define PG8_WAIT_V(n) asm volatile("s_waitcnt vmcnt(" #n ")" ::: "memory")
; #define PG8_BAR __builtin_amdgcn_s_barrier()
; template <class Epi, class Sched, bool ALIGN_EPI = false, bool SP2 = false>
; __device__ __forceinline__ void gemm_phase(PG8_LAS unsigned char* lds, const Gemm g, const Sched& S, const Epi& E) {
;     ...
;         for (int t = 0; t < nt; t += 2) {
;             const bool last = (t == nt - 2);
;             const char* a1 = cA + (size_t)(t + 1) * kstep;
;             const char* a2 = last ? nA : cA + (size_t)(t + 2) * kstep; const char* b2 = last ? nB : cB + (size_t)(t + 2) * kstep;
;             const char* a3 = a2 + kstep; const char* b3 = b2 + kstep;
;             if (last && has_next) S.a_ready(nxt);
;             if constexpr (SP2) {
;             PG8_LDB(B0, 0, 0); PG8_LDB(B1, 0, 1); PG8_SCHED; PG8_LDA(At, 0, 0); PG8_STAGE(PG8_SA(1, 1), a1 + hstep, voffA);
;             PG8_WAIT_V(8); PG8_WAIT_L(0); PG8_BAR; PG8_MMA(0, 0, At, B0); PG8_MMA(0, 1, At, B1); PG8_BAR; PG8_SCHED;
;             PG8_LDA(At, 0, 1); PG8_STAGE(PG8_SB(0, 0), b2, voffB); PG8_STAGE(PG8_SB(0, 1), b2 + hstep, voffB); PG8_STAGE(PG8_SA(0, 0), a2, voffA);
;             PG8_WAIT_V(8); PG8_WAIT_L(0); PG8_BAR; PG8_MMA(1, 0, At, B0); PG8_MMA(1, 1, At, B1); PG8_BAR; PG8_SCHED;
.LBB0_602:
	ds_read_b128 v[76:79], v171
	ds_read_b128 v[84:87], v171 offset:1024
	ds_read_b128 v[92:95], v171 offset:2048
	ds_read_b128 v[96:99], v171 offset:3072
	ds_read_b128 v[144:147], v186
	ds_read_b128 v[148:151], v186 offset:1024
	ds_read_b128 v[152:155], v186 offset:2048
	ds_read_b128 v[156:159], v186 offset:3072
	s_add_u32 s28, s62, 0xffea0080
	s_addc_u32 s29, s63, -1
	s_cmpk_eq_i32 s77, 0x54
	s_cselect_b32 s49, s39, s29
	s_cselect_b32 s48, s38, s28
	s_cselect_b32 s29, s41, s35
	s_cselect_b32 s28, s40, s34
	v_lshl_add_u64 v[200:201], s[62:63], 0, v[172:173]
	s_add_i32 m0, s61, 0xc000
	ds_read_b128 v[178:181], v187
	ds_read_b128 v[182:185], v187 offset:1024
	ds_read_b128 v[206:209], v187 offset:2048
	ds_read_b128 v[210:213], v187 offset:3072
	ds_read_b128 v[214:217], v187 offset:4096
	ds_read_b128 v[218:221], v187 offset:5120
	ds_read_b128 v[222:225], v187 offset:6144
	ds_read_b128 v[226:229], v187 offset:7168
	global_load_lds_dwordx4 v[200:201], off
	v_lshl_add_u64 v[200:201], s[62:63], 0, v[174:175]
	s_add_i32 m0, s61, 0xe000
	s_nop 0
	global_load_lds_dwordx4 v[200:201], off
	s_waitcnt vmcnt(8)
	s_waitcnt lgkmcnt(0)
	s_barrier
	s_setprio 1
	s_waitcnt lgkmcnt(0)
	v_mfma_f32_16x16x32_bf16 v[140:143], v[76:79], v[178:181], v[140:143]
	v_mfma_f32_16x16x32_bf16 v[140:143], v[84:87], v[182:185], v[140:143]
	v_mfma_f32_16x16x32_bf16 v[136:139], v[96:99], v[182:185], v[136:139]
	v_mfma_f32_16x16x32_bf16 v[136:139], v[92:95], v[178:181], v[136:139]
	v_mfma_f32_16x16x32_bf16 v[132:135], v[144:147], v[178:181], v[132:135]
	v_mfma_f32_16x16x32_bf16 v[132:135], v[148:151], v[182:185], v[132:135]
	v_mfma_f32_16x16x32_bf16 v[128:131], v[156:159], v[182:185], v[128:131]
	v_mfma_f32_16x16x32_bf16 v[128:131], v[152:155], v[178:181], v[128:131]
	v_mfma_f32_16x16x32_bf16 v[112:115], v[152:155], v[206:209], v[112:115]
	v_mfma_f32_16x16x32_bf16 v[112:115], v[156:159], v[210:213], v[112:115]
	v_mfma_f32_16x16x32_bf16 v[116:119], v[148:151], v[210:213], v[116:119]
	v_mfma_f32_16x16x32_bf16 v[116:119], v[144:147], v[206:209], v[116:119]
	v_mfma_f32_16x16x32_bf16 v[120:123], v[92:95], v[206:209], v[120:123]
	v_mfma_f32_16x16x32_bf16 v[120:123], v[96:99], v[210:213], v[120:123]
	v_mfma_f32_16x16x32_bf16 v[124:127], v[84:87], v[210:213], v[124:127]
	v_mfma_f32_16x16x32_bf16 v[124:127], v[76:79], v[206:209], v[124:127]
	s_setprio 0
	s_setprio 1
	v_mfma_f32_16x16x32_bf16 v[108:111], v[76:79], v[214:217], v[108:111]
	v_mfma_f32_16x16x32_bf16 v[108:111], v[84:87], v[218:221], v[108:111]
	v_mfma_f32_16x16x32_bf16 v[104:107], v[96:99], v[218:221], v[104:107]
	v_mfma_f32_16x16x32_bf16 v[104:107], v[92:95], v[214:217], v[104:107]
	v_mfma_f32_16x16x32_bf16 v[100:103], v[144:147], v[214:217], v[100:103]
	v_mfma_f32_16x16x32_bf16 v[100:103], v[148:151], v[218:221], v[100:103]
	v_mfma_f32_16x16x32_bf16 v[88:91], v[156:159], v[218:221], v[88:91]
	v_mfma_f32_16x16x32_bf16 v[88:91], v[152:155], v[214:217], v[88:91]
	v_mfma_f32_16x16x32_bf16 v[64:67], v[152:155], v[222:225], v[64:67]
	v_mfma_f32_16x16x32_bf16 v[64:67], v[156:159], v[226:229], v[64:67]
	v_mfma_f32_16x16x32_bf16 v[68:71], v[148:151], v[226:229], v[68:71]
	v_mfma_f32_16x16x32_bf16 v[68:71], v[144:147], v[222:225], v[68:71]
	v_mfma_f32_16x16x32_bf16 v[72:75], v[92:95], v[222:225], v[72:75]
	v_mfma_f32_16x16x32_bf16 v[72:75], v[96:99], v[226:229], v[72:75]
	s_setprio 2
	s_barrier
	v_mfma_f32_16x16x32_bf16 v[80:83], v[84:87], v[226:229], v[80:83]
	v_mfma_f32_16x16x32_bf16 v[80:83], v[76:79], v[222:225], v[80:83]
	s_setprio 0
	s_add_i32 s44, s70, s57
	v_lshl_add_u64 v[200:201], s[28:29], 0, v[160:161]
	s_mov_b32 m0, s44
	ds_read_b128 v[178:181], v187 offset:16384
	ds_read_b128 v[182:185], v187 offset:17408
	ds_read_b128 v[206:209], v187 offset:18432
	ds_read_b128 v[210:213], v187 offset:19456
	ds_read_b128 v[214:217], v187 offset:20480
	ds_read_b128 v[218:221], v187 offset:21504
	ds_read_b128 v[222:225], v187 offset:22528
	ds_read_b128 v[226:229], v187 offset:23552
	global_load_lds_dwordx4 v[200:201], off
	s_add_i32 m0, s44, 0x2000
	s_add_u32 s78, s28, 0x160000
	v_lshl_add_u64 v[230:231], s[28:29], 0, v[162:163]
	s_addc_u32 s79, s29, 0
	s_add_i32 s44, s71, s57
	global_load_lds_dwordx4 v[230:231], off
	v_lshl_add_u64 v[232:233], s[78:79], 0, v[160:161]
	s_mov_b32 m0, s44
	v_lshl_add_u64 v[234:235], s[48:49], 0, v[162:163]
	global_load_lds_dwordx4 v[232:233], off
	v_lshl_add_u64 v[232:233], s[78:79], 0, v[162:163]
	s_add_i32 m0, s44, 0x2000
	s_nop 0
	global_load_lds_dwordx4 v[232:233], off
	v_lshl_add_u64 v[232:233], s[48:49], 0, v[160:161]
	s_mov_b32 m0, s61
	s_nop 0
	global_load_lds_dwordx4 v[232:233], off
	s_mov_b32 m0, s64
	s_nop 0
	global_load_lds_dwordx4 v[234:235], off
	s_waitcnt vmcnt(8)
	s_waitcnt lgkmcnt(0)
	s_barrier
; #define PG8_STAGE(bufoff, gbase, voff) do { _Pragma("unroll") for (int _i = 0; _i < 2; ++_i) \
;         __builtin_amdgcn_global_load_lds((const unsigned*)((const char*)(gbase) + (voff)[_i]), (PG8_LAS unsigned*)(lds + (bufoff) + ldsw + _i * 8192), 16, 0, 0); } while (0)
; #define PG8_LDA(dst, b, h) do { _Pragma("unroll") for (int m = 0; m < 4; ++m) _Pragma("unroll") for (int k = 0; k < 2; ++k) dst[m][k] = *(const PG8_LAS bf16x8*)(lds + PG8_SA(b, h) + aoff + m * 2048 + k * 1024); } while (0)
; #define PG8_LDB(dst, b, h) do { _Pragma("unroll") for (int n = 0; n < 2; ++n) _Pragma("unroll") for (int k = 0; k < 2; ++k) dst[n][k] = *(const PG8_LAS bf16x8*)(lds + PG8_SB(b, h) + boff + n * 2048 + k * 1024); } while (0)
; #define PG8_MMA(ai, bj, At, Bt) do { __builtin_amdgcn_s_setprio(1); _Pragma("unroll") for (int m = 0; m < 4; ++m) _Pragma("unroll") for (int n = 0; n < 2; ++n) _Pragma("unroll") for (int k = 0; k < 2; ++k) \
;         acc[ai][bj][m][n] = __builtin_amdgcn_mfma_f32_16x16x32_bf16(Bt[n][k], At[m][k], acc[ai][bj][m][n], 0, 0, 0); __builtin_amdgcn_s_setprio(0); } while (0)
; #define PG8_WAIT_V(n) asm volatile("s_waitcnt vmcnt(" #n ")" ::: "memory")
; #define PG8_WAIT_L(n) asm volatile("s_waitcnt lgkmcnt(" #n ")" ::: "memory")
; #define PG8_BAR __builtin_amdgcn_s_barrier()
; #define PG8_SCHED __builtin_amdgcn_sched_barrier(0)
; template <class Epi, class Sched, bool ALIGN_EPI = false, bool SP2 = false>
; __device__ __forceinline__ void gemm_phase(PG8_LAS unsigned char* lds, const Gemm g, const Sched& S, const Epi& E) {
;     ...
;             PG8_WAIT_V(8); PG8_WAIT_L(0); PG8_BAR; PG8_MMA(1, 0, At, B0); PG8_MMA(1, 1, At, B1); PG8_BAR; PG8_SCHED;
;             PG8_LDB(B0, 1, 0); PG8_LDB(B1, 1, 1); PG8_SCHED; PG8_LDA(At, 1, 0); PG8_STAGE(PG8_SA(0, 1), a2 + hstep, voffA);
;             PG8_WAIT_V(8); PG8_WAIT_L(0); PG8_BAR; PG8_MMA(0, 0, At, B0); PG8_MMA(0, 1, At, B1); PG8_BAR; PG8_SCHED;
	s_setprio 1
	s_waitcnt lgkmcnt(0)
	v_mfma_f32_16x16x32_bf16 v[60:63], v[76:79], v[178:181], v[60:63]
	v_mfma_f32_16x16x32_bf16 v[60:63], v[84:87], v[182:185], v[60:63]
	v_mfma_f32_16x16x32_bf16 v[56:59], v[96:99], v[182:185], v[56:59]
	v_mfma_f32_16x16x32_bf16 v[56:59], v[92:95], v[178:181], v[56:59]
	v_mfma_f32_16x16x32_bf16 v[52:55], v[144:147], v[178:181], v[52:55]
	v_mfma_f32_16x16x32_bf16 v[52:55], v[148:151], v[182:185], v[52:55]
	v_mfma_f32_16x16x32_bf16 v[48:51], v[156:159], v[182:185], v[48:51]
	v_mfma_f32_16x16x32_bf16 v[48:51], v[152:155], v[178:181], v[48:51]
	v_mfma_f32_16x16x32_bf16 v[32:35], v[152:155], v[206:209], v[32:35]
	v_mfma_f32_16x16x32_bf16 v[32:35], v[156:159], v[210:213], v[32:35]
	v_mfma_f32_16x16x32_bf16 v[36:39], v[148:151], v[210:213], v[36:39]
	v_mfma_f32_16x16x32_bf16 v[36:39], v[144:147], v[206:209], v[36:39]
	v_mfma_f32_16x16x32_bf16 v[40:43], v[92:95], v[206:209], v[40:43]
	v_mfma_f32_16x16x32_bf16 v[40:43], v[96:99], v[210:213], v[40:43]
	v_mfma_f32_16x16x32_bf16 v[44:47], v[84:87], v[210:213], v[44:47]
	v_mfma_f32_16x16x32_bf16 v[44:47], v[76:79], v[206:209], v[44:47]
	s_setprio 0
	s_setprio 1
	v_mfma_f32_16x16x32_bf16 v[28:31], v[76:79], v[214:217], v[28:31]
	v_mfma_f32_16x16x32_bf16 v[28:31], v[84:87], v[218:221], v[28:31]
	v_mfma_f32_16x16x32_bf16 v[24:27], v[96:99], v[218:221], v[24:27]
	v_mfma_f32_16x16x32_bf16 v[24:27], v[92:95], v[214:217], v[24:27]
	v_mfma_f32_16x16x32_bf16 v[20:23], v[144:147], v[214:217], v[20:23]
	v_mfma_f32_16x16x32_bf16 v[20:23], v[148:151], v[218:221], v[20:23]
	v_mfma_f32_16x16x32_bf16 v[16:19], v[156:159], v[218:221], v[16:19]
	v_mfma_f32_16x16x32_bf16 v[16:19], v[152:155], v[214:217], v[16:19]
	v_mfma_f32_16x16x32_bf16 v[0:3], v[152:155], v[222:225], v[0:3]
	v_mfma_f32_16x16x32_bf16 v[0:3], v[156:159], v[226:229], v[0:3]
	v_mfma_f32_16x16x32_bf16 v[4:7], v[148:151], v[226:229], v[4:7]
	v_mfma_f32_16x16x32_bf16 v[4:7], v[144:147], v[222:225], v[4:7]
	v_mfma_f32_16x16x32_bf16 v[8:11], v[92:95], v[222:225], v[8:11]
	v_mfma_f32_16x16x32_bf16 v[8:11], v[96:99], v[226:229], v[8:11]
	s_setprio 2
	s_barrier
	v_mfma_f32_16x16x32_bf16 v[12:15], v[84:87], v[226:229], v[12:15]
	v_mfma_f32_16x16x32_bf16 v[12:15], v[76:79], v[222:225], v[12:15]
	s_setprio 0
	s_add_i32 s44, 0, 0x18000
	s_add_i32 s45, 0, 0x1c000
	v_add_u32_e32 v96, s44, v167
	v_add_u32_e32 v156, s45, v167
	ds_read_b128 v[76:79], v96
	ds_read_b128 v[84:87], v96 offset:1024
	ds_read_b128 v[92:95], v96 offset:2048
	ds_read_b128 v[96:99], v96 offset:3072
	ds_read_b128 v[144:147], v156
	ds_read_b128 v[148:151], v156 offset:1024
	ds_read_b128 v[152:155], v156 offset:2048
	ds_read_b128 v[156:159], v156 offset:3072
	s_add_u32 s48, s48, 0x160000
	s_addc_u32 s49, s49, 0
	s_mov_b32 m0, s65
	v_lshl_add_u64 v[236:237], s[48:49], 0, v[160:161]
	ds_read_b128 v[178:181], v187 offset:32768
	ds_read_b128 v[182:185], v187 offset:33792
	ds_read_b128 v[206:209], v187 offset:34816
	ds_read_b128 v[210:213], v187 offset:35840
	ds_read_b128 v[214:217], v187 offset:36864
	ds_read_b128 v[218:221], v187 offset:37888
	ds_read_b128 v[222:225], v187 offset:38912
	ds_read_b128 v[226:229], v187 offset:39936
	global_load_lds_dwordx4 v[236:237], off
	v_lshl_add_u64 v[236:237], s[48:49], 0, v[162:163]
	s_mov_b32 m0, s66
	s_nop 0
	global_load_lds_dwordx4 v[236:237], off
	s_waitcnt vmcnt(8)
	s_waitcnt lgkmcnt(0)
	s_barrier
	s_setprio 1
	s_waitcnt lgkmcnt(0)
	v_mfma_f32_16x16x32_bf16 v[140:143], v[76:79], v[178:181], v[140:143]
	v_mfma_f32_16x16x32_bf16 v[140:143], v[84:87], v[182:185], v[140:143]
	v_mfma_f32_16x16x32_bf16 v[136:139], v[96:99], v[182:185], v[136:139]
	v_mfma_f32_16x16x32_bf16 v[136:139], v[92:95], v[178:181], v[136:139]
	v_mfma_f32_16x16x32_bf16 v[132:135], v[144:147], v[178:181], v[132:135]
	v_mfma_f32_16x16x32_bf16 v[132:135], v[148:151], v[182:185], v[132:135]
	v_mfma_f32_16x16x32_bf16 v[128:131], v[156:159], v[182:185], v[128:131]
	v_mfma_f32_16x16x32_bf16 v[128:131], v[152:155], v[178:181], v[128:131]
	v_mfma_f32_16x16x32_bf16 v[112:115], v[152:155], v[206:209], v[112:115]
	v_mfma_f32_16x16x32_bf16 v[112:115], v[156:159], v[210:213], v[112:115]
	v_mfma_f32_16x16x32_bf16 v[116:119], v[148:151], v[210:213], v[116:119]
	v_mfma_f32_16x16x32_bf16 v[116:119], v[144:147], v[206:209], v[116:119]
	v_mfma_f32_16x16x32_bf16 v[120:123], v[92:95], v[206:209], v[120:123]
	v_mfma_f32_16x16x32_bf16 v[120:123], v[96:99], v[210:213], v[120:123]
	v_mfma_f32_16x16x32_bf16 v[124:127], v[84:87], v[210:213], v[124:127]
	v_mfma_f32_16x16x32_bf16 v[124:127], v[76:79], v[206:209], v[124:127]
	s_setprio 0
	s_setprio 1
	v_mfma_f32_16x16x32_bf16 v[108:111], v[76:79], v[214:217], v[108:111]
	v_mfma_f32_16x16x32_bf16 v[108:111], v[84:87], v[218:221], v[108:111]
	v_mfma_f32_16x16x32_bf16 v[104:107], v[96:99], v[218:221], v[104:107]
	v_mfma_f32_16x16x32_bf16 v[104:107], v[92:95], v[214:217], v[104:107]
	v_mfma_f32_16x16x32_bf16 v[100:103], v[144:147], v[214:217], v[100:103]
	v_mfma_f32_16x16x32_bf16 v[100:103], v[148:151], v[218:221], v[100:103]
	v_mfma_f32_16x16x32_bf16 v[88:91], v[156:159], v[218:221], v[88:91]
	v_mfma_f32_16x16x32_bf16 v[88:91], v[152:155], v[214:217], v[88:91]
	v_mfma_f32_16x16x32_bf16 v[64:67], v[152:155], v[222:225], v[64:67]
	v_mfma_f32_16x16x32_bf16 v[64:67], v[156:159], v[226:229], v[64:67]
	v_mfma_f32_16x16x32_bf16 v[68:71], v[148:151], v[226:229], v[68:71]
	v_mfma_f32_16x16x32_bf16 v[68:71], v[144:147], v[222:225], v[68:71]
	v_mfma_f32_16x16x32_bf16 v[72:75], v[92:95], v[222:225], v[72:75]
	v_mfma_f32_16x16x32_bf16 v[72:75], v[96:99], v[226:229], v[72:75]
	s_setprio 2
	s_barrier
; #define PG8_STAGE(bufoff, gbase, voff) do { _Pragma("unroll") for (int _i = 0; _i < 2; ++_i) \
;         __builtin_amdgcn_global_load_lds((const unsigned*)((const char*)(gbase) + (voff)[_i]), (PG8_LAS unsigned*)(lds + (bufoff) + ldsw + _i * 8192), 16, 0, 0); } while (0)
; #define PG8_LDA(dst, b, h) do { _Pragma("unroll") for (int m = 0; m < 4; ++m) _Pragma("unroll") for (int k = 0; k < 2; ++k) dst[m][k] = *(const PG8_LAS bf16x8*)(lds + PG8_SA(b, h) + aoff + m * 2048 + k * 1024); } while (0)
; #define PG8_MMA(ai, bj, At, Bt) do { __builtin_amdgcn_s_setprio(1); _Pragma("unroll") for (int m = 0; m < 4; ++m) _Pragma("unroll") for (int n = 0; n < 2; ++n) _Pragma("unroll") for (int k = 0; k < 2; ++k) \
;         acc[ai][bj][m][n] = __builtin_amdgcn_mfma_f32_16x16x32_bf16(Bt[n][k], At[m][k], acc[ai][bj][m][n], 0, 0, 0); __builtin_amdgcn_s_setprio(0); } while (0)
; #define PG8_WAIT_V(n) asm volatile("s_waitcnt vmcnt(" #n ")" ::: "memory")
; #define PG8_WAIT_L(n) asm volatile("s_waitcnt lgkmcnt(" #n ")" ::: "memory")
; #define PG8_BAR __builtin_amdgcn_s_barrier()
; #define PG8_SCHED __builtin_amdgcn_sched_barrier(0)
; template <class Epi, class Sched, bool ALIGN_EPI = false, bool SP2 = false>
; __device__ __forceinline__ void gemm_phase(PG8_LAS unsigned char* lds, const Gemm g, const Sched& S, const Epi& E) {
;     ...
;             PG8_WAIT_V(8); PG8_WAIT_L(0); PG8_BAR; PG8_MMA(0, 0, At, B0); PG8_MMA(0, 1, At, B1); PG8_BAR; PG8_SCHED;
;             PG8_LDA(At, 1, 1); PG8_STAGE(PG8_SB(1, 0), b3, voffB); PG8_STAGE(PG8_SB(1, 1), b3 + hstep, voffB); PG8_STAGE(PG8_SA(1, 0), a3, voffA);
;             PG8_WAIT_V(8); PG8_WAIT_L(0); PG8_BAR; PG8_MMA(1, 0, At, B0); PG8_MMA(1, 1, At, B1); PG8_BAR; PG8_SCHED;
;     ...
;         if constexpr (ALIGN_EPI) { if (wr == 0) PG8_BAR; }
;         if constexpr (!Epi::AFTER_DRAIN) { E(acc, cur, wr, wc, fr, fq); S.done(cur); }
;         if (!has_next) break;
	v_mfma_f32_16x16x32_bf16 v[80:83], v[84:87], v[226:229], v[80:83]
	v_mfma_f32_16x16x32_bf16 v[80:83], v[76:79], v[222:225], v[80:83]
	s_setprio 0
	s_add_i32 s44, s44, s57
	v_lshl_add_u64 v[200:201], v[200:201], 0, s[20:21]
	s_mov_b32 m0, s44
	ds_read_b128 v[178:181], v187 offset:49152
	ds_read_b128 v[182:185], v187 offset:50176
	ds_read_b128 v[206:209], v187 offset:51200
	ds_read_b128 v[210:213], v187 offset:52224
	ds_read_b128 v[214:217], v187 offset:53248
	ds_read_b128 v[218:221], v187 offset:54272
	ds_read_b128 v[222:225], v187 offset:55296
	ds_read_b128 v[226:229], v187 offset:56320
	global_load_lds_dwordx4 v[200:201], off
	s_add_i32 m0, s44, 0x2000
	s_add_u32 s28, s28, 0x160080
	v_lshl_add_u64 v[200:201], v[230:231], 0, s[20:21]
	s_addc_u32 s29, s29, 0
	s_add_i32 s44, s45, s57
	global_load_lds_dwordx4 v[200:201], off
	v_lshl_add_u64 v[200:201], s[28:29], 0, v[160:161]
	s_mov_b32 m0, s44
	s_nop 0
	global_load_lds_dwordx4 v[200:201], off
	v_lshl_add_u64 v[200:201], s[28:29], 0, v[162:163]
	s_add_i32 m0, s44, 0x2000
	s_nop 0
	global_load_lds_dwordx4 v[200:201], off
	v_lshl_add_u64 v[200:201], v[232:233], 0, s[20:21]
	s_mov_b32 m0, s67
	s_nop 0
	global_load_lds_dwordx4 v[200:201], off
	v_lshl_add_u64 v[200:201], v[234:235], 0, s[20:21]
	s_mov_b32 m0, s68
	s_nop 0
	global_load_lds_dwordx4 v[200:201], off
	s_waitcnt vmcnt(8)
	s_waitcnt lgkmcnt(0)
	s_barrier
	s_setprio 1
	s_waitcnt lgkmcnt(0)
	v_mfma_f32_16x16x32_bf16 v[60:63], v[76:79], v[178:181], v[60:63]
	v_mfma_f32_16x16x32_bf16 v[60:63], v[84:87], v[182:185], v[60:63]
	v_mfma_f32_16x16x32_bf16 v[56:59], v[96:99], v[182:185], v[56:59]
	v_mfma_f32_16x16x32_bf16 v[56:59], v[92:95], v[178:181], v[56:59]
	v_mfma_f32_16x16x32_bf16 v[52:55], v[144:147], v[178:181], v[52:55]
	v_mfma_f32_16x16x32_bf16 v[52:55], v[148:151], v[182:185], v[52:55]
	v_mfma_f32_16x16x32_bf16 v[48:51], v[156:159], v[182:185], v[48:51]
	v_mfma_f32_16x16x32_bf16 v[48:51], v[152:155], v[178:181], v[48:51]
	v_mfma_f32_16x16x32_bf16 v[32:35], v[152:155], v[206:209], v[32:35]
	v_mfma_f32_16x16x32_bf16 v[32:35], v[156:159], v[210:213], v[32:35]
	v_mfma_f32_16x16x32_bf16 v[36:39], v[148:151], v[210:213], v[36:39]
	v_mfma_f32_16x16x32_bf16 v[36:39], v[144:147], v[206:209], v[36:39]
	v_mfma_f32_16x16x32_bf16 v[40:43], v[92:95], v[206:209], v[40:43]
	v_mfma_f32_16x16x32_bf16 v[40:43], v[96:99], v[210:213], v[40:43]
	v_mfma_f32_16x16x32_bf16 v[44:47], v[84:87], v[210:213], v[44:47]
	v_mfma_f32_16x16x32_bf16 v[44:47], v[76:79], v[206:209], v[44:47]
	s_setprio 0
	s_setprio 1
	v_mfma_f32_16x16x32_bf16 v[28:31], v[76:79], v[214:217], v[28:31]
	v_mfma_f32_16x16x32_bf16 v[28:31], v[84:87], v[218:221], v[28:31]
	v_mfma_f32_16x16x32_bf16 v[24:27], v[96:99], v[218:221], v[24:27]
	v_mfma_f32_16x16x32_bf16 v[24:27], v[92:95], v[214:217], v[24:27]
	v_mfma_f32_16x16x32_bf16 v[20:23], v[144:147], v[214:217], v[20:23]
	v_mfma_f32_16x16x32_bf16 v[20:23], v[148:151], v[218:221], v[20:23]
	v_mfma_f32_16x16x32_bf16 v[16:19], v[156:159], v[218:221], v[16:19]
	v_mfma_f32_16x16x32_bf16 v[16:19], v[152:155], v[214:217], v[16:19]
	v_mfma_f32_16x16x32_bf16 v[0:3], v[152:155], v[222:225], v[0:3]
	v_mfma_f32_16x16x32_bf16 v[0:3], v[156:159], v[226:229], v[0:3]
	v_mfma_f32_16x16x32_bf16 v[4:7], v[148:151], v[226:229], v[4:7]
	v_mfma_f32_16x16x32_bf16 v[4:7], v[144:147], v[222:225], v[4:7]
	v_mfma_f32_16x16x32_bf16 v[8:11], v[92:95], v[222:225], v[8:11]
	v_mfma_f32_16x16x32_bf16 v[8:11], v[96:99], v[226:229], v[8:11]
	s_setprio 2
	s_barrier
	v_mfma_f32_16x16x32_bf16 v[12:15], v[84:87], v[226:229], v[12:15]
	v_mfma_f32_16x16x32_bf16 v[12:15], v[76:79], v[222:225], v[12:15]
	s_setprio 0
	s_add_i32 s77, s77, 2
	s_add_u32 s62, s62, 0x100
	s_addc_u32 s63, s63, 0
	s_add_u32 s34, s34, 0x100
	s_addc_u32 s35, s35, 0
	s_cmpk_gt_u32 s77, 0x55
	s_cbranch_scc0 .LBB0_602
	s_and_b64 vcc, exec, s[22:23]
	s_cbranch_vccz .LBB0_605
	s_barrier

; #define PG8_STAGE(bufoff, gbase, voff) do { _Pragma("unroll") for (int _i = 0; _i < 2; ++_i) \
;         __builtin_amdgcn_global_load_lds((const unsigned*)((const char*)(gbase) + (voff)[_i]), (PG8_LAS unsigned*)(lds + (bufoff) + ldsw + _i * 8192), 16, 0, 0); } while (0)
; #define PG8_LDA(dst, b, h) do { _Pragma("unroll") for (int m = 0; m < 4; ++m) _Pragma("unroll") for (int k = 0; k < 2; ++k) dst[m][k] = *(const PG8_LAS bf16x8*)(lds + PG8_SA(b, h) + aoff + m * 2048 + k * 1024); } while (0)
; #define PG8_LDB(dst, b, h) do { _Pragma("unroll") for (int n = 0; n < 2; ++n) _Pragma("unroll") for (int k = 0; k < 2; ++k) dst[n][k] = *(const PG8_LAS bf16x8*)(lds + PG8_SB(b, h) + boff + n * 2048 + k * 1024); } while (0)
; #define PG8_MMA(ai, bj, At, Bt) do { __builtin_amdgcn_s_setprio(1); _Pragma("unroll") for (int m = 0; m < 4; ++m) _Pragma("unroll") for (int n = 0; n < 2; ++n) _Pragma("unroll") for (int k = 0; k < 2; ++k) \
;         acc[ai][bj][m][n] = __builtin_amdgcn_mfma_f32_16x16x32_bf16(Bt[n][k], At[m][k], acc[ai][bj][m][n], 0, 0, 0); __builtin_amdgcn_s_setprio(0); } while (0)
; #define PG8_WAIT_V(n) asm volatile("s_waitcnt vmcnt(" #n ")" ::: "memory")
; #define PG8_BAR __builtin_amdgcn_s_barrier()
; template <class Epi, class Sched, bool ALIGN_EPI = false, bool SP2 = false>
; __device__ __forceinline__ void gemm_phase(PG8_LAS unsigned char* lds, const Gemm g, const Sched& S, const Epi& E) {
;     ...
;         for (int t = 0; t < nt; t += 2) {
;             const bool last = (t == nt - 2);
;             const char* a1 = cA + (size_t)(t + 1) * kstep;
;             const char* a2 = last ? nA : cA + (size_t)(t + 2) * kstep; const char* b2 = last ? nB : cB + (size_t)(t + 2) * kstep;
;             const char* a3 = a2 + kstep; const char* b3 = b2 + kstep;
;             if (last && has_next) S.a_ready(nxt);
;             if constexpr (SP2) {
;             PG8_LDB(B0, 0, 0); PG8_LDB(B1, 0, 1); PG8_SCHED; PG8_LDA(At, 0, 0); PG8_STAGE(PG8_SA(1, 1), a1 + hstep, voffA);
;             PG8_WAIT_V(8); PG8_WAIT_L(0); PG8_BAR; PG8_MMA(0, 0, At, B0); PG8_MMA(0, 1, At, B1); PG8_BAR; PG8_SCHED;
;             PG8_LDA(At, 0, 1); PG8_STAGE(PG8_SB(0, 0), b2, voffB); PG8_STAGE(PG8_SB(0, 1), b2 + hstep, voffB); PG8_STAGE(PG8_SA(0, 0), a2, voffA);
;             PG8_WAIT_V(8); PG8_WAIT_L(0); PG8_BAR; PG8_MMA(1, 0, At, B0); PG8_MMA(1, 1, At, B1); PG8_BAR; PG8_SCHED;
.LBB0_719:
	ds_read_b128 v[88:91], v208
	ds_read_b128 v[96:99], v208 offset:1024
	ds_read_b128 v[136:139], v208 offset:2048
	ds_read_b128 v[140:143], v208 offset:3072
	ds_read_b128 v[144:147], v209
	ds_read_b128 v[148:151], v209 offset:1024
	ds_read_b128 v[152:155], v209 offset:2048
	ds_read_b128 v[156:159], v209 offset:3072
	s_add_u32 s44, s62, 0xfff80080
	s_addc_u32 s45, s63, -1
	s_cmp_eq_u32 s76, 28
	s_cselect_b32 s59, s29, s45
	s_cselect_b32 s58, s34, s44
	s_cselect_b32 s57, s23, s75
	s_cselect_b32 s56, s35, s74
	v_lshl_add_u64 v[200:201], s[62:63], 0, v[172:173]
	s_add_i32 m0, s49, 0xc000
	ds_read_b128 v[178:181], v210
	ds_read_b128 v[182:185], v210 offset:1024
	ds_read_b128 v[186:189], v210 offset:2048
	ds_read_b128 v[212:215], v210 offset:3072
	ds_read_b128 v[216:219], v210 offset:4096
	ds_read_b128 v[220:223], v210 offset:5120
	ds_read_b128 v[224:227], v210 offset:6144
	ds_read_b128 v[228:231], v210 offset:7168
	global_load_lds_dwordx4 v[200:201], off
	v_lshl_add_u64 v[200:201], s[62:63], 0, v[174:175]
	s_add_i32 m0, s49, 0xe000
	s_nop 0
	global_load_lds_dwordx4 v[200:201], off
	s_waitcnt vmcnt(8)
	s_waitcnt lgkmcnt(0)
	s_barrier
	s_setprio 1
	s_waitcnt lgkmcnt(0)
	v_mfma_f32_16x16x32_bf16 v[128:131], v[88:91], v[178:181], v[128:131]
	v_mfma_f32_16x16x32_bf16 v[128:131], v[96:99], v[182:185], v[128:131]
	v_mfma_f32_16x16x32_bf16 v[120:123], v[140:143], v[182:185], v[120:123]
	v_mfma_f32_16x16x32_bf16 v[120:123], v[136:139], v[178:181], v[120:123]
	v_mfma_f32_16x16x32_bf16 v[132:135], v[144:147], v[178:181], v[132:135]
	v_mfma_f32_16x16x32_bf16 v[132:135], v[148:151], v[182:185], v[132:135]
	v_mfma_f32_16x16x32_bf16 v[124:127], v[156:159], v[182:185], v[124:127]
	v_mfma_f32_16x16x32_bf16 v[124:127], v[152:155], v[178:181], v[124:127]
	v_mfma_f32_16x16x32_bf16 v[104:107], v[152:155], v[186:189], v[104:107]
	v_mfma_f32_16x16x32_bf16 v[104:107], v[156:159], v[212:215], v[104:107]
	v_mfma_f32_16x16x32_bf16 v[112:115], v[148:151], v[212:215], v[112:115]
	v_mfma_f32_16x16x32_bf16 v[112:115], v[144:147], v[186:189], v[112:115]
	v_mfma_f32_16x16x32_bf16 v[108:111], v[136:139], v[186:189], v[108:111]
	v_mfma_f32_16x16x32_bf16 v[108:111], v[140:143], v[212:215], v[108:111]
	v_mfma_f32_16x16x32_bf16 v[116:119], v[96:99], v[212:215], v[116:119]
	v_mfma_f32_16x16x32_bf16 v[116:119], v[88:91], v[186:189], v[116:119]
	s_setprio 0
	s_setprio 1
	v_mfma_f32_16x16x32_bf16 v[100:103], v[88:91], v[216:219], v[100:103]
	v_mfma_f32_16x16x32_bf16 v[100:103], v[96:99], v[220:223], v[100:103]
	v_mfma_f32_16x16x32_bf16 v[84:87], v[140:143], v[220:223], v[84:87]
	v_mfma_f32_16x16x32_bf16 v[84:87], v[136:139], v[216:219], v[84:87]
	v_mfma_f32_16x16x32_bf16 v[92:95], v[144:147], v[216:219], v[92:95]
	v_mfma_f32_16x16x32_bf16 v[92:95], v[148:151], v[220:223], v[92:95]
	v_mfma_f32_16x16x32_bf16 v[80:83], v[156:159], v[220:223], v[80:83]
	v_mfma_f32_16x16x32_bf16 v[80:83], v[152:155], v[216:219], v[80:83]
	v_mfma_f32_16x16x32_bf16 v[64:67], v[152:155], v[224:227], v[64:67]
	v_mfma_f32_16x16x32_bf16 v[64:67], v[156:159], v[228:231], v[64:67]
	v_mfma_f32_16x16x32_bf16 v[72:75], v[148:151], v[228:231], v[72:75]
	v_mfma_f32_16x16x32_bf16 v[72:75], v[144:147], v[224:227], v[72:75]
	v_mfma_f32_16x16x32_bf16 v[68:71], v[136:139], v[224:227], v[68:71]
	v_mfma_f32_16x16x32_bf16 v[68:71], v[140:143], v[228:231], v[68:71]
	s_setprio 2
	s_barrier
	v_mfma_f32_16x16x32_bf16 v[76:79], v[96:99], v[228:231], v[76:79]
	v_mfma_f32_16x16x32_bf16 v[76:79], v[88:91], v[224:227], v[76:79]
	s_setprio 0
	s_add_i32 s44, s71, s65
	v_lshl_add_u64 v[200:201], s[56:57], 0, v[164:165]
	s_mov_b32 m0, s44
	ds_read_b128 v[178:181], v210 offset:16384
	ds_read_b128 v[182:185], v210 offset:17408
	ds_read_b128 v[186:189], v210 offset:18432
	ds_read_b128 v[212:215], v210 offset:19456
	ds_read_b128 v[216:219], v210 offset:20480
	ds_read_b128 v[220:223], v210 offset:21504
	ds_read_b128 v[224:227], v210 offset:22528
	ds_read_b128 v[228:231], v210 offset:23552
	global_load_lds_dwordx4 v[200:201], off
	s_add_i32 m0, s44, 0x2000
	s_add_u32 s78, s56, 0x80000
	v_lshl_add_u64 v[232:233], s[56:57], 0, v[168:169]
	s_addc_u32 s79, s57, 0
	s_add_i32 s44, s72, s65
	global_load_lds_dwordx4 v[232:233], off
	v_lshl_add_u64 v[234:235], s[78:79], 0, v[164:165]
	s_mov_b32 m0, s44
	v_lshl_add_u64 v[236:237], s[58:59], 0, v[168:169]
	global_load_lds_dwordx4 v[234:235], off
	v_lshl_add_u64 v[234:235], s[78:79], 0, v[168:169]
	s_add_i32 m0, s44, 0x2000
	s_nop 0
	global_load_lds_dwordx4 v[234:235], off
	v_lshl_add_u64 v[234:235], s[58:59], 0, v[164:165]
	s_mov_b32 m0, s49
	s_nop 0
	global_load_lds_dwordx4 v[234:235], off
	s_mov_b32 m0, s61
	s_nop 0
	global_load_lds_dwordx4 v[236:237], off
	s_waitcnt vmcnt(8)
	s_waitcnt lgkmcnt(0)
	s_barrier
; #define PG8_STAGE(bufoff, gbase, voff) do { _Pragma("unroll") for (int _i = 0; _i < 2; ++_i) \
;         __builtin_amdgcn_global_load_lds((const unsigned*)((const char*)(gbase) + (voff)[_i]), (PG8_LAS unsigned*)(lds + (bufoff) + ldsw + _i * 8192), 16, 0, 0); } while (0)
; #define PG8_LDA(dst, b, h) do { _Pragma("unroll") for (int m = 0; m < 4; ++m) _Pragma("unroll") for (int k = 0; k < 2; ++k) dst[m][k] = *(const PG8_LAS bf16x8*)(lds + PG8_SA(b, h) + aoff + m * 2048 + k * 1024); } while (0)
; #define PG8_LDB(dst, b, h) do { _Pragma("unroll") for (int n = 0; n < 2; ++n) _Pragma("unroll") for (int k = 0; k < 2; ++k) dst[n][k] = *(const PG8_LAS bf16x8*)(lds + PG8_SB(b, h) + boff + n * 2048 + k * 1024); } while (0)
; #define PG8_MMA(ai, bj, At, Bt) do { __builtin_amdgcn_s_setprio(1); _Pragma("unroll") for (int m = 0; m < 4; ++m) _Pragma("unroll") for (int n = 0; n < 2; ++n) _Pragma("unroll") for (int k = 0; k < 2; ++k) \
;         acc[ai][bj][m][n] = __builtin_amdgcn_mfma_f32_16x16x32_bf16(Bt[n][k], At[m][k], acc[ai][bj][m][n], 0, 0, 0); __builtin_amdgcn_s_setprio(0); } while (0)
; #define PG8_WAIT_V(n) asm volatile("s_waitcnt vmcnt(" #n ")" ::: "memory")
; #define PG8_WAIT_L(n) asm volatile("s_waitcnt lgkmcnt(" #n ")" ::: "memory")
; #define PG8_BAR __builtin_amdgcn_s_barrier()
; #define PG8_SCHED __builtin_amdgcn_sched_barrier(0)
; template <class Epi, class Sched, bool ALIGN_EPI = false, bool SP2 = false>
; __device__ __forceinline__ void gemm_phase(PG8_LAS unsigned char* lds, const Gemm g, const Sched& S, const Epi& E) {
;     ...
;             PG8_WAIT_V(8); PG8_WAIT_L(0); PG8_BAR; PG8_MMA(1, 0, At, B0); PG8_MMA(1, 1, At, B1); PG8_BAR; PG8_SCHED;
;             PG8_LDB(B0, 1, 0); PG8_LDB(B1, 1, 1); PG8_SCHED; PG8_LDA(At, 1, 0); PG8_STAGE(PG8_SA(0, 1), a2 + hstep, voffA);
;             PG8_WAIT_V(8); PG8_WAIT_L(0); PG8_BAR; PG8_MMA(0, 0, At, B0); PG8_MMA(0, 1, At, B1); PG8_BAR; PG8_SCHED;
	s_setprio 1
	s_waitcnt lgkmcnt(0)
	v_mfma_f32_16x16x32_bf16 v[56:59], v[88:91], v[178:181], v[56:59]
	v_mfma_f32_16x16x32_bf16 v[56:59], v[96:99], v[182:185], v[56:59]
	v_mfma_f32_16x16x32_bf16 v[48:51], v[140:143], v[182:185], v[48:51]
	v_mfma_f32_16x16x32_bf16 v[48:51], v[136:139], v[178:181], v[48:51]
	v_mfma_f32_16x16x32_bf16 v[60:63], v[144:147], v[178:181], v[60:63]
	v_mfma_f32_16x16x32_bf16 v[60:63], v[148:151], v[182:185], v[60:63]
	v_mfma_f32_16x16x32_bf16 v[52:55], v[156:159], v[182:185], v[52:55]
	v_mfma_f32_16x16x32_bf16 v[52:55], v[152:155], v[178:181], v[52:55]
	v_mfma_f32_16x16x32_bf16 v[32:35], v[152:155], v[186:189], v[32:35]
	v_mfma_f32_16x16x32_bf16 v[32:35], v[156:159], v[212:215], v[32:35]
	v_mfma_f32_16x16x32_bf16 v[40:43], v[148:151], v[212:215], v[40:43]
	v_mfma_f32_16x16x32_bf16 v[40:43], v[144:147], v[186:189], v[40:43]
	v_mfma_f32_16x16x32_bf16 v[36:39], v[136:139], v[186:189], v[36:39]
	v_mfma_f32_16x16x32_bf16 v[36:39], v[140:143], v[212:215], v[36:39]
	v_mfma_f32_16x16x32_bf16 v[44:47], v[96:99], v[212:215], v[44:47]
	v_mfma_f32_16x16x32_bf16 v[44:47], v[88:91], v[186:189], v[44:47]
	s_setprio 0
	s_setprio 1
	v_mfma_f32_16x16x32_bf16 v[28:31], v[88:91], v[216:219], v[28:31]
	v_mfma_f32_16x16x32_bf16 v[28:31], v[96:99], v[220:223], v[28:31]
	v_mfma_f32_16x16x32_bf16 v[20:23], v[140:143], v[220:223], v[20:23]
	v_mfma_f32_16x16x32_bf16 v[20:23], v[136:139], v[216:219], v[20:23]
	v_mfma_f32_16x16x32_bf16 v[24:27], v[144:147], v[216:219], v[24:27]
	v_mfma_f32_16x16x32_bf16 v[24:27], v[148:151], v[220:223], v[24:27]
	v_mfma_f32_16x16x32_bf16 v[16:19], v[156:159], v[220:223], v[16:19]
	v_mfma_f32_16x16x32_bf16 v[16:19], v[152:155], v[216:219], v[16:19]
	v_mfma_f32_16x16x32_bf16 v[0:3], v[152:155], v[224:227], v[0:3]
	v_mfma_f32_16x16x32_bf16 v[0:3], v[156:159], v[228:231], v[0:3]
	v_mfma_f32_16x16x32_bf16 v[8:11], v[148:151], v[228:231], v[8:11]
	v_mfma_f32_16x16x32_bf16 v[8:11], v[144:147], v[224:227], v[8:11]
	v_mfma_f32_16x16x32_bf16 v[4:7], v[136:139], v[224:227], v[4:7]
	v_mfma_f32_16x16x32_bf16 v[4:7], v[140:143], v[228:231], v[4:7]
	s_setprio 2
	s_barrier
	v_mfma_f32_16x16x32_bf16 v[12:15], v[96:99], v[228:231], v[12:15]
	v_mfma_f32_16x16x32_bf16 v[12:15], v[88:91], v[224:227], v[12:15]
	s_setprio 0
	s_add_i32 s44, 0, 0x18000
	s_add_i32 s45, 0, 0x1c000
	v_add_u32_e32 v140, s44, v163
	v_add_u32_e32 v156, s45, v163
	ds_read_b128 v[88:91], v140
	ds_read_b128 v[96:99], v140 offset:1024
	ds_read_b128 v[136:139], v140 offset:2048
	ds_read_b128 v[140:143], v140 offset:3072
	ds_read_b128 v[144:147], v156
	ds_read_b128 v[148:151], v156 offset:1024
	ds_read_b128 v[152:155], v156 offset:2048
	ds_read_b128 v[156:159], v156 offset:3072
	s_add_u32 s58, s58, 0x80000
	s_addc_u32 s59, s59, 0
	s_mov_b32 m0, s66
	v_lshl_add_u64 v[238:239], s[58:59], 0, v[164:165]
	ds_read_b128 v[178:181], v210 offset:32768
	ds_read_b128 v[182:185], v210 offset:33792
	ds_read_b128 v[186:189], v210 offset:34816
	ds_read_b128 v[212:215], v210 offset:35840
	ds_read_b128 v[216:219], v210 offset:36864
	ds_read_b128 v[220:223], v210 offset:37888
	ds_read_b128 v[224:227], v210 offset:38912
	ds_read_b128 v[228:231], v210 offset:39936
	global_load_lds_dwordx4 v[238:239], off
	v_lshl_add_u64 v[238:239], s[58:59], 0, v[168:169]
	s_mov_b32 m0, s67
	s_nop 0
	global_load_lds_dwordx4 v[238:239], off
	s_waitcnt vmcnt(8)
	s_waitcnt lgkmcnt(0)
	s_barrier
	s_setprio 1
	s_waitcnt lgkmcnt(0)
	v_mfma_f32_16x16x32_bf16 v[128:131], v[88:91], v[178:181], v[128:131]
	v_mfma_f32_16x16x32_bf16 v[128:131], v[96:99], v[182:185], v[128:131]
	v_mfma_f32_16x16x32_bf16 v[120:123], v[140:143], v[182:185], v[120:123]
	v_mfma_f32_16x16x32_bf16 v[120:123], v[136:139], v[178:181], v[120:123]
	v_mfma_f32_16x16x32_bf16 v[132:135], v[144:147], v[178:181], v[132:135]
	v_mfma_f32_16x16x32_bf16 v[132:135], v[148:151], v[182:185], v[132:135]
	v_mfma_f32_16x16x32_bf16 v[124:127], v[156:159], v[182:185], v[124:127]
	v_mfma_f32_16x16x32_bf16 v[124:127], v[152:155], v[178:181], v[124:127]
	v_mfma_f32_16x16x32_bf16 v[104:107], v[152:155], v[186:189], v[104:107]
	v_mfma_f32_16x16x32_bf16 v[104:107], v[156:159], v[212:215], v[104:107]
	v_mfma_f32_16x16x32_bf16 v[112:115], v[148:151], v[212:215], v[112:115]
	v_mfma_f32_16x16x32_bf16 v[112:115], v[144:147], v[186:189], v[112:115]
	v_mfma_f32_16x16x32_bf16 v[108:111], v[136:139], v[186:189], v[108:111]
	v_mfma_f32_16x16x32_bf16 v[108:111], v[140:143], v[212:215], v[108:111]
	v_mfma_f32_16x16x32_bf16 v[116:119], v[96:99], v[212:215], v[116:119]
	v_mfma_f32_16x16x32_bf16 v[116:119], v[88:91], v[186:189], v[116:119]
	s_setprio 0
	s_setprio 1
	v_mfma_f32_16x16x32_bf16 v[100:103], v[88:91], v[216:219], v[100:103]
	v_mfma_f32_16x16x32_bf16 v[100:103], v[96:99], v[220:223], v[100:103]
	v_mfma_f32_16x16x32_bf16 v[84:87], v[140:143], v[220:223], v[84:87]
	v_mfma_f32_16x16x32_bf16 v[84:87], v[136:139], v[216:219], v[84:87]
	v_mfma_f32_16x16x32_bf16 v[92:95], v[144:147], v[216:219], v[92:95]
	v_mfma_f32_16x16x32_bf16 v[92:95], v[148:151], v[220:223], v[92:95]
	v_mfma_f32_16x16x32_bf16 v[80:83], v[156:159], v[220:223], v[80:83]
	v_mfma_f32_16x16x32_bf16 v[80:83], v[152:155], v[216:219], v[80:83]
	v_mfma_f32_16x16x32_bf16 v[64:67], v[152:155], v[224:227], v[64:67]
	v_mfma_f32_16x16x32_bf16 v[64:67], v[156:159], v[228:231], v[64:67]
	v_mfma_f32_16x16x32_bf16 v[72:75], v[148:151], v[228:231], v[72:75]
	v_mfma_f32_16x16x32_bf16 v[72:75], v[144:147], v[224:227], v[72:75]
	v_mfma_f32_16x16x32_bf16 v[68:71], v[136:139], v[224:227], v[68:71]
	v_mfma_f32_16x16x32_bf16 v[68:71], v[140:143], v[228:231], v[68:71]
	s_setprio 2
	s_barrier
; #define PG8_STAGE(bufoff, gbase, voff) do { _Pragma("unroll") for (int _i = 0; _i < 2; ++_i) \
;         __builtin_amdgcn_global_load_lds((const unsigned*)((const char*)(gbase) + (voff)[_i]), (PG8_LAS unsigned*)(lds + (bufoff) + ldsw + _i * 8192), 16, 0, 0); } while (0)
; #define PG8_LDA(dst, b, h) do { _Pragma("unroll") for (int m = 0; m < 4; ++m) _Pragma("unroll") for (int k = 0; k < 2; ++k) dst[m][k] = *(const PG8_LAS bf16x8*)(lds + PG8_SA(b, h) + aoff + m * 2048 + k * 1024); } while (0)
; #define PG8_MMA(ai, bj, At, Bt) do { __builtin_amdgcn_s_setprio(1); _Pragma("unroll") for (int m = 0; m < 4; ++m) _Pragma("unroll") for (int n = 0; n < 2; ++n) _Pragma("unroll") for (int k = 0; k < 2; ++k) \
;         acc[ai][bj][m][n] = __builtin_amdgcn_mfma_f32_16x16x32_bf16(Bt[n][k], At[m][k], acc[ai][bj][m][n], 0, 0, 0); __builtin_amdgcn_s_setprio(0); } while (0)
; #define PG8_WAIT_V(n) asm volatile("s_waitcnt vmcnt(" #n ")" ::: "memory")
; #define PG8_WAIT_L(n) asm volatile("s_waitcnt lgkmcnt(" #n ")" ::: "memory")
; #define PG8_BAR __builtin_amdgcn_s_barrier()
; #define PG8_SCHED __builtin_amdgcn_sched_barrier(0)
; template <class Epi, class Sched, bool ALIGN_EPI = false, bool SP2 = false>
; __device__ __forceinline__ void gemm_phase(PG8_LAS unsigned char* lds, const Gemm g, const Sched& S, const Epi& E) {
;     ...
;         for (int t = 0; t < nt; t += 2) {
;     ...
;             PG8_WAIT_V(8); PG8_WAIT_L(0); PG8_BAR; PG8_MMA(0, 0, At, B0); PG8_MMA(0, 1, At, B1); PG8_BAR; PG8_SCHED;
;             PG8_LDA(At, 1, 1); PG8_STAGE(PG8_SB(1, 0), b3, voffB); PG8_STAGE(PG8_SB(1, 1), b3 + hstep, voffB); PG8_STAGE(PG8_SA(1, 0), a3, voffA);
;             PG8_WAIT_V(8); PG8_WAIT_L(0); PG8_BAR; PG8_MMA(1, 0, At, B0); PG8_MMA(1, 1, At, B1); PG8_BAR; PG8_SCHED;
	v_mfma_f32_16x16x32_bf16 v[76:79], v[96:99], v[228:231], v[76:79]
	v_mfma_f32_16x16x32_bf16 v[76:79], v[88:91], v[224:227], v[76:79]
	s_setprio 0
	s_add_i32 s44, s44, s65
	v_lshl_add_u64 v[200:201], v[200:201], 0, s[18:19]
	s_mov_b32 m0, s44
	ds_read_b128 v[178:181], v210 offset:49152
	ds_read_b128 v[182:185], v210 offset:50176
	ds_read_b128 v[186:189], v210 offset:51200
	ds_read_b128 v[212:215], v210 offset:52224
	ds_read_b128 v[216:219], v210 offset:53248
	ds_read_b128 v[220:223], v210 offset:54272
	ds_read_b128 v[224:227], v210 offset:55296
	ds_read_b128 v[228:231], v210 offset:56320
	global_load_lds_dwordx4 v[200:201], off
	s_add_i32 m0, s44, 0x2000
	s_add_u32 s56, s56, 0x80080
	v_lshl_add_u64 v[200:201], v[232:233], 0, s[18:19]
	s_addc_u32 s57, s57, 0
	s_add_i32 s44, s45, s65
	global_load_lds_dwordx4 v[200:201], off
	v_lshl_add_u64 v[200:201], s[56:57], 0, v[164:165]
	s_mov_b32 m0, s44
	s_nop 0
	global_load_lds_dwordx4 v[200:201], off
	v_lshl_add_u64 v[200:201], s[56:57], 0, v[168:169]
	s_add_i32 m0, s44, 0x2000
	s_nop 0
	global_load_lds_dwordx4 v[200:201], off
	v_lshl_add_u64 v[200:201], v[234:235], 0, s[18:19]
	s_mov_b32 m0, s68
	s_nop 0
	global_load_lds_dwordx4 v[200:201], off
	v_lshl_add_u64 v[200:201], v[236:237], 0, s[18:19]
	s_mov_b32 m0, s69
	s_nop 0
	global_load_lds_dwordx4 v[200:201], off
	s_waitcnt vmcnt(8)
	s_waitcnt lgkmcnt(0)
	s_barrier
	s_setprio 1
	s_waitcnt lgkmcnt(0)
	v_mfma_f32_16x16x32_bf16 v[56:59], v[88:91], v[178:181], v[56:59]
	v_mfma_f32_16x16x32_bf16 v[56:59], v[96:99], v[182:185], v[56:59]
	v_mfma_f32_16x16x32_bf16 v[48:51], v[140:143], v[182:185], v[48:51]
	v_mfma_f32_16x16x32_bf16 v[48:51], v[136:139], v[178:181], v[48:51]
	v_mfma_f32_16x16x32_bf16 v[60:63], v[144:147], v[178:181], v[60:63]
	v_mfma_f32_16x16x32_bf16 v[60:63], v[148:151], v[182:185], v[60:63]
	v_mfma_f32_16x16x32_bf16 v[52:55], v[156:159], v[182:185], v[52:55]
	v_mfma_f32_16x16x32_bf16 v[52:55], v[152:155], v[178:181], v[52:55]
	v_mfma_f32_16x16x32_bf16 v[32:35], v[152:155], v[186:189], v[32:35]
	v_mfma_f32_16x16x32_bf16 v[32:35], v[156:159], v[212:215], v[32:35]
	v_mfma_f32_16x16x32_bf16 v[40:43], v[148:151], v[212:215], v[40:43]
	v_mfma_f32_16x16x32_bf16 v[40:43], v[144:147], v[186:189], v[40:43]
	v_mfma_f32_16x16x32_bf16 v[36:39], v[136:139], v[186:189], v[36:39]
	v_mfma_f32_16x16x32_bf16 v[36:39], v[140:143], v[212:215], v[36:39]
	v_mfma_f32_16x16x32_bf16 v[44:47], v[96:99], v[212:215], v[44:47]
	v_mfma_f32_16x16x32_bf16 v[44:47], v[88:91], v[186:189], v[44:47]
	s_setprio 0
	s_setprio 1
	v_mfma_f32_16x16x32_bf16 v[28:31], v[88:91], v[216:219], v[28:31]
	v_mfma_f32_16x16x32_bf16 v[28:31], v[96:99], v[220:223], v[28:31]
	v_mfma_f32_16x16x32_bf16 v[20:23], v[140:143], v[220:223], v[20:23]
	v_mfma_f32_16x16x32_bf16 v[20:23], v[136:139], v[216:219], v[20:23]
	v_mfma_f32_16x16x32_bf16 v[24:27], v[144:147], v[216:219], v[24:27]
	v_mfma_f32_16x16x32_bf16 v[24:27], v[148:151], v[220:223], v[24:27]
	v_mfma_f32_16x16x32_bf16 v[16:19], v[156:159], v[220:223], v[16:19]
	v_mfma_f32_16x16x32_bf16 v[16:19], v[152:155], v[216:219], v[16:19]
	v_mfma_f32_16x16x32_bf16 v[0:3], v[152:155], v[224:227], v[0:3]
	v_mfma_f32_16x16x32_bf16 v[0:3], v[156:159], v[228:231], v[0:3]
	v_mfma_f32_16x16x32_bf16 v[8:11], v[148:151], v[228:231], v[8:11]
	v_mfma_f32_16x16x32_bf16 v[8:11], v[144:147], v[224:227], v[8:11]
	v_mfma_f32_16x16x32_bf16 v[4:7], v[136:139], v[224:227], v[4:7]
	v_mfma_f32_16x16x32_bf16 v[4:7], v[140:143], v[228:231], v[4:7]
	s_setprio 2
	s_barrier
	v_mfma_f32_16x16x32_bf16 v[12:15], v[96:99], v[228:231], v[12:15]
	v_mfma_f32_16x16x32_bf16 v[12:15], v[88:91], v[224:227], v[12:15]
	s_setprio 0
	s_add_i32 s76, s76, 2
	s_add_u32 s62, s62, 0x100
	s_addc_u32 s63, s63, 0
	s_add_u32 s74, s74, 0x100
	s_addc_u32 s75, s75, 0
	s_cmp_gt_u32 s76, 29
	s_cbranch_scc0 .LBB0_719
	s_and_b64 vcc, exec, s[20:21]
	s_cbranch_vccz .LBB0_722
	s_barrier

; #define PG8_STAGE(bufoff, gbase, voff) do { _Pragma("unroll") for (int _i = 0; _i < 2; ++_i) \
;         __builtin_amdgcn_global_load_lds((const unsigned*)((const char*)(gbase) + (voff)[_i]), (PG8_LAS unsigned*)(lds + (bufoff) + ldsw + _i * 8192), 16, 0, 0); } while (0)
; #define PG8_LDA(dst, b, h) do { _Pragma("unroll") for (int m = 0; m < 4; ++m) _Pragma("unroll") for (int k = 0; k < 2; ++k) dst[m][k] = *(const PG8_LAS bf16x8*)(lds + PG8_SA(b, h) + aoff + m * 2048 + k * 1024); } while (0)
; #define PG8_LDB(dst, b, h) do { _Pragma("unroll") for (int n = 0; n < 2; ++n) _Pragma("unroll") for (int k = 0; k < 2; ++k) dst[n][k] = *(const PG8_LAS bf16x8*)(lds + PG8_SB(b, h) + boff + n * 2048 + k * 1024); } while (0)
; #define PG8_MMA(ai, bj, At, Bt) do { __builtin_amdgcn_s_setprio(1); _Pragma("unroll") for (int m = 0; m < 4; ++m) _Pragma("unroll") for (int n = 0; n < 2; ++n) _Pragma("unroll") for (int k = 0; k < 2; ++k) \
;         acc[ai][bj][m][n] = __builtin_amdgcn_mfma_f32_16x16x32_bf16(Bt[n][k], At[m][k], acc[ai][bj][m][n], 0, 0, 0); __builtin_amdgcn_s_setprio(0); } while (0)
; #define PG8_WAIT_V(n) asm volatile("s_waitcnt vmcnt(" #n ")" ::: "memory")
; #define PG8_WAIT_L(n) asm volatile("s_waitcnt lgkmcnt(" #n ")" ::: "memory")
; #define PG8_BAR __builtin_amdgcn_s_barrier()
; #define PG8_SCHED __builtin_amdgcn_sched_barrier(0)
; template <class Epi, class Sched, bool ALIGN_EPI = false, bool SP2 = false>
; __device__ __forceinline__ void gemm_phase(PG8_LAS unsigned char* lds, const Gemm g, const Sched& S, const Epi& E) {
;     ...
;             PG8_LDB(B0, 0, 0); PG8_LDB(B1, 0, 1); PG8_SCHED; PG8_LDA(At, 0, 0); PG8_STAGE(PG8_SA(1, 1), a1 + hstep, voffA);
;             PG8_WAIT_V(8); PG8_WAIT_L(0); PG8_BAR; PG8_MMA(0, 0, At, B0); PG8_MMA(0, 1, At, B1); PG8_BAR; PG8_SCHED;
;             PG8_LDA(At, 0, 1); PG8_STAGE(PG8_SB(0, 0), b2, voffB); PG8_STAGE(PG8_SB(0, 1), b2 + hstep, voffB); PG8_STAGE(PG8_SA(0, 0), a2, voffA);
;             PG8_WAIT_V(8); PG8_WAIT_L(0); PG8_BAR; PG8_MMA(1, 0, At, B0); PG8_MMA(1, 1, At, B1); PG8_BAR; PG8_SCHED;
.LBB0_774:
	ds_read_b128 v[136:139], v156
	ds_read_b128 v[140:143], v156 offset:1024
	ds_read_b128 v[172:175], v156 offset:2048
	ds_read_b128 v[176:179], v156 offset:3072
	ds_read_b128 v[180:183], v157
	ds_read_b128 v[184:187], v157 offset:1024
	ds_read_b128 v[208:211], v157 offset:2048
	ds_read_b128 v[212:215], v157 offset:3072
	s_add_u32 s42, s40, 0xfff80080
	s_addc_u32 s43, s41, -1
	s_cmp_eq_u32 s71, 28
	s_cselect_b32 s49, s23, s43
	s_cselect_b32 s48, s34, s42
	s_cselect_b32 s43, s21, s70
	s_cselect_b32 s42, s35, s69
	v_lshl_add_u64 v[188:189], s[40:41], 0, v[128:129]
	s_add_i32 m0, s11, 0xc000
	ds_read_b128 v[216:219], v158
	ds_read_b128 v[220:223], v158 offset:1024
	ds_read_b128 v[224:227], v158 offset:2048
	ds_read_b128 v[228:231], v158 offset:3072
	ds_read_b128 v[232:235], v158 offset:4096
	ds_read_b128 v[236:239], v158 offset:5120
	ds_read_b128 v[240:243], v158 offset:6144
	ds_read_b128 v[244:247], v158 offset:7168
	global_load_lds_dwordx4 v[188:189], off
	v_lshl_add_u64 v[188:189], s[40:41], 0, v[130:131]
	s_add_i32 m0, s11, 0xe000
	s_nop 0
	global_load_lds_dwordx4 v[188:189], off
	s_waitcnt vmcnt(8)
	s_waitcnt lgkmcnt(0)
	s_barrier
	s_setprio 1
	s_waitcnt lgkmcnt(0)
	v_mfma_f32_16x16x32_bf16 v[124:127], v[136:139], v[216:219], v[124:127]
	v_mfma_f32_16x16x32_bf16 v[124:127], v[140:143], v[220:223], v[124:127]
	v_mfma_f32_16x16x32_bf16 v[120:123], v[176:179], v[220:223], v[120:123]
	v_mfma_f32_16x16x32_bf16 v[120:123], v[172:175], v[216:219], v[120:123]
	v_mfma_f32_16x16x32_bf16 v[116:119], v[180:183], v[216:219], v[116:119]
	v_mfma_f32_16x16x32_bf16 v[116:119], v[184:187], v[220:223], v[116:119]
	v_mfma_f32_16x16x32_bf16 v[112:115], v[212:215], v[220:223], v[112:115]
	v_mfma_f32_16x16x32_bf16 v[112:115], v[208:211], v[216:219], v[112:115]
	v_mfma_f32_16x16x32_bf16 v[92:95], v[208:211], v[224:227], v[92:95]
	v_mfma_f32_16x16x32_bf16 v[92:95], v[212:215], v[228:231], v[92:95]
	v_mfma_f32_16x16x32_bf16 v[100:103], v[184:187], v[228:231], v[100:103]
	v_mfma_f32_16x16x32_bf16 v[100:103], v[180:183], v[224:227], v[100:103]
	v_mfma_f32_16x16x32_bf16 v[104:107], v[172:175], v[224:227], v[104:107]
	v_mfma_f32_16x16x32_bf16 v[104:107], v[176:179], v[228:231], v[104:107]
	v_mfma_f32_16x16x32_bf16 v[108:111], v[140:143], v[228:231], v[108:111]
	v_mfma_f32_16x16x32_bf16 v[108:111], v[136:139], v[224:227], v[108:111]
	s_setprio 0
	s_setprio 1
	v_mfma_f32_16x16x32_bf16 v[96:99], v[136:139], v[232:235], v[96:99]
	v_mfma_f32_16x16x32_bf16 v[96:99], v[140:143], v[236:239], v[96:99]
	v_mfma_f32_16x16x32_bf16 v[88:91], v[176:179], v[236:239], v[88:91]
	v_mfma_f32_16x16x32_bf16 v[88:91], v[172:175], v[232:235], v[88:91]
	v_mfma_f32_16x16x32_bf16 v[84:87], v[180:183], v[232:235], v[84:87]
	v_mfma_f32_16x16x32_bf16 v[84:87], v[184:187], v[236:239], v[84:87]
	v_mfma_f32_16x16x32_bf16 v[76:79], v[212:215], v[236:239], v[76:79]
	v_mfma_f32_16x16x32_bf16 v[76:79], v[208:211], v[232:235], v[76:79]
	v_mfma_f32_16x16x32_bf16 v[64:67], v[208:211], v[240:243], v[64:67]
	v_mfma_f32_16x16x32_bf16 v[64:67], v[212:215], v[244:247], v[64:67]
	v_mfma_f32_16x16x32_bf16 v[68:71], v[184:187], v[244:247], v[68:71]
	v_mfma_f32_16x16x32_bf16 v[68:71], v[180:183], v[240:243], v[68:71]
	v_mfma_f32_16x16x32_bf16 v[72:75], v[172:175], v[240:243], v[72:75]
	v_mfma_f32_16x16x32_bf16 v[72:75], v[176:179], v[244:247], v[72:75]
	s_setprio 2
	s_barrier
	v_mfma_f32_16x16x32_bf16 v[80:83], v[140:143], v[244:247], v[80:83]
	v_mfma_f32_16x16x32_bf16 v[80:83], v[136:139], v[240:243], v[80:83]
	s_setprio 0
	s_add_i32 s44, s64, s52
	v_lshl_add_u64 v[188:189], s[42:43], 0, v[166:167]
	s_mov_b32 m0, s44
	ds_read_b128 v[216:219], v158 offset:16384
	ds_read_b128 v[220:223], v158 offset:17408
	ds_read_b128 v[224:227], v158 offset:18432
	ds_read_b128 v[228:231], v158 offset:19456
	ds_read_b128 v[232:235], v158 offset:20480
	ds_read_b128 v[236:239], v158 offset:21504
	ds_read_b128 v[240:243], v158 offset:22528
	ds_read_b128 v[244:247], v158 offset:23552
	global_load_lds_dwordx4 v[188:189], off
	s_add_i32 m0, s44, 0x2000
	s_add_u32 s72, s42, 0x80000
	v_lshl_add_u64 v[200:201], s[42:43], 0, v[170:171]
	s_addc_u32 s73, s43, 0
	s_add_i32 s44, s65, s52
	global_load_lds_dwordx4 v[200:201], off
	v_lshl_add_u64 v[248:249], s[72:73], 0, v[166:167]
	s_mov_b32 m0, s44
	v_lshl_add_u64 v[250:251], s[48:49], 0, v[168:169]
	global_load_lds_dwordx4 v[248:249], off
	v_lshl_add_u64 v[248:249], s[72:73], 0, v[170:171]
	s_add_i32 m0, s44, 0x2000
	s_nop 0
	global_load_lds_dwordx4 v[248:249], off
	v_lshl_add_u64 v[248:249], s[48:49], 0, v[164:165]
	s_mov_b32 m0, s11
	s_nop 0
	global_load_lds_dwordx4 v[248:249], off
	s_mov_b32 m0, s58
	s_nop 0
	global_load_lds_dwordx4 v[250:251], off
	s_waitcnt vmcnt(8)
	s_waitcnt lgkmcnt(0)
	s_barrier
; #define PG8_STAGE(bufoff, gbase, voff) do { _Pragma("unroll") for (int _i = 0; _i < 2; ++_i) \
;         __builtin_amdgcn_global_load_lds((const unsigned*)((const char*)(gbase) + (voff)[_i]), (PG8_LAS unsigned*)(lds + (bufoff) + ldsw + _i * 8192), 16, 0, 0); } while (0)
; #define PG8_LDA(dst, b, h) do { _Pragma("unroll") for (int m = 0; m < 4; ++m) _Pragma("unroll") for (int k = 0; k < 2; ++k) dst[m][k] = *(const PG8_LAS bf16x8*)(lds + PG8_SA(b, h) + aoff + m * 2048 + k * 1024); } while (0)
; #define PG8_LDB(dst, b, h) do { _Pragma("unroll") for (int n = 0; n < 2; ++n) _Pragma("unroll") for (int k = 0; k < 2; ++k) dst[n][k] = *(const PG8_LAS bf16x8*)(lds + PG8_SB(b, h) + boff + n * 2048 + k * 1024); } while (0)
; #define PG8_MMA(ai, bj, At, Bt) do { __builtin_amdgcn_s_setprio(1); _Pragma("unroll") for (int m = 0; m < 4; ++m) _Pragma("unroll") for (int n = 0; n < 2; ++n) _Pragma("unroll") for (int k = 0; k < 2; ++k) \
;         acc[ai][bj][m][n] = __builtin_amdgcn_mfma_f32_16x16x32_bf16(Bt[n][k], At[m][k], acc[ai][bj][m][n], 0, 0, 0); __builtin_amdgcn_s_setprio(0); } while (0)
; #define PG8_WAIT_V(n) asm volatile("s_waitcnt vmcnt(" #n ")" ::: "memory")
; #define PG8_WAIT_L(n) asm volatile("s_waitcnt lgkmcnt(" #n ")" ::: "memory")
; #define PG8_BAR __builtin_amdgcn_s_barrier()
; #define PG8_SCHED __builtin_amdgcn_sched_barrier(0)
; template <class Epi, class Sched, bool ALIGN_EPI = false, bool SP2 = false>
; __device__ __forceinline__ void gemm_phase(PG8_LAS unsigned char* lds, const Gemm g, const Sched& S, const Epi& E) {
;     ...
;             PG8_WAIT_V(8); PG8_WAIT_L(0); PG8_BAR; PG8_MMA(1, 0, At, B0); PG8_MMA(1, 1, At, B1); PG8_BAR; PG8_SCHED;
;             PG8_LDB(B0, 1, 0); PG8_LDB(B1, 1, 1); PG8_SCHED; PG8_LDA(At, 1, 0); PG8_STAGE(PG8_SA(0, 1), a2 + hstep, voffA);
;             PG8_WAIT_V(8); PG8_WAIT_L(0); PG8_BAR; PG8_MMA(0, 0, At, B0); PG8_MMA(0, 1, At, B1); PG8_BAR; PG8_SCHED;
	s_setprio 1
	s_waitcnt lgkmcnt(0)
	v_mfma_f32_16x16x32_bf16 v[60:63], v[136:139], v[216:219], v[60:63]
	v_mfma_f32_16x16x32_bf16 v[60:63], v[140:143], v[220:223], v[60:63]
	v_mfma_f32_16x16x32_bf16 v[56:59], v[176:179], v[220:223], v[56:59]
	v_mfma_f32_16x16x32_bf16 v[56:59], v[172:175], v[216:219], v[56:59]
	v_mfma_f32_16x16x32_bf16 v[52:55], v[180:183], v[216:219], v[52:55]
	v_mfma_f32_16x16x32_bf16 v[52:55], v[184:187], v[220:223], v[52:55]
	v_mfma_f32_16x16x32_bf16 v[44:47], v[212:215], v[220:223], v[44:47]
	v_mfma_f32_16x16x32_bf16 v[44:47], v[208:211], v[216:219], v[44:47]
	v_mfma_f32_16x16x32_bf16 v[28:31], v[208:211], v[224:227], v[28:31]
	v_mfma_f32_16x16x32_bf16 v[28:31], v[212:215], v[228:231], v[28:31]
	v_mfma_f32_16x16x32_bf16 v[36:39], v[184:187], v[228:231], v[36:39]
	v_mfma_f32_16x16x32_bf16 v[36:39], v[180:183], v[224:227], v[36:39]
	v_mfma_f32_16x16x32_bf16 v[40:43], v[172:175], v[224:227], v[40:43]
	v_mfma_f32_16x16x32_bf16 v[40:43], v[176:179], v[228:231], v[40:43]
	v_mfma_f32_16x16x32_bf16 v[48:51], v[140:143], v[228:231], v[48:51]
	v_mfma_f32_16x16x32_bf16 v[48:51], v[136:139], v[224:227], v[48:51]
	s_setprio 0
	s_setprio 1
	v_mfma_f32_16x16x32_bf16 v[32:35], v[136:139], v[232:235], v[32:35]
	v_mfma_f32_16x16x32_bf16 v[32:35], v[140:143], v[236:239], v[32:35]
	v_mfma_f32_16x16x32_bf16 v[24:27], v[176:179], v[236:239], v[24:27]
	v_mfma_f32_16x16x32_bf16 v[24:27], v[172:175], v[232:235], v[24:27]
	v_mfma_f32_16x16x32_bf16 v[20:23], v[180:183], v[232:235], v[20:23]
	v_mfma_f32_16x16x32_bf16 v[20:23], v[184:187], v[236:239], v[20:23]
	v_mfma_f32_16x16x32_bf16 v[16:19], v[212:215], v[236:239], v[16:19]
	v_mfma_f32_16x16x32_bf16 v[16:19], v[208:211], v[232:235], v[16:19]
	v_mfma_f32_16x16x32_bf16 v[0:3], v[208:211], v[240:243], v[0:3]
	v_mfma_f32_16x16x32_bf16 v[0:3], v[212:215], v[244:247], v[0:3]
	v_mfma_f32_16x16x32_bf16 v[4:7], v[184:187], v[244:247], v[4:7]
	v_mfma_f32_16x16x32_bf16 v[4:7], v[180:183], v[240:243], v[4:7]
	v_mfma_f32_16x16x32_bf16 v[8:11], v[172:175], v[240:243], v[8:11]
	v_mfma_f32_16x16x32_bf16 v[8:11], v[176:179], v[244:247], v[8:11]
	s_setprio 2
	s_barrier
	v_mfma_f32_16x16x32_bf16 v[12:15], v[140:143], v[244:247], v[12:15]
	v_mfma_f32_16x16x32_bf16 v[12:15], v[136:139], v[240:243], v[12:15]
	s_setprio 0
	s_add_i32 s44, 0, 0x18000
	v_add_u32_e32 v144, s44, v146
	s_add_i32 s45, 0, 0x1c000
	ds_read_b128 v[136:139], v144
	ds_read_b128 v[140:143], v144 offset:1024
	ds_read_b128 v[172:175], v144 offset:2048
	ds_read_b128 v[176:179], v144 offset:3072
	v_add_u32_e32 v144, s45, v146
	ds_read_b128 v[180:183], v144
	ds_read_b128 v[184:187], v144 offset:1024
	ds_read_b128 v[208:211], v144 offset:2048
	ds_read_b128 v[212:215], v144 offset:3072
	s_add_u32 s48, s48, 0x80000
	s_addc_u32 s49, s49, 0
	s_mov_b32 m0, s59
	v_lshl_add_u64 v[252:253], s[48:49], 0, v[164:165]
	ds_read_b128 v[216:219], v158 offset:32768
	ds_read_b128 v[220:223], v158 offset:33792
	ds_read_b128 v[224:227], v158 offset:34816
	ds_read_b128 v[228:231], v158 offset:35840
	ds_read_b128 v[232:235], v158 offset:36864
	ds_read_b128 v[236:239], v158 offset:37888
	ds_read_b128 v[240:243], v158 offset:38912
	ds_read_b128 v[244:247], v158 offset:39936
	global_load_lds_dwordx4 v[252:253], off
	v_lshl_add_u64 v[252:253], s[48:49], 0, v[168:169]
	s_mov_b32 m0, s60
	s_nop 0
	global_load_lds_dwordx4 v[252:253], off
	s_waitcnt vmcnt(8)
	s_waitcnt lgkmcnt(0)
	s_barrier
	s_setprio 1
	s_waitcnt lgkmcnt(0)
	v_mfma_f32_16x16x32_bf16 v[124:127], v[136:139], v[216:219], v[124:127]
	v_mfma_f32_16x16x32_bf16 v[124:127], v[140:143], v[220:223], v[124:127]
	v_mfma_f32_16x16x32_bf16 v[120:123], v[176:179], v[220:223], v[120:123]
	v_mfma_f32_16x16x32_bf16 v[120:123], v[172:175], v[216:219], v[120:123]
	v_mfma_f32_16x16x32_bf16 v[116:119], v[180:183], v[216:219], v[116:119]
	v_mfma_f32_16x16x32_bf16 v[116:119], v[184:187], v[220:223], v[116:119]
	v_mfma_f32_16x16x32_bf16 v[112:115], v[212:215], v[220:223], v[112:115]
	v_mfma_f32_16x16x32_bf16 v[112:115], v[208:211], v[216:219], v[112:115]
	v_mfma_f32_16x16x32_bf16 v[92:95], v[208:211], v[224:227], v[92:95]
	v_mfma_f32_16x16x32_bf16 v[92:95], v[212:215], v[228:231], v[92:95]
	v_mfma_f32_16x16x32_bf16 v[100:103], v[184:187], v[228:231], v[100:103]
	v_mfma_f32_16x16x32_bf16 v[100:103], v[180:183], v[224:227], v[100:103]
	v_mfma_f32_16x16x32_bf16 v[104:107], v[172:175], v[224:227], v[104:107]
	v_mfma_f32_16x16x32_bf16 v[104:107], v[176:179], v[228:231], v[104:107]
	v_mfma_f32_16x16x32_bf16 v[108:111], v[140:143], v[228:231], v[108:111]
	v_mfma_f32_16x16x32_bf16 v[108:111], v[136:139], v[224:227], v[108:111]
	s_setprio 0
	s_setprio 1
	v_mfma_f32_16x16x32_bf16 v[96:99], v[136:139], v[232:235], v[96:99]
	v_mfma_f32_16x16x32_bf16 v[96:99], v[140:143], v[236:239], v[96:99]
	v_mfma_f32_16x16x32_bf16 v[88:91], v[176:179], v[236:239], v[88:91]
	v_mfma_f32_16x16x32_bf16 v[88:91], v[172:175], v[232:235], v[88:91]
	v_mfma_f32_16x16x32_bf16 v[84:87], v[180:183], v[232:235], v[84:87]
	v_mfma_f32_16x16x32_bf16 v[84:87], v[184:187], v[236:239], v[84:87]
	v_mfma_f32_16x16x32_bf16 v[76:79], v[212:215], v[236:239], v[76:79]
	v_mfma_f32_16x16x32_bf16 v[76:79], v[208:211], v[232:235], v[76:79]
	v_mfma_f32_16x16x32_bf16 v[64:67], v[208:211], v[240:243], v[64:67]
	v_mfma_f32_16x16x32_bf16 v[64:67], v[212:215], v[244:247], v[64:67]
	v_mfma_f32_16x16x32_bf16 v[68:71], v[184:187], v[244:247], v[68:71]
	v_mfma_f32_16x16x32_bf16 v[68:71], v[180:183], v[240:243], v[68:71]
	v_mfma_f32_16x16x32_bf16 v[72:75], v[172:175], v[240:243], v[72:75]
	v_mfma_f32_16x16x32_bf16 v[72:75], v[176:179], v[244:247], v[72:75]
	s_setprio 2
	s_barrier
; #define PG8_STAGE(bufoff, gbase, voff) do { _Pragma("unroll") for (int _i = 0; _i < 2; ++_i) \
;         __builtin_amdgcn_global_load_lds((const unsigned*)((const char*)(gbase) + (voff)[_i]), (PG8_LAS unsigned*)(lds + (bufoff) + ldsw + _i * 8192), 16, 0, 0); } while (0)
; #define PG8_LDA(dst, b, h) do { _Pragma("unroll") for (int m = 0; m < 4; ++m) _Pragma("unroll") for (int k = 0; k < 2; ++k) dst[m][k] = *(const PG8_LAS bf16x8*)(lds + PG8_SA(b, h) + aoff + m * 2048 + k * 1024); } while (0)
; #define PG8_MMA(ai, bj, At, Bt) do { __builtin_amdgcn_s_setprio(1); _Pragma("unroll") for (int m = 0; m < 4; ++m) _Pragma("unroll") for (int n = 0; n < 2; ++n) _Pragma("unroll") for (int k = 0; k < 2; ++k) \
;         acc[ai][bj][m][n] = __builtin_amdgcn_mfma_f32_16x16x32_bf16(Bt[n][k], At[m][k], acc[ai][bj][m][n], 0, 0, 0); __builtin_amdgcn_s_setprio(0); } while (0)
; #define PG8_WAIT_V(n) asm volatile("s_waitcnt vmcnt(" #n ")" ::: "memory")
; #define PG8_WAIT_L(n) asm volatile("s_waitcnt lgkmcnt(" #n ")" ::: "memory")
; #define PG8_BAR __builtin_amdgcn_s_barrier()
; #define PG8_SCHED __builtin_amdgcn_sched_barrier(0)
; template <class Epi, class Sched, bool ALIGN_EPI = false, bool SP2 = false>
; __device__ __forceinline__ void gemm_phase(PG8_LAS unsigned char* lds, const Gemm g, const Sched& S, const Epi& E) {
;     ...
;         for (int t = 0; t < nt; t += 2) {
;     ...
;             PG8_WAIT_V(8); PG8_WAIT_L(0); PG8_BAR; PG8_MMA(0, 0, At, B0); PG8_MMA(0, 1, At, B1); PG8_BAR; PG8_SCHED;
;             PG8_LDA(At, 1, 1); PG8_STAGE(PG8_SB(1, 0), b3, voffB); PG8_STAGE(PG8_SB(1, 1), b3 + hstep, voffB); PG8_STAGE(PG8_SA(1, 0), a3, voffA);
;             PG8_WAIT_V(8); PG8_WAIT_L(0); PG8_BAR; PG8_MMA(1, 0, At, B0); PG8_MMA(1, 1, At, B1); PG8_BAR; PG8_SCHED;
	v_mfma_f32_16x16x32_bf16 v[80:83], v[140:143], v[244:247], v[80:83]
	v_mfma_f32_16x16x32_bf16 v[80:83], v[136:139], v[240:243], v[80:83]
	s_setprio 0
	s_add_i32 s44, s44, s52
	v_lshl_add_u64 v[188:189], v[188:189], 0, s[16:17]
	s_mov_b32 m0, s44
	ds_read_b128 v[216:219], v158 offset:49152
	ds_read_b128 v[220:223], v158 offset:50176
	ds_read_b128 v[224:227], v158 offset:51200
	ds_read_b128 v[228:231], v158 offset:52224
	ds_read_b128 v[232:235], v158 offset:53248
	ds_read_b128 v[236:239], v158 offset:54272
	ds_read_b128 v[240:243], v158 offset:55296
	ds_read_b128 v[244:247], v158 offset:56320
	global_load_lds_dwordx4 v[188:189], off
	s_add_i32 m0, s44, 0x2000
	s_add_u32 s42, s42, 0x80080
	v_lshl_add_u64 v[188:189], v[200:201], 0, s[16:17]
	s_addc_u32 s43, s43, 0
	s_add_i32 s44, s45, s52
	global_load_lds_dwordx4 v[188:189], off
	v_lshl_add_u64 v[188:189], s[42:43], 0, v[166:167]
	s_mov_b32 m0, s44
	s_nop 0
	global_load_lds_dwordx4 v[188:189], off
	v_lshl_add_u64 v[188:189], s[42:43], 0, v[170:171]
	s_add_i32 m0, s44, 0x2000
	s_nop 0
	global_load_lds_dwordx4 v[188:189], off
	v_lshl_add_u64 v[188:189], v[248:249], 0, s[16:17]
	s_mov_b32 m0, s62
	s_nop 0
	global_load_lds_dwordx4 v[188:189], off
	v_lshl_add_u64 v[188:189], v[250:251], 0, s[16:17]
	s_mov_b32 m0, s63
	s_nop 0
	global_load_lds_dwordx4 v[188:189], off
	s_waitcnt vmcnt(8)
	s_waitcnt lgkmcnt(0)
	s_barrier
	s_setprio 1
	s_waitcnt lgkmcnt(0)
	v_mfma_f32_16x16x32_bf16 v[60:63], v[136:139], v[216:219], v[60:63]
	v_mfma_f32_16x16x32_bf16 v[60:63], v[140:143], v[220:223], v[60:63]
	v_mfma_f32_16x16x32_bf16 v[56:59], v[176:179], v[220:223], v[56:59]
	v_mfma_f32_16x16x32_bf16 v[56:59], v[172:175], v[216:219], v[56:59]
	v_mfma_f32_16x16x32_bf16 v[52:55], v[180:183], v[216:219], v[52:55]
	v_mfma_f32_16x16x32_bf16 v[52:55], v[184:187], v[220:223], v[52:55]
	v_mfma_f32_16x16x32_bf16 v[44:47], v[212:215], v[220:223], v[44:47]
	v_mfma_f32_16x16x32_bf16 v[44:47], v[208:211], v[216:219], v[44:47]
	v_mfma_f32_16x16x32_bf16 v[28:31], v[208:211], v[224:227], v[28:31]
	v_mfma_f32_16x16x32_bf16 v[28:31], v[212:215], v[228:231], v[28:31]
	v_mfma_f32_16x16x32_bf16 v[36:39], v[184:187], v[228:231], v[36:39]
	v_mfma_f32_16x16x32_bf16 v[36:39], v[180:183], v[224:227], v[36:39]
	v_mfma_f32_16x16x32_bf16 v[40:43], v[172:175], v[224:227], v[40:43]
	v_mfma_f32_16x16x32_bf16 v[40:43], v[176:179], v[228:231], v[40:43]
	v_mfma_f32_16x16x32_bf16 v[48:51], v[140:143], v[228:231], v[48:51]
	v_mfma_f32_16x16x32_bf16 v[48:51], v[136:139], v[224:227], v[48:51]
	s_setprio 0
	s_setprio 1
	v_mfma_f32_16x16x32_bf16 v[32:35], v[136:139], v[232:235], v[32:35]
	v_mfma_f32_16x16x32_bf16 v[32:35], v[140:143], v[236:239], v[32:35]
	v_mfma_f32_16x16x32_bf16 v[24:27], v[176:179], v[236:239], v[24:27]
	v_mfma_f32_16x16x32_bf16 v[24:27], v[172:175], v[232:235], v[24:27]
	v_mfma_f32_16x16x32_bf16 v[20:23], v[180:183], v[232:235], v[20:23]
	v_mfma_f32_16x16x32_bf16 v[20:23], v[184:187], v[236:239], v[20:23]
	v_mfma_f32_16x16x32_bf16 v[16:19], v[212:215], v[236:239], v[16:19]
	v_mfma_f32_16x16x32_bf16 v[16:19], v[208:211], v[232:235], v[16:19]
	v_mfma_f32_16x16x32_bf16 v[0:3], v[208:211], v[240:243], v[0:3]
	v_mfma_f32_16x16x32_bf16 v[0:3], v[212:215], v[244:247], v[0:3]
	v_mfma_f32_16x16x32_bf16 v[4:7], v[184:187], v[244:247], v[4:7]
	v_mfma_f32_16x16x32_bf16 v[4:7], v[180:183], v[240:243], v[4:7]
	v_mfma_f32_16x16x32_bf16 v[8:11], v[172:175], v[240:243], v[8:11]
	v_mfma_f32_16x16x32_bf16 v[8:11], v[176:179], v[244:247], v[8:11]
	s_setprio 2
	s_barrier
	v_mfma_f32_16x16x32_bf16 v[12:15], v[140:143], v[244:247], v[12:15]
	v_mfma_f32_16x16x32_bf16 v[12:15], v[136:139], v[240:243], v[12:15]
	s_setprio 0
	s_add_i32 s71, s71, 2
	s_add_u32 s40, s40, 0x100
	s_addc_u32 s41, s41, 0
	s_add_u32 s69, s69, 0x100
	s_addc_u32 s70, s70, 0
	s_cmp_gt_u32 s71, 29
	s_cbranch_scc0 .LBB0_774
	s_and_b64 vcc, exec, s[18:19]
	s_cbranch_vccz .LBB0_777
	s_barrier

; #define PG8_STAGE(bufoff, gbase, voff) do { _Pragma("unroll") for (int _i = 0; _i < 2; ++_i) \
;         __builtin_amdgcn_global_load_lds((const unsigned*)((const char*)(gbase) + (voff)[_i]), (PG8_LAS unsigned*)(lds + (bufoff) + ldsw + _i * 8192), 16, 0, 0); } while (0)
; #define PG8_LDA(dst, b, h) do { _Pragma("unroll") for (int m = 0; m < 4; ++m) _Pragma("unroll") for (int k = 0; k < 2; ++k) dst[m][k] = *(const PG8_LAS bf16x8*)(lds + PG8_SA(b, h) + aoff + m * 2048 + k * 1024); } while (0)
; #define PG8_LDB(dst, b, h) do { _Pragma("unroll") for (int n = 0; n < 2; ++n) _Pragma("unroll") for (int k = 0; k < 2; ++k) dst[n][k] = *(const PG8_LAS bf16x8*)(lds + PG8_SB(b, h) + boff + n * 2048 + k * 1024); } while (0)
; #define PG8_MMA(ai, bj, At, Bt) do { __builtin_amdgcn_s_setprio(1); _Pragma("unroll") for (int m = 0; m < 4; ++m) _Pragma("unroll") for (int n = 0; n < 2; ++n) _Pragma("unroll") for (int k = 0; k < 2; ++k) \
;         acc[ai][bj][m][n] = __builtin_amdgcn_mfma_f32_16x16x32_bf16(Bt[n][k], At[m][k], acc[ai][bj][m][n], 0, 0, 0); __builtin_amdgcn_s_setprio(0); } while (0)
; #define PG8_WAIT_V(n) asm volatile("s_waitcnt vmcnt(" #n ")" ::: "memory")
; #define PG8_WAIT_L(n) asm volatile("s_waitcnt lgkmcnt(" #n ")" ::: "memory")
; #define PG8_BAR __builtin_amdgcn_s_barrier()
; #define PG8_SCHED __builtin_amdgcn_sched_barrier(0)
; template <class Epi, class Sched, bool ALIGN_EPI = false, bool SP2 = false>
; __device__ __forceinline__ void gemm_phase(PG8_LAS unsigned char* lds, const Gemm g, const Sched& S, const Epi& E) {
;     ...
;             PG8_LDB(B0, 0, 0); PG8_LDB(B1, 0, 1); PG8_SCHED; PG8_LDA(At, 0, 0); PG8_STAGE(PG8_SA(1, 1), a1 + hstep, voffA);
;             PG8_WAIT_V(8); PG8_WAIT_L(0); PG8_BAR; PG8_MMA(0, 0, At, B0); PG8_MMA(0, 1, At, B1); PG8_BAR; PG8_SCHED;
;             PG8_LDA(At, 0, 1); PG8_STAGE(PG8_SB(0, 0), b2, voffB); PG8_STAGE(PG8_SB(0, 1), b2 + hstep, voffB); PG8_STAGE(PG8_SA(0, 0), a2, voffA);
;             PG8_WAIT_V(8); PG8_WAIT_L(0); PG8_BAR; PG8_MMA(1, 0, At, B0); PG8_MMA(1, 1, At, B1); PG8_BAR; PG8_SCHED;
.LBB0_837:
	ds_read_b128 v[134:137], v143
	ds_read_b128 v[146:149], v143 offset:1024
	ds_read_b128 v[150:153], v143 offset:2048
	ds_read_b128 v[154:157], v143 offset:3072
	ds_read_b128 v[172:175], v144
	ds_read_b128 v[176:179], v144 offset:1024
	ds_read_b128 v[180:183], v144 offset:2048
	ds_read_b128 v[184:187], v144 offset:3072
	s_add_u32 s44, s42, 0xffea0080
	s_addc_u32 s45, s43, -1
	s_cmpk_eq_i32 s75, 0x54
	s_cselect_b32 s53, s39, s45
	s_cselect_b32 s52, s38, s44
	s_cselect_b32 s49, s41, s35
	s_cselect_b32 s48, s40, s34
	v_lshl_add_u64 v[138:139], s[42:43], 0, v[128:129]
	s_add_i32 m0, s61, 0xc000
	ds_read_b128 v[208:211], v145
	ds_read_b128 v[212:215], v145 offset:1024
	ds_read_b128 v[216:219], v145 offset:2048
	ds_read_b128 v[220:223], v145 offset:3072
	ds_read_b128 v[224:227], v145 offset:4096
	ds_read_b128 v[228:231], v145 offset:5120
	ds_read_b128 v[232:235], v145 offset:6144
	ds_read_b128 v[236:239], v145 offset:7168
	global_load_lds_dwordx4 v[138:139], off
	v_lshl_add_u64 v[138:139], s[42:43], 0, v[130:131]
	s_add_i32 m0, s61, 0xe000
	s_nop 0
	global_load_lds_dwordx4 v[138:139], off
	s_waitcnt vmcnt(8)
	s_waitcnt lgkmcnt(0)
	s_barrier
	s_setprio 1
	s_waitcnt lgkmcnt(0)
	v_mfma_f32_16x16x32_bf16 v[124:127], v[134:137], v[208:211], v[124:127]
	v_mfma_f32_16x16x32_bf16 v[124:127], v[146:149], v[212:215], v[124:127]
	v_mfma_f32_16x16x32_bf16 v[120:123], v[154:157], v[212:215], v[120:123]
	v_mfma_f32_16x16x32_bf16 v[120:123], v[150:153], v[208:211], v[120:123]
	v_mfma_f32_16x16x32_bf16 v[108:111], v[172:175], v[208:211], v[108:111]
	v_mfma_f32_16x16x32_bf16 v[108:111], v[176:179], v[212:215], v[108:111]
	v_mfma_f32_16x16x32_bf16 v[104:107], v[184:187], v[212:215], v[104:107]
	v_mfma_f32_16x16x32_bf16 v[104:107], v[180:183], v[208:211], v[104:107]
	v_mfma_f32_16x16x32_bf16 v[96:99], v[180:183], v[216:219], v[96:99]
	v_mfma_f32_16x16x32_bf16 v[96:99], v[184:187], v[220:223], v[96:99]
	v_mfma_f32_16x16x32_bf16 v[100:103], v[176:179], v[220:223], v[100:103]
	v_mfma_f32_16x16x32_bf16 v[100:103], v[172:175], v[216:219], v[100:103]
	v_mfma_f32_16x16x32_bf16 v[112:115], v[150:153], v[216:219], v[112:115]
	v_mfma_f32_16x16x32_bf16 v[112:115], v[154:157], v[220:223], v[112:115]
	v_mfma_f32_16x16x32_bf16 v[116:119], v[146:149], v[220:223], v[116:119]
	v_mfma_f32_16x16x32_bf16 v[116:119], v[134:137], v[216:219], v[116:119]
	s_setprio 0
	s_setprio 1
	v_mfma_f32_16x16x32_bf16 v[92:95], v[134:137], v[224:227], v[92:95]
	v_mfma_f32_16x16x32_bf16 v[92:95], v[146:149], v[228:231], v[92:95]
	v_mfma_f32_16x16x32_bf16 v[88:91], v[154:157], v[228:231], v[88:91]
	v_mfma_f32_16x16x32_bf16 v[88:91], v[150:153], v[224:227], v[88:91]
	v_mfma_f32_16x16x32_bf16 v[76:79], v[172:175], v[224:227], v[76:79]
	v_mfma_f32_16x16x32_bf16 v[76:79], v[176:179], v[228:231], v[76:79]
	v_mfma_f32_16x16x32_bf16 v[72:75], v[184:187], v[228:231], v[72:75]
	v_mfma_f32_16x16x32_bf16 v[72:75], v[180:183], v[224:227], v[72:75]
	v_mfma_f32_16x16x32_bf16 v[64:67], v[180:183], v[232:235], v[64:67]
	v_mfma_f32_16x16x32_bf16 v[64:67], v[184:187], v[236:239], v[64:67]
	v_mfma_f32_16x16x32_bf16 v[68:71], v[176:179], v[236:239], v[68:71]
	v_mfma_f32_16x16x32_bf16 v[68:71], v[172:175], v[232:235], v[68:71]
	v_mfma_f32_16x16x32_bf16 v[80:83], v[150:153], v[232:235], v[80:83]
	v_mfma_f32_16x16x32_bf16 v[80:83], v[154:157], v[236:239], v[80:83]
	s_setprio 2
	s_barrier
	v_mfma_f32_16x16x32_bf16 v[84:87], v[146:149], v[236:239], v[84:87]
	v_mfma_f32_16x16x32_bf16 v[84:87], v[134:137], v[232:235], v[84:87]
	s_setprio 0
	s_add_i32 s44, s68, s60
	v_lshl_add_u64 v[138:139], s[48:49], 0, v[160:161]
	s_mov_b32 m0, s44
	ds_read_b128 v[208:211], v145 offset:16384
	ds_read_b128 v[212:215], v145 offset:17408
	ds_read_b128 v[216:219], v145 offset:18432
	ds_read_b128 v[220:223], v145 offset:19456
	ds_read_b128 v[224:227], v145 offset:20480
	ds_read_b128 v[228:231], v145 offset:21504
	ds_read_b128 v[232:235], v145 offset:22528
	ds_read_b128 v[236:239], v145 offset:23552
	global_load_lds_dwordx4 v[138:139], off
	s_add_i32 m0, s44, 0x2000
	s_add_u32 s76, s48, 0x160000
	v_lshl_add_u64 v[158:159], s[48:49], 0, v[162:163]
	s_addc_u32 s77, s49, 0
	s_add_i32 s44, s69, s60
	global_load_lds_dwordx4 v[158:159], off
	v_lshl_add_u64 v[188:189], s[76:77], 0, v[160:161]
	s_mov_b32 m0, s44
	v_lshl_add_u64 v[200:201], s[52:53], 0, v[162:163]
	global_load_lds_dwordx4 v[188:189], off
	v_lshl_add_u64 v[188:189], s[76:77], 0, v[162:163]
	s_add_i32 m0, s44, 0x2000
	s_nop 0
	global_load_lds_dwordx4 v[188:189], off
	v_lshl_add_u64 v[188:189], s[52:53], 0, v[160:161]
	s_mov_b32 m0, s61
	s_nop 0
	global_load_lds_dwordx4 v[188:189], off
	s_mov_b32 m0, s62
	s_nop 0
	global_load_lds_dwordx4 v[200:201], off
	s_waitcnt vmcnt(8)
	s_waitcnt lgkmcnt(0)
	s_barrier
; #define PG8_STAGE(bufoff, gbase, voff) do { _Pragma("unroll") for (int _i = 0; _i < 2; ++_i) \
;         __builtin_amdgcn_global_load_lds((const unsigned*)((const char*)(gbase) + (voff)[_i]), (PG8_LAS unsigned*)(lds + (bufoff) + ldsw + _i * 8192), 16, 0, 0); } while (0)
; #define PG8_LDA(dst, b, h) do { _Pragma("unroll") for (int m = 0; m < 4; ++m) _Pragma("unroll") for (int k = 0; k < 2; ++k) dst[m][k] = *(const PG8_LAS bf16x8*)(lds + PG8_SA(b, h) + aoff + m * 2048 + k * 1024); } while (0)
; #define PG8_LDB(dst, b, h) do { _Pragma("unroll") for (int n = 0; n < 2; ++n) _Pragma("unroll") for (int k = 0; k < 2; ++k) dst[n][k] = *(const PG8_LAS bf16x8*)(lds + PG8_SB(b, h) + boff + n * 2048 + k * 1024); } while (0)
; #define PG8_MMA(ai, bj, At, Bt) do { __builtin_amdgcn_s_setprio(1); _Pragma("unroll") for (int m = 0; m < 4; ++m) _Pragma("unroll") for (int n = 0; n < 2; ++n) _Pragma("unroll") for (int k = 0; k < 2; ++k) \
;         acc[ai][bj][m][n] = __builtin_amdgcn_mfma_f32_16x16x32_bf16(Bt[n][k], At[m][k], acc[ai][bj][m][n], 0, 0, 0); __builtin_amdgcn_s_setprio(0); } while (0)
; #define PG8_WAIT_V(n) asm volatile("s_waitcnt vmcnt(" #n ")" ::: "memory")
; #define PG8_WAIT_L(n) asm volatile("s_waitcnt lgkmcnt(" #n ")" ::: "memory")
; #define PG8_BAR __builtin_amdgcn_s_barrier()
; #define PG8_SCHED __builtin_amdgcn_sched_barrier(0)
; template <class Epi, class Sched, bool ALIGN_EPI = false, bool SP2 = false>
; __device__ __forceinline__ void gemm_phase(PG8_LAS unsigned char* lds, const Gemm g, const Sched& S, const Epi& E) {
;     ...
;             PG8_WAIT_V(8); PG8_WAIT_L(0); PG8_BAR; PG8_MMA(1, 0, At, B0); PG8_MMA(1, 1, At, B1); PG8_BAR; PG8_SCHED;
;             PG8_LDB(B0, 1, 0); PG8_LDB(B1, 1, 1); PG8_SCHED; PG8_LDA(At, 1, 0); PG8_STAGE(PG8_SA(0, 1), a2 + hstep, voffA);
;             PG8_WAIT_V(8); PG8_WAIT_L(0); PG8_BAR; PG8_MMA(0, 0, At, B0); PG8_MMA(0, 1, At, B1); PG8_BAR; PG8_SCHED;
	s_setprio 1
	s_waitcnt lgkmcnt(0)
	v_mfma_f32_16x16x32_bf16 v[60:63], v[134:137], v[208:211], v[60:63]
	v_mfma_f32_16x16x32_bf16 v[60:63], v[146:149], v[212:215], v[60:63]
	v_mfma_f32_16x16x32_bf16 v[56:59], v[154:157], v[212:215], v[56:59]
	v_mfma_f32_16x16x32_bf16 v[56:59], v[150:153], v[208:211], v[56:59]
	v_mfma_f32_16x16x32_bf16 v[44:47], v[172:175], v[208:211], v[44:47]
	v_mfma_f32_16x16x32_bf16 v[44:47], v[176:179], v[212:215], v[44:47]
	v_mfma_f32_16x16x32_bf16 v[40:43], v[184:187], v[212:215], v[40:43]
	v_mfma_f32_16x16x32_bf16 v[40:43], v[180:183], v[208:211], v[40:43]
	v_mfma_f32_16x16x32_bf16 v[32:35], v[180:183], v[216:219], v[32:35]
	v_mfma_f32_16x16x32_bf16 v[32:35], v[184:187], v[220:223], v[32:35]
	v_mfma_f32_16x16x32_bf16 v[36:39], v[176:179], v[220:223], v[36:39]
	v_mfma_f32_16x16x32_bf16 v[36:39], v[172:175], v[216:219], v[36:39]
	v_mfma_f32_16x16x32_bf16 v[48:51], v[150:153], v[216:219], v[48:51]
	v_mfma_f32_16x16x32_bf16 v[48:51], v[154:157], v[220:223], v[48:51]
	v_mfma_f32_16x16x32_bf16 v[52:55], v[146:149], v[220:223], v[52:55]
	v_mfma_f32_16x16x32_bf16 v[52:55], v[134:137], v[216:219], v[52:55]
	s_setprio 0
	s_setprio 1
	v_mfma_f32_16x16x32_bf16 v[28:31], v[134:137], v[224:227], v[28:31]
	v_mfma_f32_16x16x32_bf16 v[28:31], v[146:149], v[228:231], v[28:31]
	v_mfma_f32_16x16x32_bf16 v[24:27], v[154:157], v[228:231], v[24:27]
	v_mfma_f32_16x16x32_bf16 v[24:27], v[150:153], v[224:227], v[24:27]
	v_mfma_f32_16x16x32_bf16 v[12:15], v[172:175], v[224:227], v[12:15]
	v_mfma_f32_16x16x32_bf16 v[12:15], v[176:179], v[228:231], v[12:15]
	v_mfma_f32_16x16x32_bf16 v[8:11], v[184:187], v[228:231], v[8:11]
	v_mfma_f32_16x16x32_bf16 v[8:11], v[180:183], v[224:227], v[8:11]
	v_mfma_f32_16x16x32_bf16 v[0:3], v[180:183], v[232:235], v[0:3]
	v_mfma_f32_16x16x32_bf16 v[0:3], v[184:187], v[236:239], v[0:3]
	v_mfma_f32_16x16x32_bf16 v[4:7], v[176:179], v[236:239], v[4:7]
	v_mfma_f32_16x16x32_bf16 v[4:7], v[172:175], v[232:235], v[4:7]
	v_mfma_f32_16x16x32_bf16 v[16:19], v[150:153], v[232:235], v[16:19]
	v_mfma_f32_16x16x32_bf16 v[16:19], v[154:157], v[236:239], v[16:19]
	s_setprio 2
	s_barrier
	v_mfma_f32_16x16x32_bf16 v[20:23], v[146:149], v[236:239], v[20:23]
	v_mfma_f32_16x16x32_bf16 v[20:23], v[134:137], v[232:235], v[20:23]
	s_setprio 0
	s_add_i32 s44, 0, 0x18000
	s_add_i32 s45, 0, 0x1c000
	v_add_u32_e32 v154, s44, v141
	v_add_u32_e32 v165, s45, v141
	ds_read_b128 v[134:137], v154
	ds_read_b128 v[146:149], v154 offset:1024
	ds_read_b128 v[150:153], v154 offset:2048
	ds_read_b128 v[154:157], v154 offset:3072
	ds_read_b128 v[172:175], v165
	ds_read_b128 v[176:179], v165 offset:1024
	ds_read_b128 v[180:183], v165 offset:2048
	ds_read_b128 v[184:187], v165 offset:3072
	s_add_u32 s52, s52, 0x160000
	s_addc_u32 s53, s53, 0
	s_mov_b32 m0, s63
	v_lshl_add_u64 v[240:241], s[52:53], 0, v[160:161]
	ds_read_b128 v[208:211], v145 offset:32768
	ds_read_b128 v[212:215], v145 offset:33792
	ds_read_b128 v[216:219], v145 offset:34816
	ds_read_b128 v[220:223], v145 offset:35840
	ds_read_b128 v[224:227], v145 offset:36864
	ds_read_b128 v[228:231], v145 offset:37888
	ds_read_b128 v[232:235], v145 offset:38912
	ds_read_b128 v[236:239], v145 offset:39936
	global_load_lds_dwordx4 v[240:241], off
	v_lshl_add_u64 v[240:241], s[52:53], 0, v[162:163]
	s_mov_b32 m0, s64
	s_nop 0
	global_load_lds_dwordx4 v[240:241], off
	s_waitcnt vmcnt(8)
	s_waitcnt lgkmcnt(0)
	s_barrier
	s_setprio 1
	s_waitcnt lgkmcnt(0)
	v_mfma_f32_16x16x32_bf16 v[124:127], v[134:137], v[208:211], v[124:127]
	v_mfma_f32_16x16x32_bf16 v[124:127], v[146:149], v[212:215], v[124:127]
	v_mfma_f32_16x16x32_bf16 v[120:123], v[154:157], v[212:215], v[120:123]
	v_mfma_f32_16x16x32_bf16 v[120:123], v[150:153], v[208:211], v[120:123]
	v_mfma_f32_16x16x32_bf16 v[108:111], v[172:175], v[208:211], v[108:111]
	v_mfma_f32_16x16x32_bf16 v[108:111], v[176:179], v[212:215], v[108:111]
	v_mfma_f32_16x16x32_bf16 v[104:107], v[184:187], v[212:215], v[104:107]
	v_mfma_f32_16x16x32_bf16 v[104:107], v[180:183], v[208:211], v[104:107]
	v_mfma_f32_16x16x32_bf16 v[96:99], v[180:183], v[216:219], v[96:99]
	v_mfma_f32_16x16x32_bf16 v[96:99], v[184:187], v[220:223], v[96:99]
	v_mfma_f32_16x16x32_bf16 v[100:103], v[176:179], v[220:223], v[100:103]
	v_mfma_f32_16x16x32_bf16 v[100:103], v[172:175], v[216:219], v[100:103]
	v_mfma_f32_16x16x32_bf16 v[112:115], v[150:153], v[216:219], v[112:115]
	v_mfma_f32_16x16x32_bf16 v[112:115], v[154:157], v[220:223], v[112:115]
	v_mfma_f32_16x16x32_bf16 v[116:119], v[146:149], v[220:223], v[116:119]
	v_mfma_f32_16x16x32_bf16 v[116:119], v[134:137], v[216:219], v[116:119]
	s_setprio 0
	s_setprio 1
	v_mfma_f32_16x16x32_bf16 v[92:95], v[134:137], v[224:227], v[92:95]
	v_mfma_f32_16x16x32_bf16 v[92:95], v[146:149], v[228:231], v[92:95]
	v_mfma_f32_16x16x32_bf16 v[88:91], v[154:157], v[228:231], v[88:91]
	v_mfma_f32_16x16x32_bf16 v[88:91], v[150:153], v[224:227], v[88:91]
	v_mfma_f32_16x16x32_bf16 v[76:79], v[172:175], v[224:227], v[76:79]
	v_mfma_f32_16x16x32_bf16 v[76:79], v[176:179], v[228:231], v[76:79]
	v_mfma_f32_16x16x32_bf16 v[72:75], v[184:187], v[228:231], v[72:75]
	v_mfma_f32_16x16x32_bf16 v[72:75], v[180:183], v[224:227], v[72:75]
	v_mfma_f32_16x16x32_bf16 v[64:67], v[180:183], v[232:235], v[64:67]
	v_mfma_f32_16x16x32_bf16 v[64:67], v[184:187], v[236:239], v[64:67]
	v_mfma_f32_16x16x32_bf16 v[68:71], v[176:179], v[236:239], v[68:71]
	v_mfma_f32_16x16x32_bf16 v[68:71], v[172:175], v[232:235], v[68:71]
	v_mfma_f32_16x16x32_bf16 v[80:83], v[150:153], v[232:235], v[80:83]
	v_mfma_f32_16x16x32_bf16 v[80:83], v[154:157], v[236:239], v[80:83]
	s_setprio 2
	s_barrier
; #define PG8_STAGE(bufoff, gbase, voff) do { _Pragma("unroll") for (int _i = 0; _i < 2; ++_i) \
;         __builtin_amdgcn_global_load_lds((const unsigned*)((const char*)(gbase) + (voff)[_i]), (PG8_LAS unsigned*)(lds + (bufoff) + ldsw + _i * 8192), 16, 0, 0); } while (0)
; #define PG8_LDA(dst, b, h) do { _Pragma("unroll") for (int m = 0; m < 4; ++m) _Pragma("unroll") for (int k = 0; k < 2; ++k) dst[m][k] = *(const PG8_LAS bf16x8*)(lds + PG8_SA(b, h) + aoff + m * 2048 + k * 1024); } while (0)
; #define PG8_MMA(ai, bj, At, Bt) do { __builtin_amdgcn_s_setprio(1); _Pragma("unroll") for (int m = 0; m < 4; ++m) _Pragma("unroll") for (int n = 0; n < 2; ++n) _Pragma("unroll") for (int k = 0; k < 2; ++k) \
;         acc[ai][bj][m][n] = __builtin_amdgcn_mfma_f32_16x16x32_bf16(Bt[n][k], At[m][k], acc[ai][bj][m][n], 0, 0, 0); __builtin_amdgcn_s_setprio(0); } while (0)
; #define PG8_WAIT_V(n) asm volatile("s_waitcnt vmcnt(" #n ")" ::: "memory")
; #define PG8_WAIT_L(n) asm volatile("s_waitcnt lgkmcnt(" #n ")" ::: "memory")
; #define PG8_BAR __builtin_amdgcn_s_barrier()
; #define PG8_SCHED __builtin_amdgcn_sched_barrier(0)
; template <class Epi, class Sched, bool ALIGN_EPI = false, bool SP2 = false>
; __device__ __forceinline__ void gemm_phase(PG8_LAS unsigned char* lds, const Gemm g, const Sched& S, const Epi& E) {
;     ...
;         for (int t = 0; t < nt; t += 2) {
;     ...
;             PG8_WAIT_V(8); PG8_WAIT_L(0); PG8_BAR; PG8_MMA(0, 0, At, B0); PG8_MMA(0, 1, At, B1); PG8_BAR; PG8_SCHED;
;             PG8_LDA(At, 1, 1); PG8_STAGE(PG8_SB(1, 0), b3, voffB); PG8_STAGE(PG8_SB(1, 1), b3 + hstep, voffB); PG8_STAGE(PG8_SA(1, 0), a3, voffA);
;             PG8_WAIT_V(8); PG8_WAIT_L(0); PG8_BAR; PG8_MMA(1, 0, At, B0); PG8_MMA(1, 1, At, B1); PG8_BAR; PG8_SCHED;
	v_mfma_f32_16x16x32_bf16 v[84:87], v[146:149], v[236:239], v[84:87]
	v_mfma_f32_16x16x32_bf16 v[84:87], v[134:137], v[232:235], v[84:87]
	s_setprio 0
	s_add_i32 s44, s44, s60
	v_lshl_add_u64 v[138:139], v[138:139], 0, s[16:17]
	s_mov_b32 m0, s44
	ds_read_b128 v[208:211], v145 offset:49152
	ds_read_b128 v[212:215], v145 offset:50176
	ds_read_b128 v[216:219], v145 offset:51200
	ds_read_b128 v[220:223], v145 offset:52224
	ds_read_b128 v[224:227], v145 offset:53248
	ds_read_b128 v[228:231], v145 offset:54272
	ds_read_b128 v[232:235], v145 offset:55296
	ds_read_b128 v[236:239], v145 offset:56320
	global_load_lds_dwordx4 v[138:139], off
	s_add_i32 m0, s44, 0x2000
	s_add_u32 s48, s48, 0x160080
	v_lshl_add_u64 v[138:139], v[158:159], 0, s[16:17]
	s_addc_u32 s49, s49, 0
	s_add_i32 s44, s45, s60
	global_load_lds_dwordx4 v[138:139], off
	v_lshl_add_u64 v[138:139], s[48:49], 0, v[160:161]
	s_mov_b32 m0, s44
	s_nop 0
	global_load_lds_dwordx4 v[138:139], off
	v_lshl_add_u64 v[138:139], s[48:49], 0, v[162:163]
	s_add_i32 m0, s44, 0x2000
	s_nop 0
	global_load_lds_dwordx4 v[138:139], off
	v_lshl_add_u64 v[138:139], v[188:189], 0, s[16:17]
	s_mov_b32 m0, s65
	s_nop 0
	global_load_lds_dwordx4 v[138:139], off
	v_lshl_add_u64 v[138:139], v[200:201], 0, s[16:17]
	s_mov_b32 m0, s66
	s_nop 0
	global_load_lds_dwordx4 v[138:139], off
	s_waitcnt vmcnt(8)
	s_waitcnt lgkmcnt(0)
	s_barrier
	s_setprio 1
	s_waitcnt lgkmcnt(0)
	v_mfma_f32_16x16x32_bf16 v[60:63], v[134:137], v[208:211], v[60:63]
	v_mfma_f32_16x16x32_bf16 v[60:63], v[146:149], v[212:215], v[60:63]
	v_mfma_f32_16x16x32_bf16 v[56:59], v[154:157], v[212:215], v[56:59]
	v_mfma_f32_16x16x32_bf16 v[56:59], v[150:153], v[208:211], v[56:59]
	v_mfma_f32_16x16x32_bf16 v[44:47], v[172:175], v[208:211], v[44:47]
	v_mfma_f32_16x16x32_bf16 v[44:47], v[176:179], v[212:215], v[44:47]
	v_mfma_f32_16x16x32_bf16 v[40:43], v[184:187], v[212:215], v[40:43]
	v_mfma_f32_16x16x32_bf16 v[40:43], v[180:183], v[208:211], v[40:43]
	v_mfma_f32_16x16x32_bf16 v[32:35], v[180:183], v[216:219], v[32:35]
	v_mfma_f32_16x16x32_bf16 v[32:35], v[184:187], v[220:223], v[32:35]
	v_mfma_f32_16x16x32_bf16 v[36:39], v[176:179], v[220:223], v[36:39]
	v_mfma_f32_16x16x32_bf16 v[36:39], v[172:175], v[216:219], v[36:39]
	v_mfma_f32_16x16x32_bf16 v[48:51], v[150:153], v[216:219], v[48:51]
	v_mfma_f32_16x16x32_bf16 v[48:51], v[154:157], v[220:223], v[48:51]
	v_mfma_f32_16x16x32_bf16 v[52:55], v[146:149], v[220:223], v[52:55]
	v_mfma_f32_16x16x32_bf16 v[52:55], v[134:137], v[216:219], v[52:55]
	s_setprio 0
	s_setprio 1
	v_mfma_f32_16x16x32_bf16 v[28:31], v[134:137], v[224:227], v[28:31]
	v_mfma_f32_16x16x32_bf16 v[28:31], v[146:149], v[228:231], v[28:31]
	v_mfma_f32_16x16x32_bf16 v[24:27], v[154:157], v[228:231], v[24:27]
	v_mfma_f32_16x16x32_bf16 v[24:27], v[150:153], v[224:227], v[24:27]
	v_mfma_f32_16x16x32_bf16 v[12:15], v[172:175], v[224:227], v[12:15]
	v_mfma_f32_16x16x32_bf16 v[12:15], v[176:179], v[228:231], v[12:15]
	v_mfma_f32_16x16x32_bf16 v[8:11], v[184:187], v[228:231], v[8:11]
	v_mfma_f32_16x16x32_bf16 v[8:11], v[180:183], v[224:227], v[8:11]
	v_mfma_f32_16x16x32_bf16 v[0:3], v[180:183], v[232:235], v[0:3]
	v_mfma_f32_16x16x32_bf16 v[0:3], v[184:187], v[236:239], v[0:3]
	v_mfma_f32_16x16x32_bf16 v[4:7], v[176:179], v[236:239], v[4:7]
	v_mfma_f32_16x16x32_bf16 v[4:7], v[172:175], v[232:235], v[4:7]
	v_mfma_f32_16x16x32_bf16 v[16:19], v[150:153], v[232:235], v[16:19]
	v_mfma_f32_16x16x32_bf16 v[16:19], v[154:157], v[236:239], v[16:19]
	s_setprio 2
	s_barrier
	v_mfma_f32_16x16x32_bf16 v[20:23], v[146:149], v[236:239], v[20:23]
	v_mfma_f32_16x16x32_bf16 v[20:23], v[134:137], v[232:235], v[20:23]
	s_setprio 0
	s_add_i32 s75, s75, 2
	s_add_u32 s42, s42, 0x100
	s_addc_u32 s43, s43, 0
	s_add_u32 s34, s34, 0x100
	s_addc_u32 s35, s35, 0
	s_cmpk_gt_u32 s75, 0x55
	s_cbranch_scc0 .LBB0_837
	s_and_b64 vcc, exec, s[18:19]
	s_cbranch_vccz .LBB0_840
	s_barrier

; #define PG8_STAGE(bufoff, gbase, voff) do { _Pragma("unroll") for (int _i = 0; _i < 2; ++_i) \
;         __builtin_amdgcn_global_load_lds((const unsigned*)((const char*)(gbase) + (voff)[_i]), (PG8_LAS unsigned*)(lds + (bufoff) + ldsw + _i * 8192), 16, 0, 0); } while (0)
; #define PG8_LDA(dst, b, h) do { _Pragma("unroll") for (int m = 0; m < 4; ++m) _Pragma("unroll") for (int k = 0; k < 2; ++k) dst[m][k] = *(const PG8_LAS bf16x8*)(lds + PG8_SA(b, h) + aoff + m * 2048 + k * 1024); } while (0)
; #define PG8_LDB(dst, b, h) do { _Pragma("unroll") for (int n = 0; n < 2; ++n) _Pragma("unroll") for (int k = 0; k < 2; ++k) dst[n][k] = *(const PG8_LAS bf16x8*)(lds + PG8_SB(b, h) + boff + n * 2048 + k * 1024); } while (0)
; #define PG8_MMA(ai, bj, At, Bt) do { __builtin_amdgcn_s_setprio(1); _Pragma("unroll") for (int m = 0; m < 4; ++m) _Pragma("unroll") for (int n = 0; n < 2; ++n) _Pragma("unroll") for (int k = 0; k < 2; ++k) \
;         acc[ai][bj][m][n] = __builtin_amdgcn_mfma_f32_16x16x32_bf16(Bt[n][k], At[m][k], acc[ai][bj][m][n], 0, 0, 0); __builtin_amdgcn_s_setprio(0); } while (0)
; #define PG8_WAIT_V(n) asm volatile("s_waitcnt vmcnt(" #n ")" ::: "memory")
; #define PG8_WAIT_L(n) asm volatile("s_waitcnt lgkmcnt(" #n ")" ::: "memory")
; #define PG8_BAR __builtin_amdgcn_s_barrier()
; #define PG8_SCHED __builtin_amdgcn_sched_barrier(0)
; template <class Epi, class Sched, bool ALIGN_EPI = false, bool SP2 = false>
; __device__ __forceinline__ void gemm_phase(PG8_LAS unsigned char* lds, const Gemm g, const Sched& S, const Epi& E) {
;     ...
;             PG8_LDB(B0, 0, 0); PG8_LDB(B1, 0, 1); PG8_SCHED; PG8_LDA(At, 0, 0); PG8_STAGE(PG8_SA(1, 1), a1 + hstep, voffA);
;             PG8_WAIT_V(8); PG8_WAIT_L(0); PG8_BAR; PG8_MMA(0, 0, At, B0); PG8_MMA(0, 1, At, B1); PG8_BAR; PG8_SCHED;
;             PG8_LDA(At, 0, 1); PG8_STAGE(PG8_SB(0, 0), b2, voffB); PG8_STAGE(PG8_SB(0, 1), b2 + hstep, voffB); PG8_STAGE(PG8_SA(0, 0), a2, voffA);
;             PG8_WAIT_V(8); PG8_WAIT_L(0); PG8_BAR; PG8_MMA(1, 0, At, B0); PG8_MMA(1, 1, At, B1); PG8_BAR; PG8_SCHED;
.LBB0_880:
	ds_read_b128 v[136:139], v156
	ds_read_b128 v[140:143], v156 offset:1024
	ds_read_b128 v[172:175], v156 offset:2048
	ds_read_b128 v[176:179], v156 offset:3072
	ds_read_b128 v[180:183], v157
	ds_read_b128 v[184:187], v157 offset:1024
	ds_read_b128 v[196:199], v157 offset:2048
	ds_read_b128 v[208:211], v157 offset:3072
	s_add_u32 s40, s38, 0xfff80080
	s_addc_u32 s41, s39, -1
	s_cmp_eq_u32 s63, 28
	s_cselect_b32 s43, s19, s41
	s_cselect_b32 s42, s34, s40
	s_cselect_b32 s41, s21, s62
	s_cselect_b32 s40, s35, s61
	v_lshl_add_u64 v[188:189], s[38:39], 0, v[128:129]
	s_add_i32 m0, s7, 0xc000
	ds_read_b128 v[212:215], v158
	ds_read_b128 v[216:219], v158 offset:1024
	ds_read_b128 v[220:223], v158 offset:2048
	ds_read_b128 v[224:227], v158 offset:3072
	ds_read_b128 v[228:231], v158 offset:4096
	ds_read_b128 v[232:235], v158 offset:5120
	ds_read_b128 v[236:239], v158 offset:6144
	ds_read_b128 v[240:243], v158 offset:7168
	global_load_lds_dwordx4 v[188:189], off
	v_lshl_add_u64 v[188:189], s[38:39], 0, v[130:131]
	s_add_i32 m0, s7, 0xe000
	s_nop 0
	global_load_lds_dwordx4 v[188:189], off
	s_waitcnt vmcnt(8)
	s_waitcnt lgkmcnt(0)
	s_barrier
	s_setprio 1
	s_waitcnt lgkmcnt(0)
	v_mfma_f32_16x16x32_bf16 v[124:127], v[136:139], v[212:215], v[124:127]
	v_mfma_f32_16x16x32_bf16 v[124:127], v[140:143], v[216:219], v[124:127]
	v_mfma_f32_16x16x32_bf16 v[120:123], v[176:179], v[216:219], v[120:123]
	v_mfma_f32_16x16x32_bf16 v[120:123], v[172:175], v[212:215], v[120:123]
	v_mfma_f32_16x16x32_bf16 v[116:119], v[180:183], v[212:215], v[116:119]
	v_mfma_f32_16x16x32_bf16 v[116:119], v[184:187], v[216:219], v[116:119]
	v_mfma_f32_16x16x32_bf16 v[112:115], v[208:211], v[216:219], v[112:115]
	v_mfma_f32_16x16x32_bf16 v[112:115], v[196:199], v[212:215], v[112:115]
	v_mfma_f32_16x16x32_bf16 v[92:95], v[196:199], v[220:223], v[92:95]
	v_mfma_f32_16x16x32_bf16 v[92:95], v[208:211], v[224:227], v[92:95]
	v_mfma_f32_16x16x32_bf16 v[100:103], v[184:187], v[224:227], v[100:103]
	v_mfma_f32_16x16x32_bf16 v[100:103], v[180:183], v[220:223], v[100:103]
	v_mfma_f32_16x16x32_bf16 v[104:107], v[172:175], v[220:223], v[104:107]
	v_mfma_f32_16x16x32_bf16 v[104:107], v[176:179], v[224:227], v[104:107]
	v_mfma_f32_16x16x32_bf16 v[108:111], v[140:143], v[224:227], v[108:111]
	v_mfma_f32_16x16x32_bf16 v[108:111], v[136:139], v[220:223], v[108:111]
	s_setprio 0
	s_setprio 1
	v_mfma_f32_16x16x32_bf16 v[96:99], v[136:139], v[228:231], v[96:99]
	v_mfma_f32_16x16x32_bf16 v[96:99], v[140:143], v[232:235], v[96:99]
	v_mfma_f32_16x16x32_bf16 v[88:91], v[176:179], v[232:235], v[88:91]
	v_mfma_f32_16x16x32_bf16 v[88:91], v[172:175], v[228:231], v[88:91]
	v_mfma_f32_16x16x32_bf16 v[84:87], v[180:183], v[228:231], v[84:87]
	v_mfma_f32_16x16x32_bf16 v[84:87], v[184:187], v[232:235], v[84:87]
	v_mfma_f32_16x16x32_bf16 v[76:79], v[208:211], v[232:235], v[76:79]
	v_mfma_f32_16x16x32_bf16 v[76:79], v[196:199], v[228:231], v[76:79]
	v_mfma_f32_16x16x32_bf16 v[64:67], v[196:199], v[236:239], v[64:67]
	v_mfma_f32_16x16x32_bf16 v[64:67], v[208:211], v[240:243], v[64:67]
	v_mfma_f32_16x16x32_bf16 v[68:71], v[184:187], v[240:243], v[68:71]
	v_mfma_f32_16x16x32_bf16 v[68:71], v[180:183], v[236:239], v[68:71]
	v_mfma_f32_16x16x32_bf16 v[72:75], v[172:175], v[236:239], v[72:75]
	v_mfma_f32_16x16x32_bf16 v[72:75], v[176:179], v[240:243], v[72:75]
	s_setprio 2
	s_barrier
	v_mfma_f32_16x16x32_bf16 v[80:83], v[140:143], v[240:243], v[80:83]
	v_mfma_f32_16x16x32_bf16 v[80:83], v[136:139], v[236:239], v[80:83]
	s_setprio 0
	s_add_i32 s44, s52, s33
	v_lshl_add_u64 v[188:189], s[40:41], 0, v[166:167]
	s_mov_b32 m0, s44
	ds_read_b128 v[212:215], v158 offset:16384
	ds_read_b128 v[216:219], v158 offset:17408
	ds_read_b128 v[220:223], v158 offset:18432
	ds_read_b128 v[224:227], v158 offset:19456
	ds_read_b128 v[228:231], v158 offset:20480
	ds_read_b128 v[232:235], v158 offset:21504
	ds_read_b128 v[236:239], v158 offset:22528
	ds_read_b128 v[240:243], v158 offset:23552
	global_load_lds_dwordx4 v[188:189], off
	s_add_i32 m0, s44, 0x2000
	s_add_u32 s64, s40, 0x80000
	v_lshl_add_u64 v[200:201], s[40:41], 0, v[170:171]
	s_addc_u32 s65, s41, 0
	s_add_i32 s44, s53, s33
	global_load_lds_dwordx4 v[200:201], off
	v_lshl_add_u64 v[244:245], s[64:65], 0, v[166:167]
	s_mov_b32 m0, s44
	v_lshl_add_u64 v[246:247], s[42:43], 0, v[168:169]
	global_load_lds_dwordx4 v[244:245], off
	v_lshl_add_u64 v[244:245], s[64:65], 0, v[170:171]
	s_add_i32 m0, s44, 0x2000
	s_nop 0
	global_load_lds_dwordx4 v[244:245], off
	v_lshl_add_u64 v[244:245], s[42:43], 0, v[164:165]
	s_mov_b32 m0, s7
	s_nop 0
	global_load_lds_dwordx4 v[244:245], off
	s_mov_b32 m0, s37
	s_nop 0
	global_load_lds_dwordx4 v[246:247], off
	s_waitcnt vmcnt(8)
	s_waitcnt lgkmcnt(0)
	s_barrier
; #define PG8_STAGE(bufoff, gbase, voff) do { _Pragma("unroll") for (int _i = 0; _i < 2; ++_i) \
;         __builtin_amdgcn_global_load_lds((const unsigned*)((const char*)(gbase) + (voff)[_i]), (PG8_LAS unsigned*)(lds + (bufoff) + ldsw + _i * 8192), 16, 0, 0); } while (0)
; #define PG8_LDA(dst, b, h) do { _Pragma("unroll") for (int m = 0; m < 4; ++m) _Pragma("unroll") for (int k = 0; k < 2; ++k) dst[m][k] = *(const PG8_LAS bf16x8*)(lds + PG8_SA(b, h) + aoff + m * 2048 + k * 1024); } while (0)
; #define PG8_LDB(dst, b, h) do { _Pragma("unroll") for (int n = 0; n < 2; ++n) _Pragma("unroll") for (int k = 0; k < 2; ++k) dst[n][k] = *(const PG8_LAS bf16x8*)(lds + PG8_SB(b, h) + boff + n * 2048 + k * 1024); } while (0)
; #define PG8_MMA(ai, bj, At, Bt) do { __builtin_amdgcn_s_setprio(1); _Pragma("unroll") for (int m = 0; m < 4; ++m) _Pragma("unroll") for (int n = 0; n < 2; ++n) _Pragma("unroll") for (int k = 0; k < 2; ++k) \
;         acc[ai][bj][m][n] = __builtin_amdgcn_mfma_f32_16x16x32_bf16(Bt[n][k], At[m][k], acc[ai][bj][m][n], 0, 0, 0); __builtin_amdgcn_s_setprio(0); } while (0)
; #define PG8_WAIT_V(n) asm volatile("s_waitcnt vmcnt(" #n ")" ::: "memory")
; #define PG8_WAIT_L(n) asm volatile("s_waitcnt lgkmcnt(" #n ")" ::: "memory")
; #define PG8_BAR __builtin_amdgcn_s_barrier()
; #define PG8_SCHED __builtin_amdgcn_sched_barrier(0)
; template <class Epi, class Sched, bool ALIGN_EPI = false, bool SP2 = false>
; __device__ __forceinline__ void gemm_phase(PG8_LAS unsigned char* lds, const Gemm g, const Sched& S, const Epi& E) {
;     ...
;             PG8_WAIT_V(8); PG8_WAIT_L(0); PG8_BAR; PG8_MMA(1, 0, At, B0); PG8_MMA(1, 1, At, B1); PG8_BAR; PG8_SCHED;
;             PG8_LDB(B0, 1, 0); PG8_LDB(B1, 1, 1); PG8_SCHED; PG8_LDA(At, 1, 0); PG8_STAGE(PG8_SA(0, 1), a2 + hstep, voffA);
;             PG8_WAIT_V(8); PG8_WAIT_L(0); PG8_BAR; PG8_MMA(0, 0, At, B0); PG8_MMA(0, 1, At, B1); PG8_BAR; PG8_SCHED;
	s_setprio 1
	s_waitcnt lgkmcnt(0)
	v_mfma_f32_16x16x32_bf16 v[60:63], v[136:139], v[212:215], v[60:63]
	v_mfma_f32_16x16x32_bf16 v[60:63], v[140:143], v[216:219], v[60:63]
	v_mfma_f32_16x16x32_bf16 v[56:59], v[176:179], v[216:219], v[56:59]
	v_mfma_f32_16x16x32_bf16 v[56:59], v[172:175], v[212:215], v[56:59]
	v_mfma_f32_16x16x32_bf16 v[52:55], v[180:183], v[212:215], v[52:55]
	v_mfma_f32_16x16x32_bf16 v[52:55], v[184:187], v[216:219], v[52:55]
	v_mfma_f32_16x16x32_bf16 v[44:47], v[208:211], v[216:219], v[44:47]
	v_mfma_f32_16x16x32_bf16 v[44:47], v[196:199], v[212:215], v[44:47]
	v_mfma_f32_16x16x32_bf16 v[28:31], v[196:199], v[220:223], v[28:31]
	v_mfma_f32_16x16x32_bf16 v[28:31], v[208:211], v[224:227], v[28:31]
	v_mfma_f32_16x16x32_bf16 v[36:39], v[184:187], v[224:227], v[36:39]
	v_mfma_f32_16x16x32_bf16 v[36:39], v[180:183], v[220:223], v[36:39]
	v_mfma_f32_16x16x32_bf16 v[40:43], v[172:175], v[220:223], v[40:43]
	v_mfma_f32_16x16x32_bf16 v[40:43], v[176:179], v[224:227], v[40:43]
	v_mfma_f32_16x16x32_bf16 v[48:51], v[140:143], v[224:227], v[48:51]
	v_mfma_f32_16x16x32_bf16 v[48:51], v[136:139], v[220:223], v[48:51]
	s_setprio 0
	s_setprio 1
	v_mfma_f32_16x16x32_bf16 v[32:35], v[136:139], v[228:231], v[32:35]
	v_mfma_f32_16x16x32_bf16 v[32:35], v[140:143], v[232:235], v[32:35]
	v_mfma_f32_16x16x32_bf16 v[24:27], v[176:179], v[232:235], v[24:27]
	v_mfma_f32_16x16x32_bf16 v[24:27], v[172:175], v[228:231], v[24:27]
	v_mfma_f32_16x16x32_bf16 v[20:23], v[180:183], v[228:231], v[20:23]
	v_mfma_f32_16x16x32_bf16 v[20:23], v[184:187], v[232:235], v[20:23]
	v_mfma_f32_16x16x32_bf16 v[16:19], v[208:211], v[232:235], v[16:19]
	v_mfma_f32_16x16x32_bf16 v[16:19], v[196:199], v[228:231], v[16:19]
	v_mfma_f32_16x16x32_bf16 v[0:3], v[196:199], v[236:239], v[0:3]
	v_mfma_f32_16x16x32_bf16 v[0:3], v[208:211], v[240:243], v[0:3]
	v_mfma_f32_16x16x32_bf16 v[4:7], v[184:187], v[240:243], v[4:7]
	v_mfma_f32_16x16x32_bf16 v[4:7], v[180:183], v[236:239], v[4:7]
	v_mfma_f32_16x16x32_bf16 v[8:11], v[172:175], v[236:239], v[8:11]
	v_mfma_f32_16x16x32_bf16 v[8:11], v[176:179], v[240:243], v[8:11]
	s_setprio 2
	s_barrier
	v_mfma_f32_16x16x32_bf16 v[12:15], v[140:143], v[240:243], v[12:15]
	v_mfma_f32_16x16x32_bf16 v[12:15], v[136:139], v[236:239], v[12:15]
	s_setprio 0
	s_add_i32 s44, 0, 0x18000
	v_add_u32_e32 v144, s44, v146
	s_add_i32 s45, 0, 0x1c000
	ds_read_b128 v[136:139], v144
	ds_read_b128 v[140:143], v144 offset:1024
	ds_read_b128 v[172:175], v144 offset:2048
	ds_read_b128 v[176:179], v144 offset:3072
	v_add_u32_e32 v144, s45, v146
	ds_read_b128 v[180:183], v144
	ds_read_b128 v[184:187], v144 offset:1024
	ds_read_b128 v[196:199], v144 offset:2048
	ds_read_b128 v[208:211], v144 offset:3072
	s_add_u32 s42, s42, 0x80000
	s_addc_u32 s43, s43, 0
	s_mov_b32 m0, s48
	v_lshl_add_u64 v[248:249], s[42:43], 0, v[164:165]
	ds_read_b128 v[212:215], v158 offset:32768
	ds_read_b128 v[216:219], v158 offset:33792
	ds_read_b128 v[220:223], v158 offset:34816
	ds_read_b128 v[224:227], v158 offset:35840
	ds_read_b128 v[228:231], v158 offset:36864
	ds_read_b128 v[232:235], v158 offset:37888
	ds_read_b128 v[236:239], v158 offset:38912
	ds_read_b128 v[240:243], v158 offset:39936
	global_load_lds_dwordx4 v[248:249], off
	v_lshl_add_u64 v[248:249], s[42:43], 0, v[168:169]
	s_mov_b32 m0, s49
	s_nop 0
	global_load_lds_dwordx4 v[248:249], off
	s_waitcnt vmcnt(8)
	s_waitcnt lgkmcnt(0)
	s_barrier
	s_setprio 1
	s_waitcnt lgkmcnt(0)
	v_mfma_f32_16x16x32_bf16 v[124:127], v[136:139], v[212:215], v[124:127]
	v_mfma_f32_16x16x32_bf16 v[124:127], v[140:143], v[216:219], v[124:127]
	v_mfma_f32_16x16x32_bf16 v[120:123], v[176:179], v[216:219], v[120:123]
	v_mfma_f32_16x16x32_bf16 v[120:123], v[172:175], v[212:215], v[120:123]
	v_mfma_f32_16x16x32_bf16 v[116:119], v[180:183], v[212:215], v[116:119]
	v_mfma_f32_16x16x32_bf16 v[116:119], v[184:187], v[216:219], v[116:119]
	v_mfma_f32_16x16x32_bf16 v[112:115], v[208:211], v[216:219], v[112:115]
	v_mfma_f32_16x16x32_bf16 v[112:115], v[196:199], v[212:215], v[112:115]
	v_mfma_f32_16x16x32_bf16 v[92:95], v[196:199], v[220:223], v[92:95]
	v_mfma_f32_16x16x32_bf16 v[92:95], v[208:211], v[224:227], v[92:95]
	v_mfma_f32_16x16x32_bf16 v[100:103], v[184:187], v[224:227], v[100:103]
	v_mfma_f32_16x16x32_bf16 v[100:103], v[180:183], v[220:223], v[100:103]
	v_mfma_f32_16x16x32_bf16 v[104:107], v[172:175], v[220:223], v[104:107]
	v_mfma_f32_16x16x32_bf16 v[104:107], v[176:179], v[224:227], v[104:107]
	v_mfma_f32_16x16x32_bf16 v[108:111], v[140:143], v[224:227], v[108:111]
	v_mfma_f32_16x16x32_bf16 v[108:111], v[136:139], v[220:223], v[108:111]
	s_setprio 0
	s_setprio 1
	v_mfma_f32_16x16x32_bf16 v[96:99], v[136:139], v[228:231], v[96:99]
	v_mfma_f32_16x16x32_bf16 v[96:99], v[140:143], v[232:235], v[96:99]
	v_mfma_f32_16x16x32_bf16 v[88:91], v[176:179], v[232:235], v[88:91]
	v_mfma_f32_16x16x32_bf16 v[88:91], v[172:175], v[228:231], v[88:91]
	v_mfma_f32_16x16x32_bf16 v[84:87], v[180:183], v[228:231], v[84:87]
	v_mfma_f32_16x16x32_bf16 v[84:87], v[184:187], v[232:235], v[84:87]
	v_mfma_f32_16x16x32_bf16 v[76:79], v[208:211], v[232:235], v[76:79]
	v_mfma_f32_16x16x32_bf16 v[76:79], v[196:199], v[228:231], v[76:79]
	v_mfma_f32_16x16x32_bf16 v[64:67], v[196:199], v[236:239], v[64:67]
	v_mfma_f32_16x16x32_bf16 v[64:67], v[208:211], v[240:243], v[64:67]
	v_mfma_f32_16x16x32_bf16 v[68:71], v[184:187], v[240:243], v[68:71]
	v_mfma_f32_16x16x32_bf16 v[68:71], v[180:183], v[236:239], v[68:71]
	v_mfma_f32_16x16x32_bf16 v[72:75], v[172:175], v[236:239], v[72:75]
	v_mfma_f32_16x16x32_bf16 v[72:75], v[176:179], v[240:243], v[72:75]
	s_setprio 2
	s_barrier
; #define PG8_STAGE(bufoff, gbase, voff) do { _Pragma("unroll") for (int _i = 0; _i < 2; ++_i) \
;         __builtin_amdgcn_global_load_lds((const unsigned*)((const char*)(gbase) + (voff)[_i]), (PG8_LAS unsigned*)(lds + (bufoff) + ldsw + _i * 8192), 16, 0, 0); } while (0)
; #define PG8_LDA(dst, b, h) do { _Pragma("unroll") for (int m = 0; m < 4; ++m) _Pragma("unroll") for (int k = 0; k < 2; ++k) dst[m][k] = *(const PG8_LAS bf16x8*)(lds + PG8_SA(b, h) + aoff + m * 2048 + k * 1024); } while (0)
; #define PG8_MMA(ai, bj, At, Bt) do { __builtin_amdgcn_s_setprio(1); _Pragma("unroll") for (int m = 0; m < 4; ++m) _Pragma("unroll") for (int n = 0; n < 2; ++n) _Pragma("unroll") for (int k = 0; k < 2; ++k) \
;         acc[ai][bj][m][n] = __builtin_amdgcn_mfma_f32_16x16x32_bf16(Bt[n][k], At[m][k], acc[ai][bj][m][n], 0, 0, 0); __builtin_amdgcn_s_setprio(0); } while (0)
; #define PG8_WAIT_V(n) asm volatile("s_waitcnt vmcnt(" #n ")" ::: "memory")
; #define PG8_WAIT_L(n) asm volatile("s_waitcnt lgkmcnt(" #n ")" ::: "memory")
; #define PG8_BAR __builtin_amdgcn_s_barrier()
; #define PG8_SCHED __builtin_amdgcn_sched_barrier(0)
; template <class Epi, class Sched, bool ALIGN_EPI = false, bool SP2 = false>
; __device__ __forceinline__ void gemm_phase(PG8_LAS unsigned char* lds, const Gemm g, const Sched& S, const Epi& E) {
;     ...
;         for (int t = 0; t < nt; t += 2) {
;     ...
;             PG8_WAIT_V(8); PG8_WAIT_L(0); PG8_BAR; PG8_MMA(0, 0, At, B0); PG8_MMA(0, 1, At, B1); PG8_BAR; PG8_SCHED;
;             PG8_LDA(At, 1, 1); PG8_STAGE(PG8_SB(1, 0), b3, voffB); PG8_STAGE(PG8_SB(1, 1), b3 + hstep, voffB); PG8_STAGE(PG8_SA(1, 0), a3, voffA);
;             PG8_WAIT_V(8); PG8_WAIT_L(0); PG8_BAR; PG8_MMA(1, 0, At, B0); PG8_MMA(1, 1, At, B1); PG8_BAR; PG8_SCHED;
	v_mfma_f32_16x16x32_bf16 v[80:83], v[140:143], v[240:243], v[80:83]
	v_mfma_f32_16x16x32_bf16 v[80:83], v[136:139], v[236:239], v[80:83]
	s_setprio 0
	s_add_i32 s42, s44, s33
	v_lshl_add_u64 v[188:189], v[188:189], 0, s[14:15]
	s_mov_b32 m0, s42
	ds_read_b128 v[212:215], v158 offset:49152
	ds_read_b128 v[216:219], v158 offset:50176
	ds_read_b128 v[220:223], v158 offset:51200
	ds_read_b128 v[224:227], v158 offset:52224
	ds_read_b128 v[228:231], v158 offset:53248
	ds_read_b128 v[232:235], v158 offset:54272
	ds_read_b128 v[236:239], v158 offset:55296
	ds_read_b128 v[240:243], v158 offset:56320
	global_load_lds_dwordx4 v[188:189], off
	s_add_i32 m0, s42, 0x2000
	s_add_u32 s40, s40, 0x80080
	v_lshl_add_u64 v[188:189], v[200:201], 0, s[14:15]
	s_addc_u32 s41, s41, 0
	s_add_i32 s42, s45, s33
	global_load_lds_dwordx4 v[188:189], off
	v_lshl_add_u64 v[188:189], s[40:41], 0, v[166:167]
	s_mov_b32 m0, s42
	s_nop 0
	global_load_lds_dwordx4 v[188:189], off
	v_lshl_add_u64 v[188:189], s[40:41], 0, v[170:171]
	s_add_i32 m0, s42, 0x2000
	s_nop 0
	global_load_lds_dwordx4 v[188:189], off
	v_lshl_add_u64 v[188:189], v[244:245], 0, s[14:15]
	s_mov_b32 m0, s50
	s_nop 0
	global_load_lds_dwordx4 v[188:189], off
	v_lshl_add_u64 v[188:189], v[246:247], 0, s[14:15]
	s_mov_b32 m0, s51
	s_nop 0
	global_load_lds_dwordx4 v[188:189], off
	s_waitcnt vmcnt(8)
	s_waitcnt lgkmcnt(0)
	s_barrier
	s_setprio 1
	s_waitcnt lgkmcnt(0)
	v_mfma_f32_16x16x32_bf16 v[60:63], v[136:139], v[212:215], v[60:63]
	v_mfma_f32_16x16x32_bf16 v[60:63], v[140:143], v[216:219], v[60:63]
	v_mfma_f32_16x16x32_bf16 v[56:59], v[176:179], v[216:219], v[56:59]
	v_mfma_f32_16x16x32_bf16 v[56:59], v[172:175], v[212:215], v[56:59]
	v_mfma_f32_16x16x32_bf16 v[52:55], v[180:183], v[212:215], v[52:55]
	v_mfma_f32_16x16x32_bf16 v[52:55], v[184:187], v[216:219], v[52:55]
	v_mfma_f32_16x16x32_bf16 v[44:47], v[208:211], v[216:219], v[44:47]
	v_mfma_f32_16x16x32_bf16 v[44:47], v[196:199], v[212:215], v[44:47]
	v_mfma_f32_16x16x32_bf16 v[28:31], v[196:199], v[220:223], v[28:31]
	v_mfma_f32_16x16x32_bf16 v[28:31], v[208:211], v[224:227], v[28:31]
	v_mfma_f32_16x16x32_bf16 v[36:39], v[184:187], v[224:227], v[36:39]
	v_mfma_f32_16x16x32_bf16 v[36:39], v[180:183], v[220:223], v[36:39]
	v_mfma_f32_16x16x32_bf16 v[40:43], v[172:175], v[220:223], v[40:43]
	v_mfma_f32_16x16x32_bf16 v[40:43], v[176:179], v[224:227], v[40:43]
	v_mfma_f32_16x16x32_bf16 v[48:51], v[140:143], v[224:227], v[48:51]
	v_mfma_f32_16x16x32_bf16 v[48:51], v[136:139], v[220:223], v[48:51]
	s_setprio 0
	s_setprio 1
	v_mfma_f32_16x16x32_bf16 v[32:35], v[136:139], v[228:231], v[32:35]
	v_mfma_f32_16x16x32_bf16 v[32:35], v[140:143], v[232:235], v[32:35]
	v_mfma_f32_16x16x32_bf16 v[24:27], v[176:179], v[232:235], v[24:27]
	v_mfma_f32_16x16x32_bf16 v[24:27], v[172:175], v[228:231], v[24:27]
	v_mfma_f32_16x16x32_bf16 v[20:23], v[180:183], v[228:231], v[20:23]
	v_mfma_f32_16x16x32_bf16 v[20:23], v[184:187], v[232:235], v[20:23]
	v_mfma_f32_16x16x32_bf16 v[16:19], v[208:211], v[232:235], v[16:19]
	v_mfma_f32_16x16x32_bf16 v[16:19], v[196:199], v[228:231], v[16:19]
	v_mfma_f32_16x16x32_bf16 v[0:3], v[196:199], v[236:239], v[0:3]
	v_mfma_f32_16x16x32_bf16 v[0:3], v[208:211], v[240:243], v[0:3]
	v_mfma_f32_16x16x32_bf16 v[4:7], v[184:187], v[240:243], v[4:7]
	v_mfma_f32_16x16x32_bf16 v[4:7], v[180:183], v[236:239], v[4:7]
	v_mfma_f32_16x16x32_bf16 v[8:11], v[172:175], v[236:239], v[8:11]
	v_mfma_f32_16x16x32_bf16 v[8:11], v[176:179], v[240:243], v[8:11]
	s_setprio 2
	s_barrier
	v_mfma_f32_16x16x32_bf16 v[12:15], v[140:143], v[240:243], v[12:15]
	v_mfma_f32_16x16x32_bf16 v[12:15], v[136:139], v[236:239], v[12:15]
	s_setprio 0
	s_add_i32 s63, s63, 2
	s_add_u32 s38, s38, 0x100
	s_addc_u32 s39, s39, 0
	s_add_u32 s61, s61, 0x100
	s_addc_u32 s62, s62, 0
	s_cmp_gt_u32 s63, 29
	s_cbranch_scc0 .LBB0_880
	s_and_b64 vcc, exec, s[16:17]
	s_cbranch_vccz .LBB0_883
	s_barrier

; #define PG8_STAGE(bufoff, gbase, voff) do { _Pragma("unroll") for (int _i = 0; _i < 2; ++_i) \
;         __builtin_amdgcn_global_load_lds((const unsigned*)((const char*)(gbase) + (voff)[_i]), (PG8_LAS unsigned*)(lds + (bufoff) + ldsw + _i * 8192), 16, 0, 0); } while (0)
; #define PG8_LDA(dst, b, h) do { _Pragma("unroll") for (int m = 0; m < 4; ++m) _Pragma("unroll") for (int k = 0; k < 2; ++k) dst[m][k] = *(const PG8_LAS bf16x8*)(lds + PG8_SA(b, h) + aoff + m * 2048 + k * 1024); } while (0)
; #define PG8_LDB(dst, b, h) do { _Pragma("unroll") for (int n = 0; n < 2; ++n) _Pragma("unroll") for (int k = 0; k < 2; ++k) dst[n][k] = *(const PG8_LAS bf16x8*)(lds + PG8_SB(b, h) + boff + n * 2048 + k * 1024); } while (0)
; #define PG8_MMA(ai, bj, At, Bt) do { __builtin_amdgcn_s_setprio(1); _Pragma("unroll") for (int m = 0; m < 4; ++m) _Pragma("unroll") for (int n = 0; n < 2; ++n) _Pragma("unroll") for (int k = 0; k < 2; ++k) \
;         acc[ai][bj][m][n] = __builtin_amdgcn_mfma_f32_16x16x32_bf16(Bt[n][k], At[m][k], acc[ai][bj][m][n], 0, 0, 0); __builtin_amdgcn_s_setprio(0); } while (0)
; #define PG8_WAIT_V(n) asm volatile("s_waitcnt vmcnt(" #n ")" ::: "memory")
; #define PG8_WAIT_L(n) asm volatile("s_waitcnt lgkmcnt(" #n ")" ::: "memory")
; #define PG8_BAR __builtin_amdgcn_s_barrier()
; #define PG8_SCHED __builtin_amdgcn_sched_barrier(0)
; template <class Epi, class Sched, bool ALIGN_EPI = false, bool SP2 = false>
; __device__ __forceinline__ void gemm_phase(PG8_LAS unsigned char* lds, const Gemm g, const Sched& S, const Epi& E) {
;     ...
;             PG8_LDB(B0, 0, 0); PG8_LDB(B1, 0, 1); PG8_SCHED; PG8_LDA(At, 0, 0); PG8_STAGE(PG8_SA(1, 1), a1 + hstep, voffA);
;             PG8_WAIT_V(8); PG8_WAIT_L(0); PG8_BAR; PG8_MMA(0, 0, At, B0); PG8_MMA(0, 1, At, B1); PG8_BAR; PG8_SCHED;
;             PG8_LDA(At, 0, 1); PG8_STAGE(PG8_SB(0, 0), b2, voffB); PG8_STAGE(PG8_SB(0, 1), b2 + hstep, voffB); PG8_STAGE(PG8_SA(0, 0), a2, voffA);
;             PG8_WAIT_V(8); PG8_WAIT_L(0); PG8_BAR; PG8_MMA(1, 0, At, B0); PG8_MMA(1, 1, At, B1); PG8_BAR; PG8_SCHED;
.LBB0_937:
	ds_read_b128 v[128:131], v199
	ds_read_b128 v[132:135], v199 offset:1024
	ds_read_b128 v[136:139], v199 offset:2048
	ds_read_b128 v[140:143], v199 offset:3072
	ds_read_b128 v[150:153], v200
	ds_read_b128 v[154:157], v200 offset:1024
	ds_read_b128 v[164:167], v200 offset:2048
	ds_read_b128 v[168:171], v200 offset:3072
	s_add_u32 s22, s20, 0xffea0080
	s_addc_u32 s23, s21, -1
	s_cmpk_eq_i32 s49, 0x54
	s_cselect_b32 s25, s17, s23
	s_cselect_b32 s24, s16, s22
	s_cselect_b32 s23, s19, s48
	s_cselect_b32 s22, s18, s47
	v_lshl_add_u64 v[158:159], s[20:21], 0, v[144:145]
	s_add_i32 m0, s31, 0xc000
	ds_read_b128 v[172:175], v201
	ds_read_b128 v[176:179], v201 offset:1024
	ds_read_b128 v[180:183], v201 offset:2048
	ds_read_b128 v[184:187], v201 offset:3072
	ds_read_b128 v[188:191], v201 offset:4096
	ds_read_b128 v[204:207], v201 offset:5120
	ds_read_b128 v[208:211], v201 offset:6144
	ds_read_b128 v[212:215], v201 offset:7168
	global_load_lds_dwordx4 v[158:159], off
	v_lshl_add_u64 v[158:159], s[20:21], 0, v[146:147]
	s_add_i32 m0, s31, 0xe000
	s_nop 0
	global_load_lds_dwordx4 v[158:159], off
	s_waitcnt vmcnt(8)
	s_waitcnt lgkmcnt(0)
	s_barrier
	s_setprio 1
	s_waitcnt lgkmcnt(0)
	v_mfma_f32_16x16x32_bf16 v[124:127], v[128:131], v[172:175], v[124:127]
	v_mfma_f32_16x16x32_bf16 v[124:127], v[132:135], v[176:179], v[124:127]
	v_mfma_f32_16x16x32_bf16 v[120:123], v[140:143], v[176:179], v[120:123]
	v_mfma_f32_16x16x32_bf16 v[120:123], v[136:139], v[172:175], v[120:123]
	v_mfma_f32_16x16x32_bf16 v[116:119], v[150:153], v[172:175], v[116:119]
	v_mfma_f32_16x16x32_bf16 v[116:119], v[154:157], v[176:179], v[116:119]
	v_mfma_f32_16x16x32_bf16 v[112:115], v[168:171], v[176:179], v[112:115]
	v_mfma_f32_16x16x32_bf16 v[112:115], v[164:167], v[172:175], v[112:115]
	v_mfma_f32_16x16x32_bf16 v[96:99], v[164:167], v[180:183], v[96:99]
	v_mfma_f32_16x16x32_bf16 v[96:99], v[168:171], v[184:187], v[96:99]
	v_mfma_f32_16x16x32_bf16 v[100:103], v[154:157], v[184:187], v[100:103]
	v_mfma_f32_16x16x32_bf16 v[100:103], v[150:153], v[180:183], v[100:103]
	v_mfma_f32_16x16x32_bf16 v[104:107], v[136:139], v[180:183], v[104:107]
	v_mfma_f32_16x16x32_bf16 v[104:107], v[140:143], v[184:187], v[104:107]
	v_mfma_f32_16x16x32_bf16 v[108:111], v[132:135], v[184:187], v[108:111]
	v_mfma_f32_16x16x32_bf16 v[108:111], v[128:131], v[180:183], v[108:111]
	s_setprio 0
	s_setprio 1
	v_mfma_f32_16x16x32_bf16 v[92:95], v[128:131], v[188:191], v[92:95]
	v_mfma_f32_16x16x32_bf16 v[92:95], v[132:135], v[204:207], v[92:95]
	v_mfma_f32_16x16x32_bf16 v[88:91], v[140:143], v[204:207], v[88:91]
	v_mfma_f32_16x16x32_bf16 v[88:91], v[136:139], v[188:191], v[88:91]
	v_mfma_f32_16x16x32_bf16 v[84:87], v[150:153], v[188:191], v[84:87]
	v_mfma_f32_16x16x32_bf16 v[84:87], v[154:157], v[204:207], v[84:87]
	v_mfma_f32_16x16x32_bf16 v[80:83], v[168:171], v[204:207], v[80:83]
	v_mfma_f32_16x16x32_bf16 v[80:83], v[164:167], v[188:191], v[80:83]
	v_mfma_f32_16x16x32_bf16 v[64:67], v[164:167], v[208:211], v[64:67]
	v_mfma_f32_16x16x32_bf16 v[64:67], v[168:171], v[212:215], v[64:67]
	v_mfma_f32_16x16x32_bf16 v[68:71], v[154:157], v[212:215], v[68:71]
	v_mfma_f32_16x16x32_bf16 v[68:71], v[150:153], v[208:211], v[68:71]
	v_mfma_f32_16x16x32_bf16 v[72:75], v[136:139], v[208:211], v[72:75]
	v_mfma_f32_16x16x32_bf16 v[72:75], v[140:143], v[212:215], v[72:75]
	s_setprio 2
	s_barrier
	v_mfma_f32_16x16x32_bf16 v[76:79], v[132:135], v[212:215], v[76:79]
	v_mfma_f32_16x16x32_bf16 v[76:79], v[128:131], v[208:211], v[76:79]
	s_setprio 0
	s_add_i32 s50, s41, s30
	v_lshl_add_u64 v[158:159], s[22:23], 0, v[160:161]
	s_mov_b32 m0, s50
	ds_read_b128 v[172:175], v201 offset:16384
	ds_read_b128 v[176:179], v201 offset:17408
	ds_read_b128 v[180:183], v201 offset:18432
	ds_read_b128 v[184:187], v201 offset:19456
	ds_read_b128 v[188:191], v201 offset:20480
	ds_read_b128 v[204:207], v201 offset:21504
	ds_read_b128 v[208:211], v201 offset:22528
	ds_read_b128 v[212:215], v201 offset:23552
	global_load_lds_dwordx4 v[158:159], off
	s_add_i32 m0, s50, 0x2000
	s_add_u32 s50, s22, 0x160000
	v_lshl_add_u64 v[192:193], s[22:23], 0, v[162:163]
	s_addc_u32 s51, s23, 0
	s_add_i32 s52, s42, s30
	global_load_lds_dwordx4 v[192:193], off
	v_lshl_add_u64 v[216:217], s[50:51], 0, v[160:161]
	s_mov_b32 m0, s52
	v_lshl_add_u64 v[218:219], s[24:25], 0, v[162:163]
	global_load_lds_dwordx4 v[216:217], off
	v_lshl_add_u64 v[216:217], s[50:51], 0, v[162:163]
	s_add_i32 m0, s52, 0x2000
	s_nop 0
	global_load_lds_dwordx4 v[216:217], off
	v_lshl_add_u64 v[216:217], s[24:25], 0, v[160:161]
	s_mov_b32 m0, s31
	s_nop 0
	global_load_lds_dwordx4 v[216:217], off
	s_mov_b32 m0, s33
	s_nop 0
	global_load_lds_dwordx4 v[218:219], off
	s_waitcnt vmcnt(8)
	s_waitcnt lgkmcnt(0)
	s_barrier
; #define PG8_STAGE(bufoff, gbase, voff) do { _Pragma("unroll") for (int _i = 0; _i < 2; ++_i) \
;         __builtin_amdgcn_global_load_lds((const unsigned*)((const char*)(gbase) + (voff)[_i]), (PG8_LAS unsigned*)(lds + (bufoff) + ldsw + _i * 8192), 16, 0, 0); } while (0)
; #define PG8_LDA(dst, b, h) do { _Pragma("unroll") for (int m = 0; m < 4; ++m) _Pragma("unroll") for (int k = 0; k < 2; ++k) dst[m][k] = *(const PG8_LAS bf16x8*)(lds + PG8_SA(b, h) + aoff + m * 2048 + k * 1024); } while (0)
; #define PG8_LDB(dst, b, h) do { _Pragma("unroll") for (int n = 0; n < 2; ++n) _Pragma("unroll") for (int k = 0; k < 2; ++k) dst[n][k] = *(const PG8_LAS bf16x8*)(lds + PG8_SB(b, h) + boff + n * 2048 + k * 1024); } while (0)
; #define PG8_MMA(ai, bj, At, Bt) do { __builtin_amdgcn_s_setprio(1); _Pragma("unroll") for (int m = 0; m < 4; ++m) _Pragma("unroll") for (int n = 0; n < 2; ++n) _Pragma("unroll") for (int k = 0; k < 2; ++k) \
;         acc[ai][bj][m][n] = __builtin_amdgcn_mfma_f32_16x16x32_bf16(Bt[n][k], At[m][k], acc[ai][bj][m][n], 0, 0, 0); __builtin_amdgcn_s_setprio(0); } while (0)
; #define PG8_WAIT_V(n) asm volatile("s_waitcnt vmcnt(" #n ")" ::: "memory")
; #define PG8_WAIT_L(n) asm volatile("s_waitcnt lgkmcnt(" #n ")" ::: "memory")
; #define PG8_BAR __builtin_amdgcn_s_barrier()
; #define PG8_SCHED __builtin_amdgcn_sched_barrier(0)
; template <class Epi, class Sched, bool ALIGN_EPI = false, bool SP2 = false>
; __device__ __forceinline__ void gemm_phase(PG8_LAS unsigned char* lds, const Gemm g, const Sched& S, const Epi& E) {
;     ...
;             PG8_WAIT_V(8); PG8_WAIT_L(0); PG8_BAR; PG8_MMA(1, 0, At, B0); PG8_MMA(1, 1, At, B1); PG8_BAR; PG8_SCHED;
;             PG8_LDB(B0, 1, 0); PG8_LDB(B1, 1, 1); PG8_SCHED; PG8_LDA(At, 1, 0); PG8_STAGE(PG8_SA(0, 1), a2 + hstep, voffA);
;             PG8_WAIT_V(8); PG8_WAIT_L(0); PG8_BAR; PG8_MMA(0, 0, At, B0); PG8_MMA(0, 1, At, B1); PG8_BAR; PG8_SCHED;
	s_setprio 1
	s_waitcnt lgkmcnt(0)
	v_mfma_f32_16x16x32_bf16 v[60:63], v[128:131], v[172:175], v[60:63]
	v_mfma_f32_16x16x32_bf16 v[60:63], v[132:135], v[176:179], v[60:63]
	v_mfma_f32_16x16x32_bf16 v[56:59], v[140:143], v[176:179], v[56:59]
	v_mfma_f32_16x16x32_bf16 v[56:59], v[136:139], v[172:175], v[56:59]
	v_mfma_f32_16x16x32_bf16 v[52:55], v[150:153], v[172:175], v[52:55]
	v_mfma_f32_16x16x32_bf16 v[52:55], v[154:157], v[176:179], v[52:55]
	v_mfma_f32_16x16x32_bf16 v[48:51], v[168:171], v[176:179], v[48:51]
	v_mfma_f32_16x16x32_bf16 v[48:51], v[164:167], v[172:175], v[48:51]
	v_mfma_f32_16x16x32_bf16 v[32:35], v[164:167], v[180:183], v[32:35]
	v_mfma_f32_16x16x32_bf16 v[32:35], v[168:171], v[184:187], v[32:35]
	v_mfma_f32_16x16x32_bf16 v[36:39], v[154:157], v[184:187], v[36:39]
	v_mfma_f32_16x16x32_bf16 v[36:39], v[150:153], v[180:183], v[36:39]
	v_mfma_f32_16x16x32_bf16 v[40:43], v[136:139], v[180:183], v[40:43]
	v_mfma_f32_16x16x32_bf16 v[40:43], v[140:143], v[184:187], v[40:43]
	v_mfma_f32_16x16x32_bf16 v[44:47], v[132:135], v[184:187], v[44:47]
	v_mfma_f32_16x16x32_bf16 v[44:47], v[128:131], v[180:183], v[44:47]
	s_setprio 0
	s_setprio 1
	v_mfma_f32_16x16x32_bf16 v[28:31], v[128:131], v[188:191], v[28:31]
	v_mfma_f32_16x16x32_bf16 v[28:31], v[132:135], v[204:207], v[28:31]
	v_mfma_f32_16x16x32_bf16 v[24:27], v[140:143], v[204:207], v[24:27]
	v_mfma_f32_16x16x32_bf16 v[24:27], v[136:139], v[188:191], v[24:27]
	v_mfma_f32_16x16x32_bf16 v[20:23], v[150:153], v[188:191], v[20:23]
	v_mfma_f32_16x16x32_bf16 v[20:23], v[154:157], v[204:207], v[20:23]
	v_mfma_f32_16x16x32_bf16 v[16:19], v[168:171], v[204:207], v[16:19]
	v_mfma_f32_16x16x32_bf16 v[16:19], v[164:167], v[188:191], v[16:19]
	v_mfma_f32_16x16x32_bf16 v[0:3], v[164:167], v[208:211], v[0:3]
	v_mfma_f32_16x16x32_bf16 v[0:3], v[168:171], v[212:215], v[0:3]
	v_mfma_f32_16x16x32_bf16 v[4:7], v[154:157], v[212:215], v[4:7]
	v_mfma_f32_16x16x32_bf16 v[4:7], v[150:153], v[208:211], v[4:7]
	v_mfma_f32_16x16x32_bf16 v[8:11], v[136:139], v[208:211], v[8:11]
	v_mfma_f32_16x16x32_bf16 v[8:11], v[140:143], v[212:215], v[8:11]
	s_setprio 2
	s_barrier
	v_mfma_f32_16x16x32_bf16 v[12:15], v[132:135], v[212:215], v[12:15]
	v_mfma_f32_16x16x32_bf16 v[12:15], v[128:131], v[208:211], v[12:15]
	s_setprio 0
	s_add_i32 s50, 0, 0x18000
	s_add_i32 s51, 0, 0x1c000
	v_add_u32_e32 v140, s50, v196
	v_add_u32_e32 v168, s51, v196
	ds_read_b128 v[128:131], v140
	ds_read_b128 v[132:135], v140 offset:1024
	ds_read_b128 v[136:139], v140 offset:2048
	ds_read_b128 v[140:143], v140 offset:3072
	ds_read_b128 v[150:153], v168
	ds_read_b128 v[154:157], v168 offset:1024
	ds_read_b128 v[164:167], v168 offset:2048
	ds_read_b128 v[168:171], v168 offset:3072
	s_add_u32 s24, s24, 0x160000
	s_addc_u32 s25, s25, 0
	s_mov_b32 m0, s34
	v_lshl_add_u64 v[220:221], s[24:25], 0, v[160:161]
	ds_read_b128 v[172:175], v201 offset:32768
	ds_read_b128 v[176:179], v201 offset:33792
	ds_read_b128 v[180:183], v201 offset:34816
	ds_read_b128 v[184:187], v201 offset:35840
	ds_read_b128 v[188:191], v201 offset:36864
	ds_read_b128 v[204:207], v201 offset:37888
	ds_read_b128 v[208:211], v201 offset:38912
	ds_read_b128 v[212:215], v201 offset:39936
	global_load_lds_dwordx4 v[220:221], off
	v_lshl_add_u64 v[220:221], s[24:25], 0, v[162:163]
	s_mov_b32 m0, s35
	s_nop 0
	global_load_lds_dwordx4 v[220:221], off
	s_waitcnt vmcnt(8)
	s_waitcnt lgkmcnt(0)
	s_barrier
	s_setprio 1
	s_waitcnt lgkmcnt(0)
	v_mfma_f32_16x16x32_bf16 v[124:127], v[128:131], v[172:175], v[124:127]
	v_mfma_f32_16x16x32_bf16 v[124:127], v[132:135], v[176:179], v[124:127]
	v_mfma_f32_16x16x32_bf16 v[120:123], v[140:143], v[176:179], v[120:123]
	v_mfma_f32_16x16x32_bf16 v[120:123], v[136:139], v[172:175], v[120:123]
	v_mfma_f32_16x16x32_bf16 v[116:119], v[150:153], v[172:175], v[116:119]
	v_mfma_f32_16x16x32_bf16 v[116:119], v[154:157], v[176:179], v[116:119]
	v_mfma_f32_16x16x32_bf16 v[112:115], v[168:171], v[176:179], v[112:115]
	v_mfma_f32_16x16x32_bf16 v[112:115], v[164:167], v[172:175], v[112:115]
	v_mfma_f32_16x16x32_bf16 v[96:99], v[164:167], v[180:183], v[96:99]
	v_mfma_f32_16x16x32_bf16 v[96:99], v[168:171], v[184:187], v[96:99]
	v_mfma_f32_16x16x32_bf16 v[100:103], v[154:157], v[184:187], v[100:103]
	v_mfma_f32_16x16x32_bf16 v[100:103], v[150:153], v[180:183], v[100:103]
	v_mfma_f32_16x16x32_bf16 v[104:107], v[136:139], v[180:183], v[104:107]
	v_mfma_f32_16x16x32_bf16 v[104:107], v[140:143], v[184:187], v[104:107]
	v_mfma_f32_16x16x32_bf16 v[108:111], v[132:135], v[184:187], v[108:111]
	v_mfma_f32_16x16x32_bf16 v[108:111], v[128:131], v[180:183], v[108:111]
	s_setprio 0
	s_setprio 1
	v_mfma_f32_16x16x32_bf16 v[92:95], v[128:131], v[188:191], v[92:95]
	v_mfma_f32_16x16x32_bf16 v[92:95], v[132:135], v[204:207], v[92:95]
	v_mfma_f32_16x16x32_bf16 v[88:91], v[140:143], v[204:207], v[88:91]
	v_mfma_f32_16x16x32_bf16 v[88:91], v[136:139], v[188:191], v[88:91]
	v_mfma_f32_16x16x32_bf16 v[84:87], v[150:153], v[188:191], v[84:87]
	v_mfma_f32_16x16x32_bf16 v[84:87], v[154:157], v[204:207], v[84:87]
	v_mfma_f32_16x16x32_bf16 v[80:83], v[168:171], v[204:207], v[80:83]
	v_mfma_f32_16x16x32_bf16 v[80:83], v[164:167], v[188:191], v[80:83]
	v_mfma_f32_16x16x32_bf16 v[64:67], v[164:167], v[208:211], v[64:67]
	v_mfma_f32_16x16x32_bf16 v[64:67], v[168:171], v[212:215], v[64:67]
	v_mfma_f32_16x16x32_bf16 v[68:71], v[154:157], v[212:215], v[68:71]
	v_mfma_f32_16x16x32_bf16 v[68:71], v[150:153], v[208:211], v[68:71]
	v_mfma_f32_16x16x32_bf16 v[72:75], v[136:139], v[208:211], v[72:75]
	v_mfma_f32_16x16x32_bf16 v[72:75], v[140:143], v[212:215], v[72:75]
	s_setprio 2
	s_barrier
; #define PG8_STAGE(bufoff, gbase, voff) do { _Pragma("unroll") for (int _i = 0; _i < 2; ++_i) \
;         __builtin_amdgcn_global_load_lds((const unsigned*)((const char*)(gbase) + (voff)[_i]), (PG8_LAS unsigned*)(lds + (bufoff) + ldsw + _i * 8192), 16, 0, 0); } while (0)
; #define PG8_LDA(dst, b, h) do { _Pragma("unroll") for (int m = 0; m < 4; ++m) _Pragma("unroll") for (int k = 0; k < 2; ++k) dst[m][k] = *(const PG8_LAS bf16x8*)(lds + PG8_SA(b, h) + aoff + m * 2048 + k * 1024); } while (0)
; #define PG8_MMA(ai, bj, At, Bt) do { __builtin_amdgcn_s_setprio(1); _Pragma("unroll") for (int m = 0; m < 4; ++m) _Pragma("unroll") for (int n = 0; n < 2; ++n) _Pragma("unroll") for (int k = 0; k < 2; ++k) \
;         acc[ai][bj][m][n] = __builtin_amdgcn_mfma_f32_16x16x32_bf16(Bt[n][k], At[m][k], acc[ai][bj][m][n], 0, 0, 0); __builtin_amdgcn_s_setprio(0); } while (0)
; #define PG8_WAIT_V(n) asm volatile("s_waitcnt vmcnt(" #n ")" ::: "memory")
; #define PG8_WAIT_L(n) asm volatile("s_waitcnt lgkmcnt(" #n ")" ::: "memory")
; #define PG8_BAR __builtin_amdgcn_s_barrier()
; #define PG8_SCHED __builtin_amdgcn_sched_barrier(0)
; template <class Epi, class Sched, bool ALIGN_EPI = false, bool SP2 = false>
; __device__ __forceinline__ void gemm_phase(PG8_LAS unsigned char* lds, const Gemm g, const Sched& S, const Epi& E) {
;     ...
;         for (int t = 0; t < nt; t += 2) {
;     ...
;             PG8_WAIT_V(8); PG8_WAIT_L(0); PG8_BAR; PG8_MMA(0, 0, At, B0); PG8_MMA(0, 1, At, B1); PG8_BAR; PG8_SCHED;
;             PG8_LDA(At, 1, 1); PG8_STAGE(PG8_SB(1, 0), b3, voffB); PG8_STAGE(PG8_SB(1, 1), b3 + hstep, voffB); PG8_STAGE(PG8_SA(1, 0), a3, voffA);
;             PG8_WAIT_V(8); PG8_WAIT_L(0); PG8_BAR; PG8_MMA(1, 0, At, B0); PG8_MMA(1, 1, At, B1); PG8_BAR; PG8_SCHED;
	v_mfma_f32_16x16x32_bf16 v[76:79], v[132:135], v[212:215], v[76:79]
	v_mfma_f32_16x16x32_bf16 v[76:79], v[128:131], v[208:211], v[76:79]
	s_setprio 0
	s_add_i32 s24, s50, s30
	v_lshl_add_u64 v[158:159], v[158:159], 0, s[12:13]
	s_mov_b32 m0, s24
	ds_read_b128 v[172:175], v201 offset:49152
	ds_read_b128 v[176:179], v201 offset:50176
	ds_read_b128 v[180:183], v201 offset:51200
	ds_read_b128 v[184:187], v201 offset:52224
	ds_read_b128 v[188:191], v201 offset:53248
	ds_read_b128 v[204:207], v201 offset:54272
	ds_read_b128 v[208:211], v201 offset:55296
	ds_read_b128 v[212:215], v201 offset:56320
	global_load_lds_dwordx4 v[158:159], off
	s_add_i32 m0, s24, 0x2000
	s_add_u32 s22, s22, 0x160080
	v_lshl_add_u64 v[158:159], v[192:193], 0, s[12:13]
	s_addc_u32 s23, s23, 0
	s_add_i32 s24, s51, s30
	global_load_lds_dwordx4 v[158:159], off
	v_lshl_add_u64 v[158:159], s[22:23], 0, v[160:161]
	s_mov_b32 m0, s24
	s_nop 0
	global_load_lds_dwordx4 v[158:159], off
	v_lshl_add_u64 v[158:159], s[22:23], 0, v[162:163]
	s_add_i32 m0, s24, 0x2000
	s_nop 0
	global_load_lds_dwordx4 v[158:159], off
	v_lshl_add_u64 v[158:159], v[216:217], 0, s[12:13]
	s_mov_b32 m0, s39
	s_nop 0
	global_load_lds_dwordx4 v[158:159], off
	v_lshl_add_u64 v[158:159], v[218:219], 0, s[12:13]
	s_mov_b32 m0, s40
	s_nop 0
	global_load_lds_dwordx4 v[158:159], off
	s_waitcnt vmcnt(8)
	s_waitcnt lgkmcnt(0)
	s_barrier
	s_setprio 1
	s_waitcnt lgkmcnt(0)
	v_mfma_f32_16x16x32_bf16 v[60:63], v[128:131], v[172:175], v[60:63]
	v_mfma_f32_16x16x32_bf16 v[60:63], v[132:135], v[176:179], v[60:63]
	v_mfma_f32_16x16x32_bf16 v[56:59], v[140:143], v[176:179], v[56:59]
	v_mfma_f32_16x16x32_bf16 v[56:59], v[136:139], v[172:175], v[56:59]
	v_mfma_f32_16x16x32_bf16 v[52:55], v[150:153], v[172:175], v[52:55]
	v_mfma_f32_16x16x32_bf16 v[52:55], v[154:157], v[176:179], v[52:55]
	v_mfma_f32_16x16x32_bf16 v[48:51], v[168:171], v[176:179], v[48:51]
	v_mfma_f32_16x16x32_bf16 v[48:51], v[164:167], v[172:175], v[48:51]
	v_mfma_f32_16x16x32_bf16 v[32:35], v[164:167], v[180:183], v[32:35]
	v_mfma_f32_16x16x32_bf16 v[32:35], v[168:171], v[184:187], v[32:35]
	v_mfma_f32_16x16x32_bf16 v[36:39], v[154:157], v[184:187], v[36:39]
	v_mfma_f32_16x16x32_bf16 v[36:39], v[150:153], v[180:183], v[36:39]
	v_mfma_f32_16x16x32_bf16 v[40:43], v[136:139], v[180:183], v[40:43]
	v_mfma_f32_16x16x32_bf16 v[40:43], v[140:143], v[184:187], v[40:43]
	v_mfma_f32_16x16x32_bf16 v[44:47], v[132:135], v[184:187], v[44:47]
	v_mfma_f32_16x16x32_bf16 v[44:47], v[128:131], v[180:183], v[44:47]
	s_setprio 0
	s_setprio 1
	v_mfma_f32_16x16x32_bf16 v[28:31], v[128:131], v[188:191], v[28:31]
	v_mfma_f32_16x16x32_bf16 v[28:31], v[132:135], v[204:207], v[28:31]
	v_mfma_f32_16x16x32_bf16 v[24:27], v[140:143], v[204:207], v[24:27]
	v_mfma_f32_16x16x32_bf16 v[24:27], v[136:139], v[188:191], v[24:27]
	v_mfma_f32_16x16x32_bf16 v[20:23], v[150:153], v[188:191], v[20:23]
	v_mfma_f32_16x16x32_bf16 v[20:23], v[154:157], v[204:207], v[20:23]
	v_mfma_f32_16x16x32_bf16 v[16:19], v[168:171], v[204:207], v[16:19]
	v_mfma_f32_16x16x32_bf16 v[16:19], v[164:167], v[188:191], v[16:19]
	v_mfma_f32_16x16x32_bf16 v[0:3], v[164:167], v[208:211], v[0:3]
	v_mfma_f32_16x16x32_bf16 v[0:3], v[168:171], v[212:215], v[0:3]
	v_mfma_f32_16x16x32_bf16 v[4:7], v[154:157], v[212:215], v[4:7]
	v_mfma_f32_16x16x32_bf16 v[4:7], v[150:153], v[208:211], v[4:7]
	v_mfma_f32_16x16x32_bf16 v[8:11], v[136:139], v[208:211], v[8:11]
	v_mfma_f32_16x16x32_bf16 v[8:11], v[140:143], v[212:215], v[8:11]
	s_setprio 2
	s_barrier
	v_mfma_f32_16x16x32_bf16 v[12:15], v[132:135], v[212:215], v[12:15]
	v_mfma_f32_16x16x32_bf16 v[12:15], v[128:131], v[208:211], v[12:15]
	s_setprio 0
	s_add_i32 s49, s49, 2
	s_add_u32 s20, s20, 0x100
	s_addc_u32 s21, s21, 0
	s_add_u32 s47, s47, 0x100
	s_addc_u32 s48, s48, 0
	s_cmpk_gt_u32 s49, 0x55
	s_cbranch_scc0 .LBB0_937
	s_and_b64 vcc, exec, s[14:15]
	s_cbranch_vccz .LBB0_940
	s_barrier
